# speedup vs baseline: 1.0303x; 1.0090x over previous
.LBB0_110:
	ds_read_b128 v[140:143], v138
	ds_read_b128 v[144:147], v138 offset:1024
	ds_read_b128 v[148:151], v138 offset:2048
	ds_read_b128 v[152:155], v138 offset:3072
	ds_read_b128 v[156:159], v192
	ds_read_b128 v[160:163], v192 offset:1024
	ds_read_b128 v[194:197], v191
	ds_read_b128 v[198:201], v191 offset:1024
	ds_read_b128 v[202:205], v190
	ds_read_b128 v[206:209], v190 offset:1024
	ds_read_b128 v[210:213], v189
	ds_read_b128 v[214:217], v189 offset:1024
	s_waitcnt lgkmcnt(8)
	s_waitcnt vmcnt(10)
	s_barrier
	s_waitcnt lgkmcnt(0)
	s_setprio 1
	s_waitcnt lgkmcnt(0)
	v_mfma_f32_16x16x32_bf16 v[124:127], v[140:143], v[156:159], v[124:127]
	v_mfma_f32_16x16x32_bf16 v[120:123], v[148:151], v[156:159], v[120:123]
	v_mfma_f32_16x16x32_bf16 v[116:119], v[140:143], v[194:197], v[116:119]
	v_mfma_f32_16x16x32_bf16 v[112:115], v[148:151], v[194:197], v[112:115]
	v_mfma_f32_16x16x32_bf16 v[108:111], v[140:143], v[202:205], v[108:111]
	v_mfma_f32_16x16x32_bf16 v[104:107], v[148:151], v[202:205], v[104:107]
	v_mfma_f32_16x16x32_bf16 v[100:103], v[140:143], v[210:213], v[100:103]
	v_mfma_f32_16x16x32_bf16 v[96:99], v[148:151], v[210:213], v[96:99]
	v_mfma_f32_16x16x32_bf16 v[124:127], v[144:147], v[160:163], v[124:127]
	v_mfma_f32_16x16x32_bf16 v[120:123], v[152:155], v[160:163], v[120:123]
	v_mfma_f32_16x16x32_bf16 v[116:119], v[144:147], v[198:201], v[116:119]
	v_mfma_f32_16x16x32_bf16 v[112:115], v[152:155], v[198:201], v[112:115]
	v_mfma_f32_16x16x32_bf16 v[108:111], v[144:147], v[206:209], v[108:111]
	v_mfma_f32_16x16x32_bf16 v[104:107], v[152:155], v[206:209], v[104:107]
	v_mfma_f32_16x16x32_bf16 v[100:103], v[144:147], v[214:217], v[100:103]
	v_mfma_f32_16x16x32_bf16 v[96:99], v[152:155], v[214:217], v[96:99]
	s_setprio 0
	s_barrier
	v_readfirstlane_b32 s63, v188
	v_lshl_add_u64 v[234:235], s[66:67], 0, v[164:165]
	s_mov_b32 m0, s63
	v_readfirstlane_b32 s63, v187
	ds_read_b128 v[218:221], v135
	ds_read_b128 v[222:225], v135 offset:1024
	ds_read_b128 v[226:229], v135 offset:2048
	ds_read_b128 v[230:233], v135 offset:3072
	global_load_lds_dwordx4 v[234:235], off
	v_lshl_add_u64 v[236:237], v[234:235], 0, s[10:11]
	s_mov_b32 m0, s63
	s_nop 0
	global_load_lds_dwordx4 v[236:237], off
	v_readfirstlane_b32 s63, v169
	v_lshl_add_u64 v[236:237], v[128:129], 0, s[26:27]
	s_mov_b32 m0, s63
	v_readfirstlane_b32 s63, v186
	global_load_lds_dwordx4 v[236:237], off
	v_lshl_add_u64 v[236:237], v[128:129], 0, s[28:29]
	s_mov_b32 m0, s63
	s_nop 0
	global_load_lds_dwordx4 v[236:237], off
	s_waitcnt vmcnt(12)
	s_barrier
	s_waitcnt lgkmcnt(0)
	s_setprio 1
	s_waitcnt lgkmcnt(0)
	v_mfma_f32_16x16x32_bf16 v[92:95], v[218:221], v[156:159], v[92:95]
	v_mfma_f32_16x16x32_bf16 v[88:91], v[226:229], v[156:159], v[88:91]
	v_mfma_f32_16x16x32_bf16 v[84:87], v[218:221], v[194:197], v[84:87]
	v_mfma_f32_16x16x32_bf16 v[80:83], v[226:229], v[194:197], v[80:83]
	v_mfma_f32_16x16x32_bf16 v[76:79], v[218:221], v[202:205], v[76:79]
	v_mfma_f32_16x16x32_bf16 v[72:75], v[226:229], v[202:205], v[72:75]
	v_mfma_f32_16x16x32_bf16 v[68:71], v[218:221], v[210:213], v[68:71]
	v_mfma_f32_16x16x32_bf16 v[64:67], v[226:229], v[210:213], v[64:67]
	v_mfma_f32_16x16x32_bf16 v[92:95], v[222:225], v[160:163], v[92:95]
	v_mfma_f32_16x16x32_bf16 v[88:91], v[230:233], v[160:163], v[88:91]
	v_mfma_f32_16x16x32_bf16 v[84:87], v[222:225], v[198:201], v[84:87]
	v_mfma_f32_16x16x32_bf16 v[80:83], v[230:233], v[198:201], v[80:83]
	v_mfma_f32_16x16x32_bf16 v[76:79], v[222:225], v[206:209], v[76:79]
	v_mfma_f32_16x16x32_bf16 v[72:75], v[230:233], v[206:209], v[72:75]
	v_mfma_f32_16x16x32_bf16 v[68:71], v[222:225], v[214:217], v[68:71]
	v_mfma_f32_16x16x32_bf16 v[64:67], v[230:233], v[214:217], v[64:67]
	s_setprio 0
	s_barrier
	ds_read_b128 v[156:159], v192 offset:16384
	ds_read_b128 v[160:163], v192 offset:17408
	ds_read_b128 v[194:197], v191 offset:16384
	ds_read_b128 v[198:201], v191 offset:17408
	ds_read_b128 v[202:205], v190 offset:16384
	ds_read_b128 v[206:209], v190 offset:17408
	ds_read_b128 v[210:213], v189 offset:16384
	ds_read_b128 v[214:217], v189 offset:17408
	v_readfirstlane_b32 s63, v185
	v_lshl_add_u64 v[236:237], v[234:235], 0, s[30:31]
	s_mov_b32 m0, s63
	v_readfirstlane_b32 s63, v184
	global_load_lds_dwordx4 v[236:237], off
	v_lshl_add_u64 v[236:237], v[234:235], 0, s[34:35]
	s_mov_b32 m0, s63
	s_nop 0
	global_load_lds_dwordx4 v[236:237], off
	s_barrier
	s_waitcnt lgkmcnt(0)
	s_setprio 1
	s_waitcnt lgkmcnt(0)
	v_mfma_f32_16x16x32_bf16 v[60:63], v[140:143], v[156:159], v[60:63]
	v_mfma_f32_16x16x32_bf16 v[56:59], v[148:151], v[156:159], v[56:59]
	v_mfma_f32_16x16x32_bf16 v[52:55], v[140:143], v[194:197], v[52:55]
	v_mfma_f32_16x16x32_bf16 v[48:51], v[148:151], v[194:197], v[48:51]
	v_mfma_f32_16x16x32_bf16 v[44:47], v[140:143], v[202:205], v[44:47]
	v_mfma_f32_16x16x32_bf16 v[40:43], v[148:151], v[202:205], v[40:43]
	v_mfma_f32_16x16x32_bf16 v[36:39], v[140:143], v[210:213], v[36:39]
	v_mfma_f32_16x16x32_bf16 v[32:35], v[148:151], v[210:213], v[32:35]
	v_mfma_f32_16x16x32_bf16 v[60:63], v[144:147], v[160:163], v[60:63]
	v_mfma_f32_16x16x32_bf16 v[56:59], v[152:155], v[160:163], v[56:59]
	v_mfma_f32_16x16x32_bf16 v[52:55], v[144:147], v[198:201], v[52:55]
	v_mfma_f32_16x16x32_bf16 v[48:51], v[152:155], v[198:201], v[48:51]
	v_mfma_f32_16x16x32_bf16 v[44:47], v[144:147], v[206:209], v[44:47]
	v_mfma_f32_16x16x32_bf16 v[40:43], v[152:155], v[206:209], v[40:43]
	v_mfma_f32_16x16x32_bf16 v[36:39], v[144:147], v[214:217], v[36:39]
	v_mfma_f32_16x16x32_bf16 v[32:35], v[152:155], v[214:217], v[32:35]
	s_setprio 0
	s_barrier
	v_readfirstlane_b32 s63, v183
	v_lshl_add_u64 v[142:143], v[128:129], 0, s[40:41]
	s_mov_b32 m0, s63
	v_readfirstlane_b32 s63, v182
	global_load_lds_dwordx4 v[142:143], off
	s_mov_b32 m0, s63
	s_nop 0
	global_load_lds_dwordx4 v[128:129], off
	s_waitcnt vmcnt(12)
	s_barrier
	s_setprio 1
	v_mfma_f32_16x16x32_bf16 v[28:31], v[218:221], v[156:159], v[28:31]
	v_mfma_f32_16x16x32_bf16 v[24:27], v[226:229], v[156:159], v[24:27]
	v_mfma_f32_16x16x32_bf16 v[20:23], v[218:221], v[194:197], v[20:23]
	v_mfma_f32_16x16x32_bf16 v[16:19], v[226:229], v[194:197], v[16:19]
	v_mfma_f32_16x16x32_bf16 v[12:15], v[218:221], v[202:205], v[12:15]
	v_mfma_f32_16x16x32_bf16 v[8:11], v[226:229], v[202:205], v[8:11]
	v_mfma_f32_16x16x32_bf16 v[4:7], v[218:221], v[210:213], v[4:7]
	v_mfma_f32_16x16x32_bf16 v[0:3], v[226:229], v[210:213], v[0:3]
	v_mfma_f32_16x16x32_bf16 v[28:31], v[222:225], v[160:163], v[28:31]
	v_mfma_f32_16x16x32_bf16 v[24:27], v[230:233], v[160:163], v[24:27]
	v_mfma_f32_16x16x32_bf16 v[20:23], v[222:225], v[198:201], v[20:23]
	v_mfma_f32_16x16x32_bf16 v[16:19], v[230:233], v[198:201], v[16:19]
	v_mfma_f32_16x16x32_bf16 v[12:15], v[222:225], v[206:209], v[12:15]
	v_mfma_f32_16x16x32_bf16 v[8:11], v[230:233], v[206:209], v[8:11]
	v_mfma_f32_16x16x32_bf16 v[4:7], v[222:225], v[214:217], v[4:7]
	v_mfma_f32_16x16x32_bf16 v[0:3], v[230:233], v[214:217], v[0:3]
	s_setprio 0
	s_barrier
	ds_read_b128 v[140:143], v130
	ds_read_b128 v[144:147], v130 offset:1024
	ds_read_b128 v[148:151], v130 offset:2048
	ds_read_b128 v[152:155], v130 offset:3072
	ds_read_b128 v[156:159], v192 offset:32768
	ds_read_b128 v[160:163], v192 offset:33792
	ds_read_b128 v[194:197], v191 offset:32768
	ds_read_b128 v[198:201], v191 offset:33792
	ds_read_b128 v[202:205], v190 offset:32768
	ds_read_b128 v[206:209], v190 offset:33792
	ds_read_b128 v[210:213], v189 offset:32768
	ds_read_b128 v[214:217], v189 offset:33792
	s_waitcnt lgkmcnt(8)
	s_waitcnt vmcnt(10)
	s_barrier
	s_waitcnt lgkmcnt(0)
	s_setprio 1
	s_waitcnt lgkmcnt(0)
	v_mfma_f32_16x16x32_bf16 v[124:127], v[140:143], v[156:159], v[124:127]
	v_mfma_f32_16x16x32_bf16 v[120:123], v[148:151], v[156:159], v[120:123]
	v_mfma_f32_16x16x32_bf16 v[116:119], v[140:143], v[194:197], v[116:119]
	v_mfma_f32_16x16x32_bf16 v[112:115], v[148:151], v[194:197], v[112:115]
	v_mfma_f32_16x16x32_bf16 v[108:111], v[140:143], v[202:205], v[108:111]
	v_mfma_f32_16x16x32_bf16 v[104:107], v[148:151], v[202:205], v[104:107]
	v_mfma_f32_16x16x32_bf16 v[100:103], v[140:143], v[210:213], v[100:103]
	v_mfma_f32_16x16x32_bf16 v[96:99], v[148:151], v[210:213], v[96:99]
	v_mfma_f32_16x16x32_bf16 v[124:127], v[144:147], v[160:163], v[124:127]
	v_mfma_f32_16x16x32_bf16 v[120:123], v[152:155], v[160:163], v[120:123]
	v_mfma_f32_16x16x32_bf16 v[116:119], v[144:147], v[198:201], v[116:119]
	v_mfma_f32_16x16x32_bf16 v[112:115], v[152:155], v[198:201], v[112:115]
	v_mfma_f32_16x16x32_bf16 v[108:111], v[144:147], v[206:209], v[108:111]
	v_mfma_f32_16x16x32_bf16 v[104:107], v[152:155], v[206:209], v[104:107]
	v_mfma_f32_16x16x32_bf16 v[100:103], v[144:147], v[214:217], v[100:103]
	v_mfma_f32_16x16x32_bf16 v[96:99], v[152:155], v[214:217], v[96:99]
	s_setprio 0
	s_barrier
	v_readfirstlane_b32 s63, v181
	v_lshl_add_u64 v[234:235], s[64:65], 0, v[164:165]
	s_mov_b32 m0, s63
	v_readfirstlane_b32 s63, v180
	ds_read_b128 v[218:221], v132
	ds_read_b128 v[222:225], v132 offset:1024
	ds_read_b128 v[226:229], v132 offset:2048
	ds_read_b128 v[230:233], v132 offset:3072
	global_load_lds_dwordx4 v[234:235], off
	v_lshl_add_u64 v[236:237], v[234:235], 0, s[10:11]
	s_mov_b32 m0, s63
	s_nop 0
	global_load_lds_dwordx4 v[236:237], off
	v_readfirstlane_b32 s63, v179
	v_lshl_add_u64 v[236:237], v[128:129], 0, s[44:45]
	s_mov_b32 m0, s63
	v_readfirstlane_b32 s63, v177
	global_load_lds_dwordx4 v[236:237], off
	v_lshl_add_u64 v[236:237], v[128:129], 0, s[46:47]
	s_mov_b32 m0, s63
	s_nop 0
	global_load_lds_dwordx4 v[236:237], off
	s_waitcnt vmcnt(12)
	s_barrier
	s_waitcnt lgkmcnt(0)
	s_setprio 1
	s_waitcnt lgkmcnt(0)
	v_mfma_f32_16x16x32_bf16 v[92:95], v[218:221], v[156:159], v[92:95]
	v_mfma_f32_16x16x32_bf16 v[88:91], v[226:229], v[156:159], v[88:91]
	v_mfma_f32_16x16x32_bf16 v[84:87], v[218:221], v[194:197], v[84:87]
	v_mfma_f32_16x16x32_bf16 v[80:83], v[226:229], v[194:197], v[80:83]
	v_mfma_f32_16x16x32_bf16 v[76:79], v[218:221], v[202:205], v[76:79]
	v_mfma_f32_16x16x32_bf16 v[72:75], v[226:229], v[202:205], v[72:75]
	v_mfma_f32_16x16x32_bf16 v[68:71], v[218:221], v[210:213], v[68:71]
	v_mfma_f32_16x16x32_bf16 v[64:67], v[226:229], v[210:213], v[64:67]
	v_mfma_f32_16x16x32_bf16 v[92:95], v[222:225], v[160:163], v[92:95]
	v_mfma_f32_16x16x32_bf16 v[88:91], v[230:233], v[160:163], v[88:91]
	v_mfma_f32_16x16x32_bf16 v[84:87], v[222:225], v[198:201], v[84:87]
	v_mfma_f32_16x16x32_bf16 v[80:83], v[230:233], v[198:201], v[80:83]
	v_mfma_f32_16x16x32_bf16 v[76:79], v[222:225], v[206:209], v[76:79]
	v_mfma_f32_16x16x32_bf16 v[72:75], v[230:233], v[206:209], v[72:75]
	v_mfma_f32_16x16x32_bf16 v[68:71], v[222:225], v[214:217], v[68:71]
	v_mfma_f32_16x16x32_bf16 v[64:67], v[230:233], v[214:217], v[64:67]
	s_setprio 0
	s_barrier
	ds_read_b128 v[156:159], v192 offset:49152
	ds_read_b128 v[160:163], v192 offset:50176
	ds_read_b128 v[194:197], v191 offset:49152
	ds_read_b128 v[198:201], v191 offset:50176
	ds_read_b128 v[202:205], v190 offset:49152
	ds_read_b128 v[206:209], v190 offset:50176
	ds_read_b128 v[210:213], v189 offset:49152
	ds_read_b128 v[214:217], v189 offset:50176
	v_readfirstlane_b32 s63, v175
	v_lshl_add_u64 v[236:237], v[234:235], 0, s[30:31]
	s_mov_b32 m0, s63
	v_readfirstlane_b32 s63, v173
	global_load_lds_dwordx4 v[236:237], off
	v_lshl_add_u64 v[236:237], v[234:235], 0, s[34:35]
	s_mov_b32 m0, s63
	s_nop 0
	global_load_lds_dwordx4 v[236:237], off
	s_barrier
	s_waitcnt lgkmcnt(0)
	s_setprio 1
	s_waitcnt lgkmcnt(0)
	v_mfma_f32_16x16x32_bf16 v[60:63], v[140:143], v[156:159], v[60:63]
	v_mfma_f32_16x16x32_bf16 v[56:59], v[148:151], v[156:159], v[56:59]
	v_mfma_f32_16x16x32_bf16 v[52:55], v[140:143], v[194:197], v[52:55]
	v_mfma_f32_16x16x32_bf16 v[48:51], v[148:151], v[194:197], v[48:51]
	v_mfma_f32_16x16x32_bf16 v[44:47], v[140:143], v[202:205], v[44:47]
	v_mfma_f32_16x16x32_bf16 v[40:43], v[148:151], v[202:205], v[40:43]
	v_mfma_f32_16x16x32_bf16 v[36:39], v[140:143], v[210:213], v[36:39]
	v_mfma_f32_16x16x32_bf16 v[32:35], v[148:151], v[210:213], v[32:35]
	v_mfma_f32_16x16x32_bf16 v[60:63], v[144:147], v[160:163], v[60:63]
	v_mfma_f32_16x16x32_bf16 v[56:59], v[152:155], v[160:163], v[56:59]
	v_mfma_f32_16x16x32_bf16 v[52:55], v[144:147], v[198:201], v[52:55]
	v_mfma_f32_16x16x32_bf16 v[48:51], v[152:155], v[198:201], v[48:51]
	v_mfma_f32_16x16x32_bf16 v[44:47], v[144:147], v[206:209], v[44:47]
	v_mfma_f32_16x16x32_bf16 v[40:43], v[152:155], v[206:209], v[40:43]
	v_mfma_f32_16x16x32_bf16 v[36:39], v[144:147], v[214:217], v[36:39]
	v_mfma_f32_16x16x32_bf16 v[32:35], v[152:155], v[214:217], v[32:35]
	s_setprio 0
	s_barrier
	v_lshl_add_u64 v[128:129], v[128:129], 0, s[56:57]
	v_readfirstlane_b32 s63, v137
	v_lshl_add_u64 v[142:143], v[128:129], 0, s[22:23]
	s_mov_b32 m0, s63
	v_readfirstlane_b32 s63, v136
	global_load_lds_dwordx4 v[142:143], off
	v_lshl_add_u64 v[142:143], v[128:129], 0, s[24:25]
	s_mov_b32 m0, s63
	s_nop 0
	global_load_lds_dwordx4 v[142:143], off
	s_waitcnt vmcnt(12)
	s_barrier
	s_setprio 1
	v_mfma_f32_16x16x32_bf16 v[28:31], v[218:221], v[156:159], v[28:31]
	v_mfma_f32_16x16x32_bf16 v[24:27], v[226:229], v[156:159], v[24:27]
	v_mfma_f32_16x16x32_bf16 v[20:23], v[218:221], v[194:197], v[20:23]
	v_mfma_f32_16x16x32_bf16 v[16:19], v[226:229], v[194:197], v[16:19]
	v_mfma_f32_16x16x32_bf16 v[12:15], v[218:221], v[202:205], v[12:15]
	v_mfma_f32_16x16x32_bf16 v[8:11], v[226:229], v[202:205], v[8:11]
	v_mfma_f32_16x16x32_bf16 v[4:7], v[218:221], v[210:213], v[4:7]
	v_mfma_f32_16x16x32_bf16 v[0:3], v[226:229], v[210:213], v[0:3]
	v_mfma_f32_16x16x32_bf16 v[28:31], v[222:225], v[160:163], v[28:31]
	v_mfma_f32_16x16x32_bf16 v[24:27], v[230:233], v[160:163], v[24:27]
	v_mfma_f32_16x16x32_bf16 v[20:23], v[222:225], v[198:201], v[20:23]
	v_mfma_f32_16x16x32_bf16 v[16:19], v[230:233], v[198:201], v[16:19]
	v_mfma_f32_16x16x32_bf16 v[12:15], v[222:225], v[206:209], v[12:15]
	v_mfma_f32_16x16x32_bf16 v[8:11], v[230:233], v[206:209], v[8:11]
	v_mfma_f32_16x16x32_bf16 v[4:7], v[222:225], v[214:217], v[4:7]
	v_mfma_f32_16x16x32_bf16 v[0:3], v[230:233], v[214:217], v[0:3]
	s_setprio 0
	s_add_i32 s4, s4, 2
	s_add_u32 s64, s64, s68
	s_addc_u32 s65, s65, s69
	s_add_u32 s66, s66, s68
	s_addc_u32 s67, s67, s69
	s_cmp_lt_u32 s4, 28
	s_barrier
	s_cbranch_scc1 .LBB0_110
	s_lshl_b32 s4, s70, 11
	s_or_b32 s64, s71, s4
	s_or_b32 s66, s64, 0x80
	v_lshlrev_b32_e32 v128, 3, v131
	v_lshlrev_b32_e32 v129, 5, v131
	s_ashr_i32 s67, s66, 31
	v_and_b32_e32 v128, 0xffff0, v128
	v_and_b32_e32 v129, 32, v129
	s_lshl_b64 s[66:67], s[66:67], 12
	v_add_u32_e32 v129, v129, v134
	v_add_lshl_u32 v128, v133, v128, 12
	s_add_u32 s66, s54, s66
	v_lshl_add_u32 v164, v129, 1, v128
	s_addc_u32 s67, s55, s67
	v_lshl_add_u64 v[128:129], s[66:67], 0, v[164:165]
	v_readfirstlane_b32 s4, v137
	ds_read_b128 v[140:143], v138
	ds_read_b128 v[144:147], v138 offset:1024
	ds_read_b128 v[148:151], v138 offset:2048
	ds_read_b128 v[152:155], v138 offset:3072
	ds_read_b128 v[156:159], v192
	ds_read_b128 v[160:163], v192 offset:1024
	ds_read_b128 v[194:197], v191
	ds_read_b128 v[198:201], v191 offset:1024
	ds_read_b128 v[202:205], v190
	ds_read_b128 v[206:209], v190 offset:1024
	ds_read_b128 v[210:213], v189
	ds_read_b128 v[214:217], v189 offset:1024
	v_lshl_add_u64 v[138:139], v[128:129], 0, s[58:59]
	s_mov_b32 m0, s4
	v_readfirstlane_b32 s4, v136
	global_load_lds_dwordx4 v[138:139], off
	v_lshl_add_u64 v[128:129], v[128:129], 0, s[60:61]
	s_mov_b32 m0, s4
	s_ashr_i32 s65, s64, 31
	global_load_lds_dwordx4 v[128:129], off
	s_waitcnt vmcnt(10)
	s_barrier
	s_waitcnt lgkmcnt(0)
	s_setprio 1
	s_waitcnt lgkmcnt(0)
	v_mfma_f32_16x16x32_bf16 v[124:127], v[140:143], v[156:159], v[124:127]
	v_mfma_f32_16x16x32_bf16 v[120:123], v[148:151], v[156:159], v[120:123]
	v_mfma_f32_16x16x32_bf16 v[116:119], v[140:143], v[194:197], v[116:119]
	v_mfma_f32_16x16x32_bf16 v[112:115], v[148:151], v[194:197], v[112:115]
	v_mfma_f32_16x16x32_bf16 v[108:111], v[140:143], v[202:205], v[108:111]
	v_mfma_f32_16x16x32_bf16 v[104:107], v[148:151], v[202:205], v[104:107]
	v_mfma_f32_16x16x32_bf16 v[100:103], v[140:143], v[210:213], v[100:103]
	v_mfma_f32_16x16x32_bf16 v[96:99], v[148:151], v[210:213], v[96:99]
	v_mfma_f32_16x16x32_bf16 v[124:127], v[144:147], v[160:163], v[124:127]
	v_mfma_f32_16x16x32_bf16 v[120:123], v[152:155], v[160:163], v[120:123]
	v_mfma_f32_16x16x32_bf16 v[116:119], v[144:147], v[198:201], v[116:119]
	v_mfma_f32_16x16x32_bf16 v[112:115], v[152:155], v[198:201], v[112:115]
	v_mfma_f32_16x16x32_bf16 v[108:111], v[144:147], v[206:209], v[108:111]
	v_mfma_f32_16x16x32_bf16 v[104:107], v[152:155], v[206:209], v[104:107]
	v_mfma_f32_16x16x32_bf16 v[100:103], v[144:147], v[214:217], v[100:103]
	v_mfma_f32_16x16x32_bf16 v[96:99], v[152:155], v[214:217], v[96:99]
	s_setprio 0
	s_barrier
	ds_read_b128 v[136:139], v135
	ds_read_b128 v[218:221], v135 offset:1024
	ds_read_b128 v[222:225], v135 offset:2048
	ds_read_b128 v[226:229], v135 offset:3072
	s_barrier
	s_waitcnt lgkmcnt(0)
	s_setprio 1
	s_waitcnt lgkmcnt(0)
	v_mfma_f32_16x16x32_bf16 v[92:95], v[136:139], v[156:159], v[92:95]
	v_mfma_f32_16x16x32_bf16 v[88:91], v[222:225], v[156:159], v[88:91]
	v_mfma_f32_16x16x32_bf16 v[84:87], v[136:139], v[194:197], v[84:87]
	v_mfma_f32_16x16x32_bf16 v[80:83], v[222:225], v[194:197], v[80:83]
	v_mfma_f32_16x16x32_bf16 v[76:79], v[136:139], v[202:205], v[76:79]
	v_mfma_f32_16x16x32_bf16 v[72:75], v[222:225], v[202:205], v[72:75]
	v_mfma_f32_16x16x32_bf16 v[68:71], v[136:139], v[210:213], v[68:71]
	v_mfma_f32_16x16x32_bf16 v[64:67], v[222:225], v[210:213], v[64:67]
	v_mfma_f32_16x16x32_bf16 v[156:159], v[218:221], v[160:163], v[92:95]
	v_mfma_f32_16x16x32_bf16 v[160:163], v[226:229], v[160:163], v[88:91]
	v_mfma_f32_16x16x32_bf16 v[194:197], v[218:221], v[198:201], v[84:87]
	v_mfma_f32_16x16x32_bf16 v[198:201], v[226:229], v[198:201], v[80:83]
	v_mfma_f32_16x16x32_bf16 v[202:205], v[218:221], v[206:209], v[76:79]
	v_mfma_f32_16x16x32_bf16 v[206:209], v[226:229], v[206:209], v[72:75]
	v_mfma_f32_16x16x32_bf16 v[210:213], v[218:221], v[214:217], v[68:71]
	v_mfma_f32_16x16x32_bf16 v[214:217], v[226:229], v[214:217], v[64:67]
	s_setprio 0
	s_barrier
	s_nop 0
	ds_read_b128 v[64:67], v192 offset:16384
	ds_read_b128 v[68:71], v192 offset:17408
	ds_read_b128 v[72:75], v191 offset:16384
	ds_read_b128 v[76:79], v191 offset:17408
	ds_read_b128 v[80:83], v190 offset:16384
	ds_read_b128 v[84:87], v190 offset:17408
	ds_read_b128 v[88:91], v189 offset:16384
	ds_read_b128 v[92:95], v189 offset:17408
	s_waitcnt vmcnt(4)
	s_barrier
	s_waitcnt lgkmcnt(0)
	s_setprio 1
	s_waitcnt lgkmcnt(0)
	v_mfma_f32_16x16x32_bf16 v[60:63], v[140:143], v[64:67], v[60:63]
	v_mfma_f32_16x16x32_bf16 v[56:59], v[148:151], v[64:67], v[56:59]
	v_mfma_f32_16x16x32_bf16 v[52:55], v[140:143], v[72:75], v[52:55]
	v_mfma_f32_16x16x32_bf16 v[48:51], v[148:151], v[72:75], v[48:51]
	v_mfma_f32_16x16x32_bf16 v[230:233], v[140:143], v[80:83], v[44:47]
	v_mfma_f32_16x16x32_bf16 v[234:237], v[148:151], v[80:83], v[40:43]
	v_mfma_f32_16x16x32_bf16 v[140:143], v[140:143], v[88:91], v[36:39]
	v_mfma_f32_16x16x32_bf16 v[148:151], v[148:151], v[88:91], v[32:35]
	v_mfma_f32_16x16x32_bf16 v[32:35], v[144:147], v[68:71], v[60:63]
	v_mfma_f32_16x16x32_bf16 v[36:39], v[152:155], v[68:71], v[56:59]
	v_mfma_f32_16x16x32_bf16 v[40:43], v[144:147], v[76:79], v[52:55]
	v_mfma_f32_16x16x32_bf16 v[44:47], v[152:155], v[76:79], v[48:51]
	v_mfma_f32_16x16x32_bf16 v[48:51], v[144:147], v[84:87], v[230:233]
	v_mfma_f32_16x16x32_bf16 v[52:55], v[152:155], v[84:87], v[234:237]
	v_mfma_f32_16x16x32_bf16 v[56:59], v[144:147], v[92:95], v[140:143]
	v_mfma_f32_16x16x32_bf16 v[60:63], v[152:155], v[92:95], v[148:151]
	s_setprio 0
	s_setprio 1
	v_mfma_f32_16x16x32_bf16 v[28:31], v[136:139], v[64:67], v[28:31]
	v_mfma_f32_16x16x32_bf16 v[24:27], v[222:225], v[64:67], v[24:27]
	v_mfma_f32_16x16x32_bf16 v[20:23], v[136:139], v[72:75], v[20:23]
	v_mfma_f32_16x16x32_bf16 v[64:67], v[222:225], v[72:75], v[16:19]
	v_mfma_f32_16x16x32_bf16 v[12:15], v[136:139], v[80:83], v[12:15]
	v_mfma_f32_16x16x32_bf16 v[8:11], v[222:225], v[80:83], v[8:11]
	v_mfma_f32_16x16x32_bf16 v[72:75], v[136:139], v[88:91], v[4:7]
	v_mfma_f32_16x16x32_bf16 v[80:83], v[222:225], v[88:91], v[0:3]
	v_mfma_f32_16x16x32_bf16 v[0:3], v[218:221], v[68:71], v[28:31]
	v_mfma_f32_16x16x32_bf16 v[4:7], v[226:229], v[68:71], v[24:27]
	v_mfma_f32_16x16x32_bf16 v[16:19], v[218:221], v[76:79], v[20:23]
	v_mfma_f32_16x16x32_bf16 v[20:23], v[226:229], v[76:79], v[64:67]
	v_mfma_f32_16x16x32_bf16 v[64:67], v[218:221], v[84:87], v[12:15]
	v_mfma_f32_16x16x32_bf16 v[68:71], v[226:229], v[84:87], v[8:11]
	v_mfma_f32_16x16x32_bf16 v[72:75], v[218:221], v[92:95], v[72:75]
	v_mfma_f32_16x16x32_bf16 v[76:79], v[226:229], v[92:95], v[80:83]
	s_setprio 0
	s_barrier
	ds_read_b128 v[12:15], v130
	ds_read_b128 v[8:11], v130 offset:1024
	ds_read_b128 v[24:27], v130 offset:2048
	ds_read_b128 v[80:83], v130 offset:3072
	ds_read_b128 v[140:143], v192 offset:32768
	ds_read_b128 v[148:151], v192 offset:33792
	ds_read_b128 v[218:221], v191 offset:32768
	ds_read_b128 v[222:225], v191 offset:33792
	ds_read_b128 v[226:229], v190 offset:32768
	ds_read_b128 v[230:233], v190 offset:33792
	ds_read_b128 v[234:237], v189 offset:32768
	ds_read_b128 v[238:241], v189 offset:33792
	s_waitcnt vmcnt(2)
	s_barrier
	s_waitcnt lgkmcnt(0)
	s_setprio 1
	s_waitcnt lgkmcnt(0)
	v_mfma_f32_16x16x32_bf16 v[28:31], v[12:15], v[140:143], v[124:127]
	v_mfma_f32_16x16x32_bf16 v[84:87], v[24:27], v[140:143], v[120:123]
	v_mfma_f32_16x16x32_bf16 v[88:91], v[12:15], v[218:221], v[116:119]
	v_mfma_f32_16x16x32_bf16 v[92:95], v[24:27], v[218:221], v[112:115]
	v_mfma_f32_16x16x32_bf16 v[108:111], v[12:15], v[226:229], v[108:111]
	v_mfma_f32_16x16x32_bf16 v[104:107], v[24:27], v[226:229], v[104:107]
	v_mfma_f32_16x16x32_bf16 v[100:103], v[12:15], v[234:237], v[100:103]
	v_mfma_f32_16x16x32_bf16 v[96:99], v[24:27], v[234:237], v[96:99]
	v_mfma_f32_16x16x32_bf16 v[152:155], v[8:11], v[148:151], v[28:31]
	v_mfma_f32_16x16x32_bf16 v[144:147], v[80:83], v[148:151], v[84:87]
	v_mfma_f32_16x16x32_bf16 v[136:139], v[8:11], v[222:225], v[88:91]
	v_mfma_f32_16x16x32_bf16 v[128:131], v[80:83], v[222:225], v[92:95]
	v_mfma_f32_16x16x32_bf16 v[120:123], v[8:11], v[230:233], v[108:111]
	v_mfma_f32_16x16x32_bf16 v[112:115], v[80:83], v[230:233], v[104:107]
	v_mfma_f32_16x16x32_bf16 v[104:107], v[8:11], v[238:241], v[100:103]
	v_mfma_f32_16x16x32_bf16 v[28:31], v[80:83], v[238:241], v[96:99]
	s_setprio 0
	s_barrier
	ds_read_b128 v[92:95], v132
	ds_read_b128 v[84:87], v132 offset:1024
	ds_read_b128 v[96:99], v132 offset:2048
	ds_read_b128 v[88:91], v132 offset:3072
	s_waitcnt vmcnt(0)
	s_barrier
	s_waitcnt lgkmcnt(0)
	s_setprio 1
	s_waitcnt lgkmcnt(0)
	v_mfma_f32_16x16x32_bf16 v[100:103], v[92:95], v[140:143], v[156:159]
	v_mfma_f32_16x16x32_bf16 v[108:111], v[96:99], v[140:143], v[160:163]
	v_mfma_f32_16x16x32_bf16 v[116:119], v[92:95], v[218:221], v[194:197]
	v_mfma_f32_16x16x32_bf16 v[124:127], v[96:99], v[218:221], v[198:201]
	v_mfma_f32_16x16x32_bf16 v[160:163], v[92:95], v[226:229], v[202:205]
	v_mfma_f32_16x16x32_bf16 v[194:197], v[96:99], v[226:229], v[206:209]
	v_mfma_f32_16x16x32_bf16 v[198:201], v[92:95], v[234:237], v[210:213]
	v_mfma_f32_16x16x32_bf16 v[202:205], v[96:99], v[234:237], v[214:217]
	v_mfma_f32_16x16x32_bf16 v[156:159], v[84:87], v[148:151], v[100:103]
	v_mfma_f32_16x16x32_bf16 v[148:151], v[88:91], v[148:151], v[108:111]
	v_mfma_f32_16x16x32_bf16 v[140:143], v[84:87], v[222:225], v[116:119]
	v_mfma_f32_16x16x32_bf16 v[132:135], v[88:91], v[222:225], v[124:127]
	v_mfma_f32_16x16x32_bf16 v[124:127], v[84:87], v[230:233], v[160:163]
	v_mfma_f32_16x16x32_bf16 v[116:119], v[88:91], v[230:233], v[194:197]
	v_mfma_f32_16x16x32_bf16 v[108:111], v[84:87], v[238:241], v[198:201]
	v_mfma_f32_16x16x32_bf16 v[100:103], v[88:91], v[238:241], v[202:205]
	s_setprio 0
	s_lshl_b64 s[66:67], s[64:65], 2
	s_barrier
	v_mbcnt_lo_u32_b32 v162, -1, 0
	v_mbcnt_hi_u32_b32 v162, -1, v162
	s_add_u32 s66, s87, s66
	v_add_u32_e32 v160, s76, v162
	s_addc_u32 s67, s88, s67
	v_and_b32_e32 v164, 0x100, v160
	v_and_b32_e32 v162, 15, v162
	v_lshl_add_u64 v[160:161], s[66:67], 0, v[164:165]
	v_lshlrev_b32_e32 v164, 2, v162
	v_lshl_add_u64 v[160:161], v[160:161], 0, v[164:165]
	global_load_dword v178, v[160:161], off
	global_load_dword v176, v[160:161], off offset:64
	global_load_dword v174, v[160:161], off offset:128
	global_load_dword v164, v[160:161], off offset:192
	global_load_dword v172, v[160:161], off offset:512
	global_load_dword v170, v[160:161], off offset:576
	global_load_dword v168, v[160:161], off offset:640
	global_load_dword v166, v[160:161], off offset:704
	v_mbcnt_lo_u32_b32 v194, -1, 0
	v_mbcnt_hi_u32_b32 v194, -1, v194
	s_mov_b64 s[66:67], -1
	v_add_u32_e32 v160, s76, v194
	v_bfe_u32 v161, v160, 8, 1
	v_ashrrev_i32_e32 v196, 6, v160
	v_bfe_u32 v160, v194, 4, 2
	v_and_b32_e32 v198, 3, v196
	v_and_b32_e32 v195, 15, v194
	s_cmp_gt_i32 s74, 1
	v_lshlrev_b32_e32 v193, 6, v161
	v_lshlrev_b32_e32 v197, 4, v160
	s_cbranch_scc0 .LBB0_113
	v_lshlrev_b32_e32 v161, 6, v198
	v_or3_b32 v160, v193, v195, s64
	v_or3_b32 v161, v161, v197, s62
	v_lshl_add_u32 v199, v160, 12, v161
	s_waitcnt vmcnt(0)
	v_mul_f32_e32 v160, v178, v178
	v_pk_mul_f32 v[200:201], v[152:153], v[160:161] op_sel_hi:[1,0]
	v_pk_mul_f32 v[162:163], v[154:155], v[160:161] op_sel_hi:[1,0]
	v_pk_mul_f32 v[202:203], v[158:159], v[160:161] op_sel_hi:[1,0]
	v_pk_mul_f32 v[204:205], v[156:157], v[160:161] op_sel_hi:[1,0]
	v_mul_f32_e32 v160, v144, v200
	v_mul_f32_e32 v161, v145, v201
	v_cvt_pk_bf16_f32 v160, v160, v161
	v_mul_f32_e32 v161, v146, v162
	v_mul_f32_e32 v162, v147, v163
	v_cvt_pk_bf16_f32 v161, v161, v162
	v_mul_f32_e32 v162, v148, v204
	v_mul_f32_e32 v163, v149, v205
	v_cvt_pk_bf16_f32 v162, v162, v163
	v_mul_f32_e32 v163, v150, v202
	v_mul_f32_e32 v200, v151, v203
	v_cvt_pk_bf16_f32 v163, v163, v200
	global_store_dwordx4 v199, v[160:163], s[6:7]
	v_add_u32_e32 v206, 0x10000, v199
	s_mov_b64 s[66:67], 0
	v_mul_f32_e32 v160, v176, v176
	v_pk_mul_f32 v[200:201], v[136:137], v[160:161] op_sel_hi:[1,0]
	v_pk_mul_f32 v[162:163], v[138:139], v[160:161] op_sel_hi:[1,0]
	v_pk_mul_f32 v[202:203], v[142:143], v[160:161] op_sel_hi:[1,0]
	v_pk_mul_f32 v[204:205], v[140:141], v[160:161] op_sel_hi:[1,0]
	v_mul_f32_e32 v160, v128, v200
	v_mul_f32_e32 v161, v129, v201
	v_cvt_pk_bf16_f32 v160, v160, v161
	v_mul_f32_e32 v161, v130, v162
	v_mul_f32_e32 v162, v131, v163
	v_cvt_pk_bf16_f32 v161, v161, v162
	v_mul_f32_e32 v162, v132, v204
	v_mul_f32_e32 v163, v133, v205
	v_cvt_pk_bf16_f32 v162, v162, v163
	v_mul_f32_e32 v163, v134, v202
	v_mul_f32_e32 v200, v135, v203
	v_cvt_pk_bf16_f32 v163, v163, v200
	global_store_dwordx4 v206, v[160:163], s[6:7]
	v_add_u32_e32 v206, 0x20000, v199
	v_add_u32_e32 v199, 0x30000, v199
	v_mul_f32_e32 v160, v174, v174
	v_pk_mul_f32 v[200:201], v[120:121], v[160:161] op_sel_hi:[1,0]
	v_pk_mul_f32 v[162:163], v[122:123], v[160:161] op_sel_hi:[1,0]
	v_pk_mul_f32 v[202:203], v[126:127], v[160:161] op_sel_hi:[1,0]
	v_pk_mul_f32 v[204:205], v[124:125], v[160:161] op_sel_hi:[1,0]
	v_mul_f32_e32 v160, v112, v200
	v_mul_f32_e32 v161, v113, v201
	v_cvt_pk_bf16_f32 v160, v160, v161
	v_mul_f32_e32 v161, v114, v162
	v_mul_f32_e32 v162, v115, v163
	v_cvt_pk_bf16_f32 v161, v161, v162
	v_mul_f32_e32 v162, v116, v204
	v_mul_f32_e32 v163, v117, v205
	v_cvt_pk_bf16_f32 v162, v162, v163
	v_mul_f32_e32 v163, v118, v202
	v_mul_f32_e32 v200, v119, v203
	v_cvt_pk_bf16_f32 v163, v163, v200
	global_store_dwordx4 v206, v[160:163], s[6:7]
	s_nop 1
	v_mul_f32_e32 v160, v164, v164
	v_pk_mul_f32 v[200:201], v[104:105], v[160:161] op_sel_hi:[1,0]
	v_pk_mul_f32 v[162:163], v[106:107], v[160:161] op_sel_hi:[1,0]
	v_pk_mul_f32 v[202:203], v[110:111], v[160:161] op_sel_hi:[1,0]
	v_pk_mul_f32 v[204:205], v[108:109], v[160:161] op_sel_hi:[1,0]
	v_mul_f32_e32 v160, v28, v200
	v_mul_f32_e32 v161, v29, v201
	v_cvt_pk_bf16_f32 v160, v160, v161
	v_mul_f32_e32 v161, v30, v162
	v_mul_f32_e32 v162, v31, v163
	v_cvt_pk_bf16_f32 v161, v161, v162
	v_mul_f32_e32 v162, v100, v204
	v_mul_f32_e32 v163, v101, v205
	v_cvt_pk_bf16_f32 v162, v162, v163
	v_mul_f32_e32 v163, v102, v202
	v_mul_f32_e32 v200, v103, v203
	v_cvt_pk_bf16_f32 v163, v163, v200

.LBB0_178:
	ds_read_b128 v[164:167], v162
	ds_read_b128 v[168:171], v162 offset:1024
	ds_read_b128 v[172:175], v162 offset:2048
	ds_read_b128 v[176:179], v162 offset:3072
	ds_read_b128 v[180:183], v153
	ds_read_b128 v[184:187], v153 offset:1024
	ds_read_b128 v[188:191], v152
	ds_read_b128 v[192:195], v152 offset:1024
	ds_read_b128 v[196:199], v151
	ds_read_b128 v[200:203], v151 offset:1024
	ds_read_b128 v[204:207], v150
	ds_read_b128 v[208:211], v150 offset:1024
	s_waitcnt lgkmcnt(8)
	s_waitcnt vmcnt(10)
	s_barrier
	s_waitcnt lgkmcnt(0)
	s_setprio 1
	s_waitcnt lgkmcnt(0)
	v_mfma_f32_16x16x32_bf16 v[124:127], v[164:167], v[180:183], v[124:127]
	v_mfma_f32_16x16x32_bf16 v[120:123], v[172:175], v[180:183], v[120:123]
	v_mfma_f32_16x16x32_bf16 v[116:119], v[164:167], v[188:191], v[116:119]
	v_mfma_f32_16x16x32_bf16 v[112:115], v[172:175], v[188:191], v[112:115]
	v_mfma_f32_16x16x32_bf16 v[108:111], v[164:167], v[196:199], v[108:111]
	v_mfma_f32_16x16x32_bf16 v[104:107], v[172:175], v[196:199], v[104:107]
	v_mfma_f32_16x16x32_bf16 v[100:103], v[164:167], v[204:207], v[100:103]
	v_mfma_f32_16x16x32_bf16 v[96:99], v[172:175], v[204:207], v[96:99]
	v_mfma_f32_16x16x32_bf16 v[124:127], v[168:171], v[184:187], v[124:127]
	v_mfma_f32_16x16x32_bf16 v[120:123], v[176:179], v[184:187], v[120:123]
	v_mfma_f32_16x16x32_bf16 v[116:119], v[168:171], v[192:195], v[116:119]
	v_mfma_f32_16x16x32_bf16 v[112:115], v[176:179], v[192:195], v[112:115]
	v_mfma_f32_16x16x32_bf16 v[108:111], v[168:171], v[200:203], v[108:111]
	v_mfma_f32_16x16x32_bf16 v[104:107], v[176:179], v[200:203], v[104:107]
	v_mfma_f32_16x16x32_bf16 v[100:103], v[168:171], v[208:211], v[100:103]
	v_mfma_f32_16x16x32_bf16 v[96:99], v[176:179], v[208:211], v[96:99]
	s_setprio 0
	s_barrier
	v_lshl_add_u64 v[230:231], s[50:51], 0, v[130:131]
	s_mov_b64 s[66:67], 0x1880000
	v_readfirstlane_b32 s65, v149
	v_lshl_add_u64 v[232:233], v[230:231], 0, s[66:67]
	s_mov_b32 m0, s65
	s_mov_b64 s[66:67], 0x1881000
	v_readfirstlane_b32 s65, v148
	ds_read_b128 v[212:215], v159
	ds_read_b128 v[216:219], v159 offset:1024
	ds_read_b128 v[220:223], v159 offset:2048
	ds_read_b128 v[224:227], v159 offset:3072
	global_load_lds_dwordx4 v[232:233], off
	v_lshl_add_u64 v[232:233], v[230:231], 0, s[66:67]
	s_mov_b32 m0, s65
	s_nop 0
	global_load_lds_dwordx4 v[232:233], off
	s_mov_b64 s[66:67], 0xe000100
	v_readfirstlane_b32 s65, v135
	v_lshl_add_u64 v[232:233], v[228:229], 0, s[66:67]
	s_mov_b32 m0, s65
	s_mov_b64 s[66:67], 0xe040100
	v_readfirstlane_b32 s65, v147
	global_load_lds_dwordx4 v[232:233], off
	v_lshl_add_u64 v[232:233], v[228:229], 0, s[66:67]
	s_mov_b32 m0, s65
	s_nop 0
	global_load_lds_dwordx4 v[232:233], off
	s_waitcnt vmcnt(12)
	s_barrier
	s_waitcnt lgkmcnt(0)
	s_setprio 1
	s_waitcnt lgkmcnt(0)
	v_mfma_f32_16x16x32_bf16 v[92:95], v[212:215], v[180:183], v[92:95]
	v_mfma_f32_16x16x32_bf16 v[88:91], v[220:223], v[180:183], v[88:91]
	v_mfma_f32_16x16x32_bf16 v[84:87], v[212:215], v[188:191], v[84:87]
	v_mfma_f32_16x16x32_bf16 v[80:83], v[220:223], v[188:191], v[80:83]
	v_mfma_f32_16x16x32_bf16 v[76:79], v[212:215], v[196:199], v[76:79]
	v_mfma_f32_16x16x32_bf16 v[72:75], v[220:223], v[196:199], v[72:75]
	v_mfma_f32_16x16x32_bf16 v[68:71], v[212:215], v[204:207], v[68:71]
	v_mfma_f32_16x16x32_bf16 v[64:67], v[220:223], v[204:207], v[64:67]
	v_mfma_f32_16x16x32_bf16 v[92:95], v[216:219], v[184:187], v[92:95]
	v_mfma_f32_16x16x32_bf16 v[88:91], v[224:227], v[184:187], v[88:91]
	v_mfma_f32_16x16x32_bf16 v[84:87], v[216:219], v[192:195], v[84:87]
	v_mfma_f32_16x16x32_bf16 v[80:83], v[224:227], v[192:195], v[80:83]
	v_mfma_f32_16x16x32_bf16 v[76:79], v[216:219], v[200:203], v[76:79]
	v_mfma_f32_16x16x32_bf16 v[72:75], v[224:227], v[200:203], v[72:75]
	v_mfma_f32_16x16x32_bf16 v[68:71], v[216:219], v[208:211], v[68:71]
	v_mfma_f32_16x16x32_bf16 v[64:67], v[224:227], v[208:211], v[64:67]
	s_setprio 0
	s_barrier
	ds_read_b128 v[180:183], v153 offset:16384
	ds_read_b128 v[184:187], v153 offset:17408
	ds_read_b128 v[188:191], v152 offset:16384
	ds_read_b128 v[192:195], v152 offset:17408
	ds_read_b128 v[196:199], v151 offset:16384
	ds_read_b128 v[200:203], v151 offset:17408
	ds_read_b128 v[204:207], v150 offset:16384
	ds_read_b128 v[208:211], v150 offset:17408
	s_mov_b64 s[66:67], 0x1882000
	v_readfirstlane_b32 s65, v146
	v_lshl_add_u64 v[232:233], v[230:231], 0, s[66:67]
	s_mov_b32 m0, s65
	s_mov_b64 s[66:67], 0x1883000
	v_readfirstlane_b32 s65, v145
	global_load_lds_dwordx4 v[232:233], off
	v_lshl_add_u64 v[232:233], v[230:231], 0, s[66:67]
	s_mov_b32 m0, s65
	s_nop 0
	global_load_lds_dwordx4 v[232:233], off
	s_barrier
	s_waitcnt lgkmcnt(0)
	s_setprio 1
	s_waitcnt lgkmcnt(0)
	v_mfma_f32_16x16x32_bf16 v[60:63], v[164:167], v[180:183], v[60:63]
	v_mfma_f32_16x16x32_bf16 v[56:59], v[172:175], v[180:183], v[56:59]
	v_mfma_f32_16x16x32_bf16 v[52:55], v[164:167], v[188:191], v[52:55]
	v_mfma_f32_16x16x32_bf16 v[48:51], v[172:175], v[188:191], v[48:51]
	v_mfma_f32_16x16x32_bf16 v[44:47], v[164:167], v[196:199], v[44:47]
	v_mfma_f32_16x16x32_bf16 v[40:43], v[172:175], v[196:199], v[40:43]
	v_mfma_f32_16x16x32_bf16 v[36:39], v[164:167], v[204:207], v[36:39]
	v_mfma_f32_16x16x32_bf16 v[32:35], v[172:175], v[204:207], v[32:35]
	v_mfma_f32_16x16x32_bf16 v[60:63], v[168:171], v[184:187], v[60:63]
	v_mfma_f32_16x16x32_bf16 v[56:59], v[176:179], v[184:187], v[56:59]
	v_mfma_f32_16x16x32_bf16 v[52:55], v[168:171], v[192:195], v[52:55]
	v_mfma_f32_16x16x32_bf16 v[48:51], v[176:179], v[192:195], v[48:51]
	v_mfma_f32_16x16x32_bf16 v[44:47], v[168:171], v[200:203], v[44:47]
	v_mfma_f32_16x16x32_bf16 v[40:43], v[176:179], v[200:203], v[40:43]
	v_mfma_f32_16x16x32_bf16 v[36:39], v[168:171], v[208:211], v[36:39]
	v_mfma_f32_16x16x32_bf16 v[32:35], v[176:179], v[208:211], v[32:35]
	s_setprio 0
	s_barrier
	v_readfirstlane_b32 s65, v144
	v_lshl_add_u64 v[166:167], v[228:229], 0, s[26:27]
	s_mov_b32 m0, s65
	v_readfirstlane_b32 s65, v143
	global_load_lds_dwordx4 v[166:167], off
	v_lshl_add_u64 v[166:167], v[228:229], 0, s[28:29]
	s_mov_b32 m0, s65
	s_nop 0
	global_load_lds_dwordx4 v[166:167], off
	s_waitcnt vmcnt(12)
	s_barrier
	s_setprio 1
	v_mfma_f32_16x16x32_bf16 v[28:31], v[212:215], v[180:183], v[28:31]
	v_mfma_f32_16x16x32_bf16 v[24:27], v[220:223], v[180:183], v[24:27]
	v_mfma_f32_16x16x32_bf16 v[20:23], v[212:215], v[188:191], v[20:23]
	v_mfma_f32_16x16x32_bf16 v[16:19], v[220:223], v[188:191], v[16:19]
	v_mfma_f32_16x16x32_bf16 v[12:15], v[212:215], v[196:199], v[12:15]
	v_mfma_f32_16x16x32_bf16 v[8:11], v[220:223], v[196:199], v[8:11]
	v_mfma_f32_16x16x32_bf16 v[4:7], v[212:215], v[204:207], v[4:7]
	v_mfma_f32_16x16x32_bf16 v[0:3], v[220:223], v[204:207], v[0:3]
	v_mfma_f32_16x16x32_bf16 v[28:31], v[216:219], v[184:187], v[28:31]
	v_mfma_f32_16x16x32_bf16 v[24:27], v[224:227], v[184:187], v[24:27]
	v_mfma_f32_16x16x32_bf16 v[20:23], v[216:219], v[192:195], v[20:23]
	v_mfma_f32_16x16x32_bf16 v[16:19], v[224:227], v[192:195], v[16:19]
	v_mfma_f32_16x16x32_bf16 v[12:15], v[216:219], v[200:203], v[12:15]
	v_mfma_f32_16x16x32_bf16 v[8:11], v[224:227], v[200:203], v[8:11]
	v_mfma_f32_16x16x32_bf16 v[4:7], v[216:219], v[208:211], v[4:7]
	v_mfma_f32_16x16x32_bf16 v[0:3], v[224:227], v[208:211], v[0:3]
	s_setprio 0
	s_barrier
	ds_read_b128 v[164:167], v155
	ds_read_b128 v[168:171], v155 offset:1024
	ds_read_b128 v[172:175], v155 offset:2048
	ds_read_b128 v[176:179], v155 offset:3072
	ds_read_b128 v[180:183], v153 offset:32768
	ds_read_b128 v[184:187], v153 offset:33792
	ds_read_b128 v[188:191], v152 offset:32768
	ds_read_b128 v[192:195], v152 offset:33792
	ds_read_b128 v[196:199], v151 offset:32768
	ds_read_b128 v[200:203], v151 offset:33792
	ds_read_b128 v[204:207], v150 offset:32768
	ds_read_b128 v[208:211], v150 offset:33792
	s_waitcnt lgkmcnt(8)
	s_waitcnt vmcnt(10)
	s_barrier
	s_waitcnt lgkmcnt(0)
	s_setprio 1
	s_waitcnt lgkmcnt(0)
	v_mfma_f32_16x16x32_bf16 v[124:127], v[164:167], v[180:183], v[124:127]
	v_mfma_f32_16x16x32_bf16 v[120:123], v[172:175], v[180:183], v[120:123]
	v_mfma_f32_16x16x32_bf16 v[116:119], v[164:167], v[188:191], v[116:119]
	v_mfma_f32_16x16x32_bf16 v[112:115], v[172:175], v[188:191], v[112:115]
	v_mfma_f32_16x16x32_bf16 v[108:111], v[164:167], v[196:199], v[108:111]
	v_mfma_f32_16x16x32_bf16 v[104:107], v[172:175], v[196:199], v[104:107]
	v_mfma_f32_16x16x32_bf16 v[100:103], v[164:167], v[204:207], v[100:103]
	v_mfma_f32_16x16x32_bf16 v[96:99], v[172:175], v[204:207], v[96:99]
	v_mfma_f32_16x16x32_bf16 v[124:127], v[168:171], v[184:187], v[124:127]
	v_mfma_f32_16x16x32_bf16 v[120:123], v[176:179], v[184:187], v[120:123]
	v_mfma_f32_16x16x32_bf16 v[116:119], v[168:171], v[192:195], v[116:119]
	v_mfma_f32_16x16x32_bf16 v[112:115], v[176:179], v[192:195], v[112:115]
	v_mfma_f32_16x16x32_bf16 v[108:111], v[168:171], v[200:203], v[108:111]
	v_mfma_f32_16x16x32_bf16 v[104:107], v[176:179], v[200:203], v[104:107]
	v_mfma_f32_16x16x32_bf16 v[100:103], v[168:171], v[208:211], v[100:103]
	v_mfma_f32_16x16x32_bf16 v[96:99], v[176:179], v[208:211], v[96:99]
	s_setprio 0
	s_barrier
	v_readfirstlane_b32 s65, v142
	v_lshl_add_u64 v[232:233], v[230:231], 0, s[30:31]
	s_mov_b32 m0, s65
	v_readfirstlane_b32 s65, v141
	ds_read_b128 v[212:215], v154
	ds_read_b128 v[216:219], v154 offset:1024
	ds_read_b128 v[220:223], v154 offset:2048
	ds_read_b128 v[224:227], v154 offset:3072
	global_load_lds_dwordx4 v[232:233], off
	v_lshl_add_u64 v[232:233], v[230:231], 0, s[34:35]
	s_mov_b32 m0, s65
	s_nop 0
	global_load_lds_dwordx4 v[232:233], off
	v_readfirstlane_b32 s65, v140
	v_lshl_add_u64 v[232:233], v[228:229], 0, s[40:41]
	s_mov_b32 m0, s65
	v_readfirstlane_b32 s65, v139
	global_load_lds_dwordx4 v[232:233], off
	v_lshl_add_u64 v[228:229], v[228:229], 0, s[44:45]
	s_mov_b32 m0, s65
	s_nop 0
	global_load_lds_dwordx4 v[228:229], off
	s_waitcnt vmcnt(12)
	s_barrier
	s_waitcnt lgkmcnt(0)
	s_setprio 1
	s_waitcnt lgkmcnt(0)
	v_mfma_f32_16x16x32_bf16 v[92:95], v[212:215], v[180:183], v[92:95]
	v_mfma_f32_16x16x32_bf16 v[88:91], v[220:223], v[180:183], v[88:91]
	v_mfma_f32_16x16x32_bf16 v[84:87], v[212:215], v[188:191], v[84:87]
	v_mfma_f32_16x16x32_bf16 v[80:83], v[220:223], v[188:191], v[80:83]
	v_mfma_f32_16x16x32_bf16 v[76:79], v[212:215], v[196:199], v[76:79]
	v_mfma_f32_16x16x32_bf16 v[72:75], v[220:223], v[196:199], v[72:75]
	v_mfma_f32_16x16x32_bf16 v[68:71], v[212:215], v[204:207], v[68:71]
	v_mfma_f32_16x16x32_bf16 v[64:67], v[220:223], v[204:207], v[64:67]
	v_mfma_f32_16x16x32_bf16 v[92:95], v[216:219], v[184:187], v[92:95]
	v_mfma_f32_16x16x32_bf16 v[88:91], v[224:227], v[184:187], v[88:91]
	v_mfma_f32_16x16x32_bf16 v[84:87], v[216:219], v[192:195], v[84:87]
	v_mfma_f32_16x16x32_bf16 v[80:83], v[224:227], v[192:195], v[80:83]
	v_mfma_f32_16x16x32_bf16 v[76:79], v[216:219], v[200:203], v[76:79]
	v_mfma_f32_16x16x32_bf16 v[72:75], v[224:227], v[200:203], v[72:75]
	v_mfma_f32_16x16x32_bf16 v[68:71], v[216:219], v[208:211], v[68:71]
	v_mfma_f32_16x16x32_bf16 v[64:67], v[224:227], v[208:211], v[64:67]
	s_setprio 0
	s_barrier
	ds_read_b128 v[180:183], v153 offset:49152
	ds_read_b128 v[184:187], v153 offset:50176
	ds_read_b128 v[188:191], v152 offset:49152
	ds_read_b128 v[192:195], v152 offset:50176
	ds_read_b128 v[196:199], v151 offset:49152
	ds_read_b128 v[200:203], v151 offset:50176
	ds_read_b128 v[204:207], v150 offset:49152
	ds_read_b128 v[208:211], v150 offset:50176
	v_readfirstlane_b32 s65, v138
	v_lshl_add_u64 v[232:233], v[230:231], 0, s[46:47]
	s_mov_b32 m0, s65
	v_readfirstlane_b32 s65, v137
	global_load_lds_dwordx4 v[232:233], off
	v_lshl_add_u64 v[232:233], v[230:231], 0, s[56:57]
	s_mov_b32 m0, s65
	s_nop 0
	global_load_lds_dwordx4 v[232:233], off
	s_barrier
	s_waitcnt lgkmcnt(0)
	s_setprio 1
	s_waitcnt lgkmcnt(0)
	v_mfma_f32_16x16x32_bf16 v[60:63], v[164:167], v[180:183], v[60:63]
	v_mfma_f32_16x16x32_bf16 v[56:59], v[172:175], v[180:183], v[56:59]
	v_mfma_f32_16x16x32_bf16 v[52:55], v[164:167], v[188:191], v[52:55]
	v_mfma_f32_16x16x32_bf16 v[48:51], v[172:175], v[188:191], v[48:51]
	v_mfma_f32_16x16x32_bf16 v[44:47], v[164:167], v[196:199], v[44:47]
	v_mfma_f32_16x16x32_bf16 v[40:43], v[172:175], v[196:199], v[40:43]
	v_mfma_f32_16x16x32_bf16 v[36:39], v[164:167], v[204:207], v[36:39]
	v_mfma_f32_16x16x32_bf16 v[32:35], v[172:175], v[204:207], v[32:35]
	v_mfma_f32_16x16x32_bf16 v[60:63], v[168:171], v[184:187], v[60:63]
	v_mfma_f32_16x16x32_bf16 v[56:59], v[176:179], v[184:187], v[56:59]
	v_mfma_f32_16x16x32_bf16 v[52:55], v[168:171], v[192:195], v[52:55]
	v_mfma_f32_16x16x32_bf16 v[48:51], v[176:179], v[192:195], v[48:51]
	v_mfma_f32_16x16x32_bf16 v[44:47], v[168:171], v[200:203], v[44:47]
	v_mfma_f32_16x16x32_bf16 v[40:43], v[176:179], v[200:203], v[40:43]
	v_mfma_f32_16x16x32_bf16 v[36:39], v[168:171], v[208:211], v[36:39]
	v_mfma_f32_16x16x32_bf16 v[32:35], v[176:179], v[208:211], v[32:35]
	s_setprio 0
	s_barrier
	v_lshl_add_u64 v[132:133], v[132:133], 0, s[58:59]
	v_lshl_add_u64 v[228:229], s[50:51], 0, v[132:133]
	s_mov_b64 s[66:67], 0xe080080
	v_readfirstlane_b32 s65, v161
	v_lshl_add_u64 v[166:167], v[228:229], 0, s[66:67]
	s_mov_b32 m0, s65
	s_mov_b64 s[66:67], 0xe0c0080
	v_readfirstlane_b32 s65, v160
	global_load_lds_dwordx4 v[166:167], off
	v_lshl_add_u64 v[166:167], v[228:229], 0, s[66:67]
	s_mov_b32 m0, s65
	s_nop 0
	global_load_lds_dwordx4 v[166:167], off
	s_waitcnt vmcnt(12)
	s_barrier
	s_setprio 1
	v_mfma_f32_16x16x32_bf16 v[28:31], v[212:215], v[180:183], v[28:31]
	v_mfma_f32_16x16x32_bf16 v[24:27], v[220:223], v[180:183], v[24:27]
	v_mfma_f32_16x16x32_bf16 v[20:23], v[212:215], v[188:191], v[20:23]
	v_mfma_f32_16x16x32_bf16 v[16:19], v[220:223], v[188:191], v[16:19]
	v_mfma_f32_16x16x32_bf16 v[12:15], v[212:215], v[196:199], v[12:15]
	v_mfma_f32_16x16x32_bf16 v[8:11], v[220:223], v[196:199], v[8:11]
	v_mfma_f32_16x16x32_bf16 v[4:7], v[212:215], v[204:207], v[4:7]
	v_mfma_f32_16x16x32_bf16 v[0:3], v[220:223], v[204:207], v[0:3]
	v_mfma_f32_16x16x32_bf16 v[28:31], v[216:219], v[184:187], v[28:31]
	v_mfma_f32_16x16x32_bf16 v[24:27], v[224:227], v[184:187], v[24:27]
	v_mfma_f32_16x16x32_bf16 v[20:23], v[216:219], v[192:195], v[20:23]
	v_mfma_f32_16x16x32_bf16 v[16:19], v[224:227], v[192:195], v[16:19]
	v_mfma_f32_16x16x32_bf16 v[12:15], v[216:219], v[200:203], v[12:15]
	v_mfma_f32_16x16x32_bf16 v[8:11], v[224:227], v[200:203], v[8:11]
	v_mfma_f32_16x16x32_bf16 v[4:7], v[216:219], v[208:211], v[4:7]
	v_mfma_f32_16x16x32_bf16 v[0:3], v[224:227], v[208:211], v[0:3]
	s_setprio 0
	s_add_i32 s24, s24, 2
	v_lshl_add_u64 v[130:131], v[130:131], 0, s[10:11]
	s_cmp_lt_u32 s24, 28
	s_barrier
	s_cbranch_scc1 .LBB0_178
	s_lshl_b32 s24, s85, 5
	s_lshl_b32 s65, s85, 8
	s_and_b32 s24, s24, 0x1800
	s_and_b32 s65, s65, 0x700
	s_or_b32 s24, s65, s24
	v_lshlrev_b32_e32 v128, 3, v156
	v_lshlrev_b32_e32 v130, 5, v156
	v_and_b32_e32 v128, 0xffff0, v128
	v_and_b32_e32 v130, 32, v130
	s_lshl_b32 s65, s24, 12
	v_add_u32_e32 v130, v130, v158
	v_add_lshl_u32 v128, v157, v128, 12
	s_add_u32 s66, s68, s65
	v_lshl_add_u32 v128, v130, 1, v128
	s_addc_u32 s67, s69, 0
	v_lshl_add_u64 v[156:157], s[66:67], 0, v[128:129]
	v_readfirstlane_b32 s65, v161
	ds_read_b128 v[130:133], v162
	ds_read_b128 v[164:167], v162 offset:1024
	ds_read_b128 v[168:171], v162 offset:2048
	ds_read_b128 v[172:175], v162 offset:3072
	ds_read_b128 v[176:179], v153
	ds_read_b128 v[180:183], v153 offset:1024
	ds_read_b128 v[184:187], v152
	ds_read_b128 v[188:191], v152 offset:1024
	ds_read_b128 v[192:195], v151
	ds_read_b128 v[196:199], v151 offset:1024
	ds_read_b128 v[200:203], v150
	ds_read_b128 v[204:207], v150 offset:1024
	v_lshl_add_u64 v[162:163], v[156:157], 0, s[60:61]
	s_mov_b32 m0, s65
	v_readfirstlane_b32 s65, v160
	global_load_lds_dwordx4 v[162:163], off
	v_lshl_add_u64 v[156:157], v[156:157], 0, s[62:63]
	s_mov_b32 m0, s65
	s_nop 0
	global_load_lds_dwordx4 v[156:157], off
	s_waitcnt vmcnt(10)
	s_barrier
	s_waitcnt lgkmcnt(0)
	s_setprio 1
	s_waitcnt lgkmcnt(0)
	v_mfma_f32_16x16x32_bf16 v[124:127], v[130:133], v[176:179], v[124:127]
	v_mfma_f32_16x16x32_bf16 v[120:123], v[168:171], v[176:179], v[120:123]
	v_mfma_f32_16x16x32_bf16 v[116:119], v[130:133], v[184:187], v[116:119]
	v_mfma_f32_16x16x32_bf16 v[112:115], v[168:171], v[184:187], v[112:115]
	v_mfma_f32_16x16x32_bf16 v[108:111], v[130:133], v[192:195], v[108:111]
	v_mfma_f32_16x16x32_bf16 v[104:107], v[168:171], v[192:195], v[104:107]
	v_mfma_f32_16x16x32_bf16 v[100:103], v[130:133], v[200:203], v[100:103]
	v_mfma_f32_16x16x32_bf16 v[96:99], v[168:171], v[200:203], v[96:99]
	v_mfma_f32_16x16x32_bf16 v[124:127], v[164:167], v[180:183], v[124:127]
	v_mfma_f32_16x16x32_bf16 v[120:123], v[172:175], v[180:183], v[120:123]
	v_mfma_f32_16x16x32_bf16 v[116:119], v[164:167], v[188:191], v[116:119]
	v_mfma_f32_16x16x32_bf16 v[112:115], v[172:175], v[188:191], v[112:115]
	v_mfma_f32_16x16x32_bf16 v[108:111], v[164:167], v[196:199], v[108:111]
	v_mfma_f32_16x16x32_bf16 v[104:107], v[172:175], v[196:199], v[104:107]
	v_mfma_f32_16x16x32_bf16 v[100:103], v[164:167], v[204:207], v[100:103]
	v_mfma_f32_16x16x32_bf16 v[96:99], v[172:175], v[204:207], v[96:99]
	s_setprio 0
	s_barrier
	ds_read_b128 v[160:163], v159
	ds_read_b128 v[208:211], v159 offset:1024
	ds_read_b128 v[212:215], v159 offset:2048
	ds_read_b128 v[156:159], v159 offset:3072
	s_barrier
	s_waitcnt lgkmcnt(0)
	s_setprio 1
	s_waitcnt lgkmcnt(0)
	v_mfma_f32_16x16x32_bf16 v[92:95], v[160:163], v[176:179], v[92:95]
	v_mfma_f32_16x16x32_bf16 v[88:91], v[212:215], v[176:179], v[88:91]
	v_mfma_f32_16x16x32_bf16 v[84:87], v[160:163], v[184:187], v[84:87]
	v_mfma_f32_16x16x32_bf16 v[80:83], v[212:215], v[184:187], v[80:83]
	v_mfma_f32_16x16x32_bf16 v[76:79], v[160:163], v[192:195], v[76:79]
	v_mfma_f32_16x16x32_bf16 v[72:75], v[212:215], v[192:195], v[72:75]
	v_mfma_f32_16x16x32_bf16 v[68:71], v[160:163], v[200:203], v[68:71]
	v_mfma_f32_16x16x32_bf16 v[64:67], v[212:215], v[200:203], v[64:67]
	v_mfma_f32_16x16x32_bf16 v[176:179], v[208:211], v[180:183], v[92:95]
	v_mfma_f32_16x16x32_bf16 v[180:183], v[156:159], v[180:183], v[88:91]
	v_mfma_f32_16x16x32_bf16 v[184:187], v[208:211], v[188:191], v[84:87]
	v_mfma_f32_16x16x32_bf16 v[188:191], v[156:159], v[188:191], v[80:83]
	v_mfma_f32_16x16x32_bf16 v[192:195], v[208:211], v[196:199], v[76:79]
	v_mfma_f32_16x16x32_bf16 v[196:199], v[156:159], v[196:199], v[72:75]
	v_mfma_f32_16x16x32_bf16 v[200:203], v[208:211], v[204:207], v[68:71]
	v_mfma_f32_16x16x32_bf16 v[204:207], v[156:159], v[204:207], v[64:67]
	s_setprio 0
	s_barrier
	s_nop 0
	ds_read_b128 v[64:67], v153 offset:16384
	ds_read_b128 v[68:71], v153 offset:17408
	ds_read_b128 v[72:75], v152 offset:16384
	ds_read_b128 v[76:79], v152 offset:17408
	ds_read_b128 v[80:83], v151 offset:16384
	ds_read_b128 v[84:87], v151 offset:17408
	ds_read_b128 v[88:91], v150 offset:16384
	ds_read_b128 v[92:95], v150 offset:17408
	s_waitcnt vmcnt(4)
	s_barrier
	s_waitcnt lgkmcnt(0)
	s_setprio 1
	s_waitcnt lgkmcnt(0)
	v_mfma_f32_16x16x32_bf16 v[60:63], v[130:133], v[64:67], v[60:63]
	v_mfma_f32_16x16x32_bf16 v[56:59], v[168:171], v[64:67], v[56:59]
	v_mfma_f32_16x16x32_bf16 v[52:55], v[130:133], v[72:75], v[52:55]
	v_mfma_f32_16x16x32_bf16 v[48:51], v[168:171], v[72:75], v[48:51]
	v_mfma_f32_16x16x32_bf16 v[216:219], v[130:133], v[80:83], v[44:47]
	v_mfma_f32_16x16x32_bf16 v[220:223], v[168:171], v[80:83], v[40:43]
	v_mfma_f32_16x16x32_bf16 v[130:133], v[130:133], v[88:91], v[36:39]
	v_mfma_f32_16x16x32_bf16 v[168:171], v[168:171], v[88:91], v[32:35]
	v_mfma_f32_16x16x32_bf16 v[32:35], v[164:167], v[68:71], v[60:63]
	v_mfma_f32_16x16x32_bf16 v[36:39], v[172:175], v[68:71], v[56:59]
	v_mfma_f32_16x16x32_bf16 v[40:43], v[164:167], v[76:79], v[52:55]
	v_mfma_f32_16x16x32_bf16 v[44:47], v[172:175], v[76:79], v[48:51]
	v_mfma_f32_16x16x32_bf16 v[48:51], v[164:167], v[84:87], v[216:219]
	v_mfma_f32_16x16x32_bf16 v[52:55], v[172:175], v[84:87], v[220:223]
	v_mfma_f32_16x16x32_bf16 v[56:59], v[164:167], v[92:95], v[130:133]
	v_mfma_f32_16x16x32_bf16 v[60:63], v[172:175], v[92:95], v[168:171]
	s_setprio 0
	s_setprio 1
	v_mfma_f32_16x16x32_bf16 v[28:31], v[160:163], v[64:67], v[28:31]
	v_mfma_f32_16x16x32_bf16 v[24:27], v[212:215], v[64:67], v[24:27]
	v_mfma_f32_16x16x32_bf16 v[20:23], v[160:163], v[72:75], v[20:23]
	v_mfma_f32_16x16x32_bf16 v[64:67], v[212:215], v[72:75], v[16:19]
	v_mfma_f32_16x16x32_bf16 v[72:75], v[160:163], v[80:83], v[12:15]
	v_mfma_f32_16x16x32_bf16 v[8:11], v[212:215], v[80:83], v[8:11]
	v_mfma_f32_16x16x32_bf16 v[80:83], v[160:163], v[88:91], v[4:7]
	v_mfma_f32_16x16x32_bf16 v[0:3], v[212:215], v[88:91], v[0:3]
	v_mfma_f32_16x16x32_bf16 v[4:7], v[208:211], v[68:71], v[28:31]
	v_mfma_f32_16x16x32_bf16 v[12:15], v[156:159], v[68:71], v[24:27]
	v_mfma_f32_16x16x32_bf16 v[16:19], v[208:211], v[76:79], v[20:23]
	v_mfma_f32_16x16x32_bf16 v[20:23], v[156:159], v[76:79], v[64:67]
	v_mfma_f32_16x16x32_bf16 v[24:27], v[208:211], v[84:87], v[72:75]
	v_mfma_f32_16x16x32_bf16 v[28:31], v[156:159], v[84:87], v[8:11]
	v_mfma_f32_16x16x32_bf16 v[64:67], v[208:211], v[92:95], v[80:83]
	v_mfma_f32_16x16x32_bf16 v[68:71], v[156:159], v[92:95], v[0:3]
	s_setprio 0
	s_barrier
	ds_read_b128 v[8:11], v155
	ds_read_b128 v[0:3], v155 offset:1024
	ds_read_b128 v[76:79], v155 offset:2048
	ds_read_b128 v[72:75], v155 offset:3072
	ds_read_b128 v[130:133], v153 offset:32768
	ds_read_b128 v[156:159], v153 offset:33792
	ds_read_b128 v[160:163], v152 offset:32768
	ds_read_b128 v[164:167], v152 offset:33792
	ds_read_b128 v[168:171], v151 offset:32768
	ds_read_b128 v[172:175], v151 offset:33792
	ds_read_b128 v[208:211], v150 offset:32768
	ds_read_b128 v[212:215], v150 offset:33792
	s_waitcnt vmcnt(2)
	s_barrier
	s_waitcnt lgkmcnt(0)
	s_setprio 1
	s_waitcnt lgkmcnt(0)
	v_mfma_f32_16x16x32_bf16 v[80:83], v[8:11], v[130:133], v[124:127]
	v_mfma_f32_16x16x32_bf16 v[84:87], v[76:79], v[130:133], v[120:123]
	v_mfma_f32_16x16x32_bf16 v[88:91], v[8:11], v[160:163], v[116:119]
	v_mfma_f32_16x16x32_bf16 v[92:95], v[76:79], v[160:163], v[112:115]
	v_mfma_f32_16x16x32_bf16 v[108:111], v[8:11], v[168:171], v[108:111]
	v_mfma_f32_16x16x32_bf16 v[104:107], v[76:79], v[168:171], v[104:107]
	v_mfma_f32_16x16x32_bf16 v[100:103], v[8:11], v[208:211], v[100:103]
	v_mfma_f32_16x16x32_bf16 v[96:99], v[76:79], v[208:211], v[96:99]
	v_mfma_f32_16x16x32_bf16 v[112:115], v[0:3], v[156:159], v[80:83]
	v_mfma_f32_16x16x32_bf16 v[116:119], v[72:75], v[156:159], v[84:87]
	v_mfma_f32_16x16x32_bf16 v[120:123], v[0:3], v[164:167], v[88:91]
	v_mfma_f32_16x16x32_bf16 v[124:127], v[72:75], v[164:167], v[92:95]
	v_mfma_f32_16x16x32_bf16 v[108:111], v[0:3], v[172:175], v[108:111]
	v_mfma_f32_16x16x32_bf16 v[104:107], v[72:75], v[172:175], v[104:107]
	v_mfma_f32_16x16x32_bf16 v[100:103], v[0:3], v[212:215], v[100:103]
	v_mfma_f32_16x16x32_bf16 v[96:99], v[72:75], v[212:215], v[96:99]
	s_setprio 0
	s_barrier
	ds_read_b128 v[88:91], v154
	ds_read_b128 v[80:83], v154 offset:1024
	ds_read_b128 v[92:95], v154 offset:2048
	ds_read_b128 v[84:87], v154 offset:3072
	s_waitcnt vmcnt(0)
	s_barrier
	s_waitcnt lgkmcnt(0)
	s_setprio 1
	s_waitcnt lgkmcnt(0)
	v_mfma_f32_16x16x32_bf16 v[176:179], v[88:91], v[130:133], v[176:179]
	v_mfma_f32_16x16x32_bf16 v[130:133], v[92:95], v[130:133], v[180:183]
	v_mfma_f32_16x16x32_bf16 v[180:183], v[88:91], v[160:163], v[184:187]
	v_mfma_f32_16x16x32_bf16 v[160:163], v[92:95], v[160:163], v[188:191]
	v_mfma_f32_16x16x32_bf16 v[184:187], v[88:91], v[168:171], v[192:195]
	v_mfma_f32_16x16x32_bf16 v[168:171], v[92:95], v[168:171], v[196:199]
	v_mfma_f32_16x16x32_bf16 v[188:191], v[88:91], v[208:211], v[200:203]
	v_mfma_f32_16x16x32_bf16 v[192:195], v[92:95], v[208:211], v[204:207]
	v_mfma_f32_16x16x32_bf16 v[176:179], v[80:83], v[156:159], v[176:179]
	v_mfma_f32_16x16x32_bf16 v[130:133], v[84:87], v[156:159], v[130:133]
	v_mfma_f32_16x16x32_bf16 v[154:157], v[80:83], v[164:167], v[180:183]
	v_mfma_f32_16x16x32_bf16 v[158:161], v[84:87], v[164:167], v[160:163]
	v_mfma_f32_16x16x32_bf16 v[162:165], v[80:83], v[172:175], v[184:187]
	v_mfma_f32_16x16x32_bf16 v[166:169], v[84:87], v[172:175], v[168:171]
	v_mfma_f32_16x16x32_bf16 v[170:173], v[80:83], v[212:215], v[188:191]
	v_mfma_f32_16x16x32_bf16 v[180:183], v[84:87], v[212:215], v[192:195]
	s_setprio 0
	s_barrier
	v_mbcnt_lo_u32_b32 v128, -1, 0
	v_mbcnt_hi_u32_b32 v128, -1, v128
	v_cvt_pk_bf16_f32 v112, v112, v113
	v_cvt_pk_bf16_f32 v113, v114, v115
	v_cvt_pk_bf16_f32 v114, v116, v117
	v_cvt_pk_bf16_f32 v115, v118, v119
	s_lshl_b32 s66, s64, 9
	v_add_u32_e32 v174, s72, v128
	v_ashrrev_i32_e32 v175, 6, v174
	v_and_b32_e32 v184, 15, v128
	v_and_b32_e32 v185, 48, v128
	v_mul_lo_u32 v186, v175, s77
	v_bfe_u32 v187, v128, 3, 3
	v_lshlrev_b32_e32 v128, 4, v128
	v_add_u32_e32 v186, 0x20000, v186
	v_lshrrev_b32_e32 v174, 2, v174
	v_and_b32_e32 v128, 0x70, v128
	v_mul_u32_u24_e32 v184, 0x90, v184
	v_and_b32_e32 v174, 64, v174
	v_add3_u32 v184, v186, v184, v185
	v_or_b32_e32 v185, v186, v128
	v_or3_b32 v174, s24, v174, v187
	v_mad_u32_u24 v185, v187, s78, v185
	ds_write_b128 v184, v[112:115]
	v_cvt_pk_bf16_f32 v112, v176, v177
	v_cvt_pk_bf16_f32 v113, v178, v179
	v_cvt_pk_bf16_f32 v114, v130, v131
	v_cvt_pk_bf16_f32 v115, v132, v133
	ds_write_b128 v184, v[112:115] offset:64
	v_lshlrev_b32_e32 v175, 7, v175
	ds_read_b128 v[112:115], v185
	v_lshlrev_b32_e32 v116, 12, v174
	v_and_or_b32 v116, v175, s79, v116
	v_or3_b32 v128, v116, s66, v128
	ds_read_b128 v[116:119], v185 offset:1152
	v_lshl_add_u64 v[130:131], s[0:1], 0, v[128:129]
	s_mov_b32 s64, 0x8000
	s_waitcnt lgkmcnt(0)
	global_store_dwordx4 v128, v[112:115], s[0:1]
	v_cvt_pk_bf16_f32 v108, v108, v109
	v_cvt_pk_bf16_f32 v109, v110, v111
	v_cvt_pk_bf16_f32 v110, v104, v105
	v_cvt_pk_bf16_f32 v111, v106, v107
	v_cvt_pk_bf16_f32 v104, v162, v163
	s_nop 1
	v_add_co_u32_e32 v112, vcc, s64, v130
	v_cvt_pk_bf16_f32 v114, v124, v125
	v_cvt_pk_bf16_f32 v115, v126, v127
	v_cvt_pk_bf16_f32 v105, v164, v165
	v_cvt_pk_bf16_f32 v106, v166, v167
	s_nop 1
	v_addc_co_u32_e32 v113, vcc, 0, v131, vcc
	global_store_dwordx4 v[112:113], v[116:119], off
	v_cvt_pk_bf16_f32 v112, v120, v121
	v_cvt_pk_bf16_f32 v113, v122, v123
	ds_write_b128 v184, v[112:115]
	v_cvt_pk_bf16_f32 v112, v154, v155
	v_cvt_pk_bf16_f32 v113, v156, v157
	v_cvt_pk_bf16_f32 v114, v158, v159
	v_cvt_pk_bf16_f32 v115, v160, v161
	ds_write_b128 v184, v[112:115] offset:64
	ds_read_b128 v[112:115], v185
	ds_read_b128 v[116:119], v185 offset:1152
	v_add_co_u32_e32 v120, vcc, s74, v130
	ds_write_b128 v184, v[108:111]
	v_cvt_pk_bf16_f32 v107, v168, v169
	ds_write_b128 v184, v[104:107] offset:64
	v_addc_co_u32_e32 v121, vcc, 0, v131, vcc
	ds_read_b128 v[104:107], v185
	ds_read_b128 v[108:111], v185 offset:1152
	s_waitcnt lgkmcnt(0)
	global_store_dwordx4 v[120:121], v[112:115], off
	v_cvt_pk_bf16_f32 v100, v100, v101
	v_cvt_pk_bf16_f32 v101, v102, v103
	v_cvt_pk_bf16_f32 v102, v96, v97
	v_cvt_pk_bf16_f32 v103, v98, v99
	ds_write_b128 v184, v[100:103]
	s_nop 0
	v_add_co_u32_e32 v112, vcc, s75, v130
	v_cvt_pk_bf16_f32 v96, v170, v171
	v_cvt_pk_bf16_f32 v97, v172, v173
	v_cvt_pk_bf16_f32 v98, v180, v181
	v_cvt_pk_bf16_f32 v99, v182, v183
	s_nop 1
	v_addc_co_u32_e32 v113, vcc, 0, v131, vcc
	global_store_dwordx4 v[112:113], v[116:119], off
	v_add_co_u32_e32 v112, vcc, s76, v130
	ds_write_b128 v184, v[96:99] offset:64
	s_nop 0
	v_addc_co_u32_e32 v113, vcc, 0, v131, vcc
	ds_read_b128 v[96:99], v185
	ds_read_b128 v[100:103], v185 offset:1152
	global_store_dwordx4 v[112:113], v[104:107], off
	s_nop 1
	v_add_co_u32_e32 v104, vcc, s80, v130
	s_nop 1
	v_addc_co_u32_e32 v105, vcc, 0, v131, vcc
	global_store_dwordx4 v[104:105], v[108:111], off
	v_add_co_u32_e32 v104, vcc, s81, v130
	s_nop 1
	v_addc_co_u32_e32 v105, vcc, 0, v131, vcc
	s_waitcnt lgkmcnt(0)
	global_store_dwordx4 v[104:105], v[96:99], off
	s_nop 1
	v_add_co_u32_e32 v96, vcc, s82, v130
	s_nop 1
	v_addc_co_u32_e32 v97, vcc, 0, v131, vcc
	global_store_dwordx4 v[96:97], v[100:103], off
	ds_read_b128 v[96:99], v153 offset:49152
	ds_read_b128 v[100:103], v153 offset:50176
	ds_read_b128 v[104:107], v152 offset:49152
	ds_read_b128 v[108:111], v152 offset:50176
	ds_read_b128 v[112:115], v151 offset:49152
	ds_read_b128 v[116:119], v151 offset:50176
	ds_read_b128 v[120:123], v150 offset:49152
	ds_read_b128 v[124:127], v150 offset:50176
	s_barrier
	s_waitcnt lgkmcnt(0)
	s_setprio 1
	s_waitcnt lgkmcnt(0)
	v_mfma_f32_16x16x32_bf16 v[32:35], v[8:11], v[96:99], v[32:35]
	v_mfma_f32_16x16x32_bf16 v[36:39], v[76:79], v[96:99], v[36:39]
	v_mfma_f32_16x16x32_bf16 v[40:43], v[8:11], v[104:107], v[40:43]
	v_mfma_f32_16x16x32_bf16 v[130:133], v[76:79], v[104:107], v[44:47]
	v_mfma_f32_16x16x32_bf16 v[150:153], v[8:11], v[112:115], v[48:51]
	v_mfma_f32_16x16x32_bf16 v[52:55], v[76:79], v[112:115], v[52:55]
	v_mfma_f32_16x16x32_bf16 v[8:11], v[8:11], v[120:123], v[56:59]
	v_mfma_f32_16x16x32_bf16 v[60:63], v[76:79], v[120:123], v[60:63]
	v_mfma_f32_16x16x32_bf16 v[56:59], v[0:3], v[100:103], v[32:35]
	v_mfma_f32_16x16x32_bf16 v[48:51], v[72:75], v[100:103], v[36:39]
	v_mfma_f32_16x16x32_bf16 v[44:47], v[0:3], v[108:111], v[40:43]
	v_mfma_f32_16x16x32_bf16 v[40:43], v[72:75], v[108:111], v[130:133]
	v_mfma_f32_16x16x32_bf16 v[36:39], v[0:3], v[116:119], v[150:153]
	v_mfma_f32_16x16x32_bf16 v[32:35], v[72:75], v[116:119], v[52:55]
	v_mfma_f32_16x16x32_bf16 v[8:11], v[0:3], v[124:127], v[8:11]
	v_mfma_f32_16x16x32_bf16 v[0:3], v[72:75], v[124:127], v[60:63]
	s_setprio 0
	s_setprio 1
	v_mfma_f32_16x16x32_bf16 v[4:7], v[88:91], v[96:99], v[4:7]
	v_mfma_f32_16x16x32_bf16 v[12:15], v[92:95], v[96:99], v[12:15]
	v_mfma_f32_16x16x32_bf16 v[16:19], v[88:91], v[104:107], v[16:19]
	v_mfma_f32_16x16x32_bf16 v[20:23], v[92:95], v[104:107], v[20:23]
	v_mfma_f32_16x16x32_bf16 v[72:75], v[88:91], v[112:115], v[24:27]
	v_mfma_f32_16x16x32_bf16 v[76:79], v[92:95], v[112:115], v[28:31]
	v_mfma_f32_16x16x32_bf16 v[64:67], v[88:91], v[120:123], v[64:67]
	v_mfma_f32_16x16x32_bf16 v[68:71], v[92:95], v[120:123], v[68:71]
	v_mfma_f32_16x16x32_bf16 v[60:63], v[80:83], v[100:103], v[4:7]
	v_mfma_f32_16x16x32_bf16 v[52:55], v[84:87], v[100:103], v[12:15]
	v_mfma_f32_16x16x32_bf16 v[28:31], v[80:83], v[108:111], v[16:19]
	v_mfma_f32_16x16x32_bf16 v[24:27], v[84:87], v[108:111], v[20:23]
	v_mfma_f32_16x16x32_bf16 v[20:23], v[80:83], v[116:119], v[72:75]
	v_mfma_f32_16x16x32_bf16 v[16:19], v[84:87], v[116:119], v[76:79]
	v_mfma_f32_16x16x32_bf16 v[12:15], v[80:83], v[124:127], v[64:67]
	v_mfma_f32_16x16x32_bf16 v[4:7], v[84:87], v[124:127], v[68:71]
	s_setprio 0
	v_cmp_gt_u32_e32 vcc, s83, v136
	s_barrier
	s_and_saveexec_b64 s[64:65], vcc
	s_cbranch_execz .LBB0_181
	s_barrier

.LBB0_234:
	ds_read_b128 v[140:143], v138
	ds_read_b128 v[144:147], v138 offset:1024
	ds_read_b128 v[148:151], v138 offset:2048
	ds_read_b128 v[152:155], v138 offset:3072
	ds_read_b128 v[156:159], v193
	ds_read_b128 v[160:163], v193 offset:1024
	ds_read_b128 v[194:197], v192
	ds_read_b128 v[198:201], v192 offset:1024
	ds_read_b128 v[202:205], v191
	ds_read_b128 v[206:209], v191 offset:1024
	ds_read_b128 v[210:213], v190
	ds_read_b128 v[214:217], v190 offset:1024
	s_waitcnt lgkmcnt(8)
	s_waitcnt vmcnt(10)
	s_barrier
	s_waitcnt lgkmcnt(0)
	s_setprio 1
	s_waitcnt lgkmcnt(0)
	v_mfma_f32_16x16x32_bf16 v[124:127], v[140:143], v[156:159], v[124:127]
	v_mfma_f32_16x16x32_bf16 v[120:123], v[148:151], v[156:159], v[120:123]
	v_mfma_f32_16x16x32_bf16 v[116:119], v[140:143], v[194:197], v[116:119]
	v_mfma_f32_16x16x32_bf16 v[112:115], v[148:151], v[194:197], v[112:115]
	v_mfma_f32_16x16x32_bf16 v[108:111], v[140:143], v[202:205], v[108:111]
	v_mfma_f32_16x16x32_bf16 v[104:107], v[148:151], v[202:205], v[104:107]
	v_mfma_f32_16x16x32_bf16 v[100:103], v[140:143], v[210:213], v[100:103]
	v_mfma_f32_16x16x32_bf16 v[96:99], v[148:151], v[210:213], v[96:99]
	v_mfma_f32_16x16x32_bf16 v[124:127], v[144:147], v[160:163], v[124:127]
	v_mfma_f32_16x16x32_bf16 v[120:123], v[152:155], v[160:163], v[120:123]
	v_mfma_f32_16x16x32_bf16 v[116:119], v[144:147], v[198:201], v[116:119]
	v_mfma_f32_16x16x32_bf16 v[112:115], v[152:155], v[198:201], v[112:115]
	v_mfma_f32_16x16x32_bf16 v[108:111], v[144:147], v[206:209], v[108:111]
	v_mfma_f32_16x16x32_bf16 v[104:107], v[152:155], v[206:209], v[104:107]
	v_mfma_f32_16x16x32_bf16 v[100:103], v[144:147], v[214:217], v[100:103]
	v_mfma_f32_16x16x32_bf16 v[96:99], v[152:155], v[214:217], v[96:99]
	s_setprio 0
	s_barrier
	v_readfirstlane_b32 s82, v189
	v_lshl_add_u64 v[234:235], s[60:61], 0, v[164:165]
	s_mov_b32 m0, s82
	v_readfirstlane_b32 s82, v188
	ds_read_b128 v[218:221], v135
	ds_read_b128 v[222:225], v135 offset:1024
	ds_read_b128 v[226:229], v135 offset:2048
	ds_read_b128 v[230:233], v135 offset:3072
	global_load_lds_dwordx4 v[234:235], off
	v_lshl_add_u64 v[236:237], v[234:235], 0, s[2:3]
	s_mov_b32 m0, s82
	s_nop 0
	global_load_lds_dwordx4 v[236:237], off
	v_readfirstlane_b32 s82, v169
	v_lshl_add_u64 v[236:237], v[128:129], 0, s[22:23]
	s_mov_b32 m0, s82
	v_readfirstlane_b32 s82, v187
	global_load_lds_dwordx4 v[236:237], off
	v_lshl_add_u64 v[236:237], v[128:129], 0, s[24:25]
	s_mov_b32 m0, s82
	s_nop 0
	global_load_lds_dwordx4 v[236:237], off
	s_waitcnt vmcnt(12)
	s_barrier
	s_waitcnt lgkmcnt(0)
	s_setprio 1
	s_waitcnt lgkmcnt(0)
	v_mfma_f32_16x16x32_bf16 v[92:95], v[218:221], v[156:159], v[92:95]
	v_mfma_f32_16x16x32_bf16 v[88:91], v[226:229], v[156:159], v[88:91]
	v_mfma_f32_16x16x32_bf16 v[84:87], v[218:221], v[194:197], v[84:87]
	v_mfma_f32_16x16x32_bf16 v[80:83], v[226:229], v[194:197], v[80:83]
	v_mfma_f32_16x16x32_bf16 v[76:79], v[218:221], v[202:205], v[76:79]
	v_mfma_f32_16x16x32_bf16 v[72:75], v[226:229], v[202:205], v[72:75]
	v_mfma_f32_16x16x32_bf16 v[68:71], v[218:221], v[210:213], v[68:71]
	v_mfma_f32_16x16x32_bf16 v[64:67], v[226:229], v[210:213], v[64:67]
	v_mfma_f32_16x16x32_bf16 v[92:95], v[222:225], v[160:163], v[92:95]
	v_mfma_f32_16x16x32_bf16 v[88:91], v[230:233], v[160:163], v[88:91]
	v_mfma_f32_16x16x32_bf16 v[84:87], v[222:225], v[198:201], v[84:87]
	v_mfma_f32_16x16x32_bf16 v[80:83], v[230:233], v[198:201], v[80:83]
	v_mfma_f32_16x16x32_bf16 v[76:79], v[222:225], v[206:209], v[76:79]
	v_mfma_f32_16x16x32_bf16 v[72:75], v[230:233], v[206:209], v[72:75]
	v_mfma_f32_16x16x32_bf16 v[68:71], v[222:225], v[214:217], v[68:71]
	v_mfma_f32_16x16x32_bf16 v[64:67], v[230:233], v[214:217], v[64:67]
	s_setprio 0
	s_barrier
	ds_read_b128 v[156:159], v193 offset:16384
	ds_read_b128 v[160:163], v193 offset:17408
	ds_read_b128 v[194:197], v192 offset:16384
	ds_read_b128 v[198:201], v192 offset:17408
	ds_read_b128 v[202:205], v191 offset:16384
	ds_read_b128 v[206:209], v191 offset:17408
	ds_read_b128 v[210:213], v190 offset:16384
	ds_read_b128 v[214:217], v190 offset:17408
	v_readfirstlane_b32 s82, v186
	v_lshl_add_u64 v[236:237], v[234:235], 0, s[6:7]
	s_mov_b32 m0, s82
	v_readfirstlane_b32 s82, v185
	global_load_lds_dwordx4 v[236:237], off
	v_lshl_add_u64 v[236:237], v[234:235], 0, s[8:9]
	s_mov_b32 m0, s82
	s_nop 0
	global_load_lds_dwordx4 v[236:237], off
	s_barrier
	s_waitcnt lgkmcnt(0)
	s_setprio 1
	s_waitcnt lgkmcnt(0)
	v_mfma_f32_16x16x32_bf16 v[60:63], v[140:143], v[156:159], v[60:63]
	v_mfma_f32_16x16x32_bf16 v[56:59], v[148:151], v[156:159], v[56:59]
	v_mfma_f32_16x16x32_bf16 v[52:55], v[140:143], v[194:197], v[52:55]
	v_mfma_f32_16x16x32_bf16 v[48:51], v[148:151], v[194:197], v[48:51]
	v_mfma_f32_16x16x32_bf16 v[44:47], v[140:143], v[202:205], v[44:47]
	v_mfma_f32_16x16x32_bf16 v[40:43], v[148:151], v[202:205], v[40:43]
	v_mfma_f32_16x16x32_bf16 v[36:39], v[140:143], v[210:213], v[36:39]
	v_mfma_f32_16x16x32_bf16 v[32:35], v[148:151], v[210:213], v[32:35]
	v_mfma_f32_16x16x32_bf16 v[60:63], v[144:147], v[160:163], v[60:63]
	v_mfma_f32_16x16x32_bf16 v[56:59], v[152:155], v[160:163], v[56:59]
	v_mfma_f32_16x16x32_bf16 v[52:55], v[144:147], v[198:201], v[52:55]
	v_mfma_f32_16x16x32_bf16 v[48:51], v[152:155], v[198:201], v[48:51]
	v_mfma_f32_16x16x32_bf16 v[44:47], v[144:147], v[206:209], v[44:47]
	v_mfma_f32_16x16x32_bf16 v[40:43], v[152:155], v[206:209], v[40:43]
	v_mfma_f32_16x16x32_bf16 v[36:39], v[144:147], v[214:217], v[36:39]
	v_mfma_f32_16x16x32_bf16 v[32:35], v[152:155], v[214:217], v[32:35]
	s_setprio 0
	s_barrier
	v_readfirstlane_b32 s82, v184
	v_lshl_add_u64 v[142:143], v[128:129], 0, s[26:27]
	s_mov_b32 m0, s82
	v_readfirstlane_b32 s82, v183
	global_load_lds_dwordx4 v[142:143], off
	s_mov_b32 m0, s82
	s_nop 0
	global_load_lds_dwordx4 v[128:129], off
	s_waitcnt vmcnt(12)
	s_barrier
	s_setprio 1
	v_mfma_f32_16x16x32_bf16 v[28:31], v[218:221], v[156:159], v[28:31]
	v_mfma_f32_16x16x32_bf16 v[24:27], v[226:229], v[156:159], v[24:27]
	v_mfma_f32_16x16x32_bf16 v[20:23], v[218:221], v[194:197], v[20:23]
	v_mfma_f32_16x16x32_bf16 v[16:19], v[226:229], v[194:197], v[16:19]
	v_mfma_f32_16x16x32_bf16 v[12:15], v[218:221], v[202:205], v[12:15]
	v_mfma_f32_16x16x32_bf16 v[8:11], v[226:229], v[202:205], v[8:11]
	v_mfma_f32_16x16x32_bf16 v[4:7], v[218:221], v[210:213], v[4:7]
	v_mfma_f32_16x16x32_bf16 v[0:3], v[226:229], v[210:213], v[0:3]
	v_mfma_f32_16x16x32_bf16 v[28:31], v[222:225], v[160:163], v[28:31]
	v_mfma_f32_16x16x32_bf16 v[24:27], v[230:233], v[160:163], v[24:27]
	v_mfma_f32_16x16x32_bf16 v[20:23], v[222:225], v[198:201], v[20:23]
	v_mfma_f32_16x16x32_bf16 v[16:19], v[230:233], v[198:201], v[16:19]
	v_mfma_f32_16x16x32_bf16 v[12:15], v[222:225], v[206:209], v[12:15]
	v_mfma_f32_16x16x32_bf16 v[8:11], v[230:233], v[206:209], v[8:11]
	v_mfma_f32_16x16x32_bf16 v[4:7], v[222:225], v[214:217], v[4:7]
	v_mfma_f32_16x16x32_bf16 v[0:3], v[230:233], v[214:217], v[0:3]
	s_setprio 0
	s_barrier
	ds_read_b128 v[140:143], v130
	ds_read_b128 v[144:147], v130 offset:1024
	ds_read_b128 v[148:151], v130 offset:2048
	ds_read_b128 v[152:155], v130 offset:3072
	ds_read_b128 v[156:159], v193 offset:32768
	ds_read_b128 v[160:163], v193 offset:33792
	ds_read_b128 v[194:197], v192 offset:32768
	ds_read_b128 v[198:201], v192 offset:33792
	ds_read_b128 v[202:205], v191 offset:32768
	ds_read_b128 v[206:209], v191 offset:33792
	ds_read_b128 v[210:213], v190 offset:32768
	ds_read_b128 v[214:217], v190 offset:33792
	s_waitcnt lgkmcnt(8)
	s_waitcnt vmcnt(10)
	s_barrier
	s_waitcnt lgkmcnt(0)
	s_setprio 1
	s_waitcnt lgkmcnt(0)
	v_mfma_f32_16x16x32_bf16 v[124:127], v[140:143], v[156:159], v[124:127]
	v_mfma_f32_16x16x32_bf16 v[120:123], v[148:151], v[156:159], v[120:123]
	v_mfma_f32_16x16x32_bf16 v[116:119], v[140:143], v[194:197], v[116:119]
	v_mfma_f32_16x16x32_bf16 v[112:115], v[148:151], v[194:197], v[112:115]
	v_mfma_f32_16x16x32_bf16 v[108:111], v[140:143], v[202:205], v[108:111]
	v_mfma_f32_16x16x32_bf16 v[104:107], v[148:151], v[202:205], v[104:107]
	v_mfma_f32_16x16x32_bf16 v[100:103], v[140:143], v[210:213], v[100:103]
	v_mfma_f32_16x16x32_bf16 v[96:99], v[148:151], v[210:213], v[96:99]
	v_mfma_f32_16x16x32_bf16 v[124:127], v[144:147], v[160:163], v[124:127]
	v_mfma_f32_16x16x32_bf16 v[120:123], v[152:155], v[160:163], v[120:123]
	v_mfma_f32_16x16x32_bf16 v[116:119], v[144:147], v[198:201], v[116:119]
	v_mfma_f32_16x16x32_bf16 v[112:115], v[152:155], v[198:201], v[112:115]
	v_mfma_f32_16x16x32_bf16 v[108:111], v[144:147], v[206:209], v[108:111]
	v_mfma_f32_16x16x32_bf16 v[104:107], v[152:155], v[206:209], v[104:107]
	v_mfma_f32_16x16x32_bf16 v[100:103], v[144:147], v[214:217], v[100:103]
	v_mfma_f32_16x16x32_bf16 v[96:99], v[152:155], v[214:217], v[96:99]
	s_setprio 0
	s_barrier
	v_readfirstlane_b32 s82, v182
	v_lshl_add_u64 v[234:235], s[56:57], 0, v[164:165]
	s_mov_b32 m0, s82
	v_readfirstlane_b32 s82, v181
	ds_read_b128 v[218:221], v132
	ds_read_b128 v[222:225], v132 offset:1024
	ds_read_b128 v[226:229], v132 offset:2048
	ds_read_b128 v[230:233], v132 offset:3072
	global_load_lds_dwordx4 v[234:235], off
	v_lshl_add_u64 v[236:237], v[234:235], 0, s[2:3]
	s_mov_b32 m0, s82
	s_nop 0
	global_load_lds_dwordx4 v[236:237], off
	v_readfirstlane_b32 s82, v177
	v_lshl_add_u64 v[236:237], v[128:129], 0, s[28:29]
	s_mov_b32 m0, s82
	v_readfirstlane_b32 s82, v175
	global_load_lds_dwordx4 v[236:237], off
	v_lshl_add_u64 v[236:237], v[128:129], 0, s[30:31]
	s_mov_b32 m0, s82
	s_nop 0
	global_load_lds_dwordx4 v[236:237], off
	s_waitcnt vmcnt(12)
	s_barrier
	s_waitcnt lgkmcnt(0)
	s_setprio 1
	s_waitcnt lgkmcnt(0)
	v_mfma_f32_16x16x32_bf16 v[92:95], v[218:221], v[156:159], v[92:95]
	v_mfma_f32_16x16x32_bf16 v[88:91], v[226:229], v[156:159], v[88:91]
	v_mfma_f32_16x16x32_bf16 v[84:87], v[218:221], v[194:197], v[84:87]
	v_mfma_f32_16x16x32_bf16 v[80:83], v[226:229], v[194:197], v[80:83]
	v_mfma_f32_16x16x32_bf16 v[76:79], v[218:221], v[202:205], v[76:79]
	v_mfma_f32_16x16x32_bf16 v[72:75], v[226:229], v[202:205], v[72:75]
	v_mfma_f32_16x16x32_bf16 v[68:71], v[218:221], v[210:213], v[68:71]
	v_mfma_f32_16x16x32_bf16 v[64:67], v[226:229], v[210:213], v[64:67]
	v_mfma_f32_16x16x32_bf16 v[92:95], v[222:225], v[160:163], v[92:95]
	v_mfma_f32_16x16x32_bf16 v[88:91], v[230:233], v[160:163], v[88:91]
	v_mfma_f32_16x16x32_bf16 v[84:87], v[222:225], v[198:201], v[84:87]
	v_mfma_f32_16x16x32_bf16 v[80:83], v[230:233], v[198:201], v[80:83]
	v_mfma_f32_16x16x32_bf16 v[76:79], v[222:225], v[206:209], v[76:79]
	v_mfma_f32_16x16x32_bf16 v[72:75], v[230:233], v[206:209], v[72:75]
	v_mfma_f32_16x16x32_bf16 v[68:71], v[222:225], v[214:217], v[68:71]
	v_mfma_f32_16x16x32_bf16 v[64:67], v[230:233], v[214:217], v[64:67]
	s_setprio 0
	s_barrier
	ds_read_b128 v[156:159], v193 offset:49152
	ds_read_b128 v[160:163], v193 offset:50176
	ds_read_b128 v[194:197], v192 offset:49152
	ds_read_b128 v[198:201], v192 offset:50176
	ds_read_b128 v[202:205], v191 offset:49152
	ds_read_b128 v[206:209], v191 offset:50176
	ds_read_b128 v[210:213], v190 offset:49152
	ds_read_b128 v[214:217], v190 offset:50176
	v_readfirstlane_b32 s82, v173
	v_lshl_add_u64 v[236:237], v[234:235], 0, s[6:7]
	s_mov_b32 m0, s82
	v_readfirstlane_b32 s82, v171
	global_load_lds_dwordx4 v[236:237], off
	v_lshl_add_u64 v[236:237], v[234:235], 0, s[8:9]
	s_mov_b32 m0, s82
	s_nop 0
	global_load_lds_dwordx4 v[236:237], off
	s_barrier
	s_waitcnt lgkmcnt(0)
	s_setprio 1
	s_waitcnt lgkmcnt(0)
	v_mfma_f32_16x16x32_bf16 v[60:63], v[140:143], v[156:159], v[60:63]
	v_mfma_f32_16x16x32_bf16 v[56:59], v[148:151], v[156:159], v[56:59]
	v_mfma_f32_16x16x32_bf16 v[52:55], v[140:143], v[194:197], v[52:55]
	v_mfma_f32_16x16x32_bf16 v[48:51], v[148:151], v[194:197], v[48:51]
	v_mfma_f32_16x16x32_bf16 v[44:47], v[140:143], v[202:205], v[44:47]
	v_mfma_f32_16x16x32_bf16 v[40:43], v[148:151], v[202:205], v[40:43]
	v_mfma_f32_16x16x32_bf16 v[36:39], v[140:143], v[210:213], v[36:39]
	v_mfma_f32_16x16x32_bf16 v[32:35], v[148:151], v[210:213], v[32:35]
	v_mfma_f32_16x16x32_bf16 v[60:63], v[144:147], v[160:163], v[60:63]
	v_mfma_f32_16x16x32_bf16 v[56:59], v[152:155], v[160:163], v[56:59]
	v_mfma_f32_16x16x32_bf16 v[52:55], v[144:147], v[198:201], v[52:55]
	v_mfma_f32_16x16x32_bf16 v[48:51], v[152:155], v[198:201], v[48:51]
	v_mfma_f32_16x16x32_bf16 v[44:47], v[144:147], v[206:209], v[44:47]
	v_mfma_f32_16x16x32_bf16 v[40:43], v[152:155], v[206:209], v[40:43]
	v_mfma_f32_16x16x32_bf16 v[36:39], v[144:147], v[214:217], v[36:39]
	v_mfma_f32_16x16x32_bf16 v[32:35], v[152:155], v[214:217], v[32:35]
	s_setprio 0
	s_barrier
	v_lshl_add_u64 v[128:129], v[128:129], 0, s[34:35]
	v_readfirstlane_b32 s82, v137
	v_lshl_add_u64 v[142:143], v[128:129], 0, s[18:19]
	s_mov_b32 m0, s82
	v_readfirstlane_b32 s82, v136
	global_load_lds_dwordx4 v[142:143], off
	v_lshl_add_u64 v[142:143], v[128:129], 0, s[20:21]
	s_mov_b32 m0, s82
	s_nop 0
	global_load_lds_dwordx4 v[142:143], off
	s_waitcnt vmcnt(12)
	s_barrier
	s_setprio 1
	v_mfma_f32_16x16x32_bf16 v[28:31], v[218:221], v[156:159], v[28:31]
	v_mfma_f32_16x16x32_bf16 v[24:27], v[226:229], v[156:159], v[24:27]
	v_mfma_f32_16x16x32_bf16 v[20:23], v[218:221], v[194:197], v[20:23]
	v_mfma_f32_16x16x32_bf16 v[16:19], v[226:229], v[194:197], v[16:19]
	v_mfma_f32_16x16x32_bf16 v[12:15], v[218:221], v[202:205], v[12:15]
	v_mfma_f32_16x16x32_bf16 v[8:11], v[226:229], v[202:205], v[8:11]
	v_mfma_f32_16x16x32_bf16 v[4:7], v[218:221], v[210:213], v[4:7]
	v_mfma_f32_16x16x32_bf16 v[0:3], v[226:229], v[210:213], v[0:3]
	v_mfma_f32_16x16x32_bf16 v[28:31], v[222:225], v[160:163], v[28:31]
	v_mfma_f32_16x16x32_bf16 v[24:27], v[230:233], v[160:163], v[24:27]
	v_mfma_f32_16x16x32_bf16 v[20:23], v[222:225], v[198:201], v[20:23]
	v_mfma_f32_16x16x32_bf16 v[16:19], v[230:233], v[198:201], v[16:19]
	v_mfma_f32_16x16x32_bf16 v[12:15], v[222:225], v[206:209], v[12:15]
	v_mfma_f32_16x16x32_bf16 v[8:11], v[230:233], v[206:209], v[8:11]
	v_mfma_f32_16x16x32_bf16 v[4:7], v[222:225], v[214:217], v[4:7]
	v_mfma_f32_16x16x32_bf16 v[0:3], v[230:233], v[214:217], v[0:3]
	s_setprio 0
	s_add_i32 s14, s14, 2
	s_add_u32 s56, s56, s58
	s_addc_u32 s57, s57, s59
	s_add_u32 s60, s60, s58
	s_addc_u32 s61, s61, s59
	s_cmp_lt_u32 s14, 28
	s_barrier
	s_cbranch_scc1 .LBB0_234
	s_lshl_b32 s14, s62, 3
	s_or_b32 s82, s63, s14
	s_lshl_b32 s56, s82, 8
	v_lshlrev_b32_e32 v128, 3, v131
	v_lshlrev_b32_e32 v129, 5, v131
	s_or_b32 s14, s56, 0x80
	v_and_b32_e32 v128, 0x7fff0, v128
	v_and_b32_e32 v129, 32, v129
	s_lshl_b64 s[58:59], s[14:15], 13
	v_add_u32_e32 v129, v129, v134
	v_add_lshl_u32 v128, v133, v128, 13
	s_add_u32 s58, s40, s58
	v_lshl_add_u32 v164, v129, 1, v128
	s_addc_u32 s59, s41, s59
	v_lshl_add_u64 v[128:129], s[58:59], 0, v[164:165]
	v_readfirstlane_b32 s14, v137
	ds_read_b128 v[140:143], v138
	ds_read_b128 v[144:147], v138 offset:1024
	ds_read_b128 v[148:151], v138 offset:2048
	ds_read_b128 v[152:155], v138 offset:3072
	ds_read_b128 v[156:159], v193
	ds_read_b128 v[160:163], v193 offset:1024
	ds_read_b128 v[194:197], v192
	ds_read_b128 v[198:201], v192 offset:1024
	ds_read_b128 v[202:205], v191
	ds_read_b128 v[206:209], v191 offset:1024
	ds_read_b128 v[210:213], v190
	ds_read_b128 v[214:217], v190 offset:1024
	v_lshl_add_u64 v[138:139], v[128:129], 0, s[44:45]
	s_mov_b32 m0, s14
	v_readfirstlane_b32 s14, v136
	global_load_lds_dwordx4 v[138:139], off
	v_lshl_add_u64 v[128:129], v[128:129], 0, s[46:47]
	s_mov_b32 m0, s14
	s_mov_b32 s57, s15
	global_load_lds_dwordx4 v[128:129], off
	s_waitcnt vmcnt(10)
	s_barrier
	s_waitcnt lgkmcnt(0)
	s_setprio 1
	s_waitcnt lgkmcnt(0)
	v_mfma_f32_16x16x32_bf16 v[124:127], v[140:143], v[156:159], v[124:127]
	v_mfma_f32_16x16x32_bf16 v[120:123], v[148:151], v[156:159], v[120:123]
	v_mfma_f32_16x16x32_bf16 v[116:119], v[140:143], v[194:197], v[116:119]
	v_mfma_f32_16x16x32_bf16 v[112:115], v[148:151], v[194:197], v[112:115]
	v_mfma_f32_16x16x32_bf16 v[108:111], v[140:143], v[202:205], v[108:111]
	v_mfma_f32_16x16x32_bf16 v[104:107], v[148:151], v[202:205], v[104:107]
	v_mfma_f32_16x16x32_bf16 v[100:103], v[140:143], v[210:213], v[100:103]
	v_mfma_f32_16x16x32_bf16 v[96:99], v[148:151], v[210:213], v[96:99]
	v_mfma_f32_16x16x32_bf16 v[124:127], v[144:147], v[160:163], v[124:127]
	v_mfma_f32_16x16x32_bf16 v[120:123], v[152:155], v[160:163], v[120:123]
	v_mfma_f32_16x16x32_bf16 v[116:119], v[144:147], v[198:201], v[116:119]
	v_mfma_f32_16x16x32_bf16 v[112:115], v[152:155], v[198:201], v[112:115]
	v_mfma_f32_16x16x32_bf16 v[108:111], v[144:147], v[206:209], v[108:111]
	v_mfma_f32_16x16x32_bf16 v[104:107], v[152:155], v[206:209], v[104:107]
	v_mfma_f32_16x16x32_bf16 v[100:103], v[144:147], v[214:217], v[100:103]
	v_mfma_f32_16x16x32_bf16 v[96:99], v[152:155], v[214:217], v[96:99]
	s_setprio 0
	s_barrier
	ds_read_b128 v[136:139], v135
	ds_read_b128 v[218:221], v135 offset:1024
	ds_read_b128 v[222:225], v135 offset:2048
	ds_read_b128 v[226:229], v135 offset:3072
	s_barrier
	s_waitcnt lgkmcnt(0)
	s_setprio 1
	s_waitcnt lgkmcnt(0)
	v_mfma_f32_16x16x32_bf16 v[92:95], v[136:139], v[156:159], v[92:95]
	v_mfma_f32_16x16x32_bf16 v[84:87], v[136:139], v[194:197], v[84:87]
	v_mfma_f32_16x16x32_bf16 v[80:83], v[222:225], v[194:197], v[80:83]
	v_mfma_f32_16x16x32_bf16 v[88:91], v[222:225], v[156:159], v[88:91]
	v_mfma_f32_16x16x32_bf16 v[76:79], v[136:139], v[202:205], v[76:79]
	v_mfma_f32_16x16x32_bf16 v[72:75], v[222:225], v[202:205], v[72:75]
	v_mfma_f32_16x16x32_bf16 v[68:71], v[136:139], v[210:213], v[68:71]
	v_mfma_f32_16x16x32_bf16 v[64:67], v[222:225], v[210:213], v[64:67]
	v_mfma_f32_16x16x32_bf16 v[156:159], v[218:221], v[160:163], v[92:95]
	v_mfma_f32_16x16x32_bf16 v[194:197], v[218:221], v[198:201], v[84:87]
	v_mfma_f32_16x16x32_bf16 v[198:201], v[226:229], v[198:201], v[80:83]
	v_mfma_f32_16x16x32_bf16 v[160:163], v[226:229], v[160:163], v[88:91]
	v_mfma_f32_16x16x32_bf16 v[202:205], v[218:221], v[206:209], v[76:79]
	v_mfma_f32_16x16x32_bf16 v[206:209], v[226:229], v[206:209], v[72:75]
	v_mfma_f32_16x16x32_bf16 v[210:213], v[218:221], v[214:217], v[68:71]
	v_mfma_f32_16x16x32_bf16 v[214:217], v[226:229], v[214:217], v[64:67]
	s_setprio 0
	s_barrier
	s_nop 0
	ds_read_b128 v[64:67], v193 offset:16384
	ds_read_b128 v[68:71], v193 offset:17408
	ds_read_b128 v[72:75], v192 offset:16384
	ds_read_b128 v[76:79], v192 offset:17408
	ds_read_b128 v[80:83], v191 offset:16384
	ds_read_b128 v[84:87], v191 offset:17408
	ds_read_b128 v[88:91], v190 offset:16384
	ds_read_b128 v[92:95], v190 offset:17408
	s_waitcnt vmcnt(4)
	s_barrier
	s_waitcnt lgkmcnt(0)
	s_setprio 1
	s_waitcnt lgkmcnt(0)
	v_mfma_f32_16x16x32_bf16 v[60:63], v[140:143], v[64:67], v[60:63]
	v_mfma_f32_16x16x32_bf16 v[56:59], v[148:151], v[64:67], v[56:59]
	v_mfma_f32_16x16x32_bf16 v[52:55], v[140:143], v[72:75], v[52:55]
	v_mfma_f32_16x16x32_bf16 v[48:51], v[148:151], v[72:75], v[48:51]
	v_mfma_f32_16x16x32_bf16 v[230:233], v[140:143], v[80:83], v[44:47]
	v_mfma_f32_16x16x32_bf16 v[234:237], v[148:151], v[80:83], v[40:43]
	v_mfma_f32_16x16x32_bf16 v[140:143], v[140:143], v[88:91], v[36:39]
	v_mfma_f32_16x16x32_bf16 v[148:151], v[148:151], v[88:91], v[32:35]
	v_mfma_f32_16x16x32_bf16 v[32:35], v[144:147], v[68:71], v[60:63]
	v_mfma_f32_16x16x32_bf16 v[36:39], v[152:155], v[68:71], v[56:59]
	v_mfma_f32_16x16x32_bf16 v[40:43], v[144:147], v[76:79], v[52:55]
	v_mfma_f32_16x16x32_bf16 v[44:47], v[152:155], v[76:79], v[48:51]
	v_mfma_f32_16x16x32_bf16 v[48:51], v[144:147], v[84:87], v[230:233]
	v_mfma_f32_16x16x32_bf16 v[52:55], v[152:155], v[84:87], v[234:237]
	v_mfma_f32_16x16x32_bf16 v[56:59], v[144:147], v[92:95], v[140:143]
	v_mfma_f32_16x16x32_bf16 v[60:63], v[152:155], v[92:95], v[148:151]
	s_setprio 0
	s_setprio 1
	v_mfma_f32_16x16x32_bf16 v[28:31], v[136:139], v[64:67], v[28:31]
	v_mfma_f32_16x16x32_bf16 v[24:27], v[222:225], v[64:67], v[24:27]
	v_mfma_f32_16x16x32_bf16 v[20:23], v[136:139], v[72:75], v[20:23]
	v_mfma_f32_16x16x32_bf16 v[64:67], v[222:225], v[72:75], v[16:19]
	v_mfma_f32_16x16x32_bf16 v[12:15], v[136:139], v[80:83], v[12:15]
	v_mfma_f32_16x16x32_bf16 v[8:11], v[222:225], v[80:83], v[8:11]
	v_mfma_f32_16x16x32_bf16 v[72:75], v[136:139], v[88:91], v[4:7]
	v_mfma_f32_16x16x32_bf16 v[80:83], v[222:225], v[88:91], v[0:3]
	v_mfma_f32_16x16x32_bf16 v[0:3], v[218:221], v[68:71], v[28:31]
	v_mfma_f32_16x16x32_bf16 v[4:7], v[226:229], v[68:71], v[24:27]
	v_mfma_f32_16x16x32_bf16 v[16:19], v[218:221], v[76:79], v[20:23]
	v_mfma_f32_16x16x32_bf16 v[20:23], v[226:229], v[76:79], v[64:67]
	v_mfma_f32_16x16x32_bf16 v[24:27], v[218:221], v[84:87], v[12:15]
	v_mfma_f32_16x16x32_bf16 v[28:31], v[226:229], v[84:87], v[8:11]
	v_mfma_f32_16x16x32_bf16 v[64:67], v[218:221], v[92:95], v[72:75]
	v_mfma_f32_16x16x32_bf16 v[68:71], v[226:229], v[92:95], v[80:83]
	s_setprio 0
	s_barrier
	ds_read_b128 v[12:15], v130
	ds_read_b128 v[8:11], v130 offset:1024
	ds_read_b128 v[76:79], v130 offset:2048
	ds_read_b128 v[72:75], v130 offset:3072
	ds_read_b128 v[140:143], v193 offset:32768
	ds_read_b128 v[148:151], v193 offset:33792
	ds_read_b128 v[218:221], v192 offset:32768
	ds_read_b128 v[222:225], v192 offset:33792
	ds_read_b128 v[226:229], v191 offset:32768
	ds_read_b128 v[230:233], v191 offset:33792
	ds_read_b128 v[234:237], v190 offset:32768
	ds_read_b128 v[238:241], v190 offset:33792
	s_waitcnt vmcnt(2)
	s_barrier
	s_waitcnt lgkmcnt(0)
	s_setprio 1
	s_waitcnt lgkmcnt(0)
	v_mfma_f32_16x16x32_bf16 v[80:83], v[12:15], v[140:143], v[124:127]
	v_mfma_f32_16x16x32_bf16 v[84:87], v[76:79], v[140:143], v[120:123]
	v_mfma_f32_16x16x32_bf16 v[88:91], v[12:15], v[218:221], v[116:119]
	v_mfma_f32_16x16x32_bf16 v[92:95], v[76:79], v[218:221], v[112:115]
	v_mfma_f32_16x16x32_bf16 v[108:111], v[12:15], v[226:229], v[108:111]
	v_mfma_f32_16x16x32_bf16 v[104:107], v[76:79], v[226:229], v[104:107]
	v_mfma_f32_16x16x32_bf16 v[100:103], v[12:15], v[234:237], v[100:103]
	v_mfma_f32_16x16x32_bf16 v[96:99], v[76:79], v[234:237], v[96:99]
	v_mfma_f32_16x16x32_bf16 v[152:155], v[8:11], v[148:151], v[80:83]
	v_mfma_f32_16x16x32_bf16 v[144:147], v[72:75], v[148:151], v[84:87]
	v_mfma_f32_16x16x32_bf16 v[136:139], v[8:11], v[222:225], v[88:91]
	v_mfma_f32_16x16x32_bf16 v[128:131], v[72:75], v[222:225], v[92:95]
	v_mfma_f32_16x16x32_bf16 v[120:123], v[8:11], v[230:233], v[108:111]
	v_mfma_f32_16x16x32_bf16 v[112:115], v[72:75], v[230:233], v[104:107]
	v_mfma_f32_16x16x32_bf16 v[104:107], v[8:11], v[238:241], v[100:103]
	v_mfma_f32_16x16x32_bf16 v[96:99], v[72:75], v[238:241], v[96:99]
	s_setprio 0
	s_barrier
	ds_read_b128 v[88:91], v132
	ds_read_b128 v[80:83], v132 offset:1024
	ds_read_b128 v[92:95], v132 offset:2048
	ds_read_b128 v[84:87], v132 offset:3072
	s_waitcnt vmcnt(0)
	s_barrier
	s_waitcnt lgkmcnt(0)
	s_setprio 1
	s_waitcnt lgkmcnt(0)
	v_mfma_f32_16x16x32_bf16 v[100:103], v[88:91], v[140:143], v[156:159]
	v_mfma_f32_16x16x32_bf16 v[108:111], v[92:95], v[140:143], v[160:163]
	v_mfma_f32_16x16x32_bf16 v[116:119], v[88:91], v[218:221], v[194:197]
	v_mfma_f32_16x16x32_bf16 v[124:127], v[92:95], v[218:221], v[198:201]
	v_mfma_f32_16x16x32_bf16 v[160:163], v[88:91], v[226:229], v[202:205]
	v_mfma_f32_16x16x32_bf16 v[194:197], v[92:95], v[226:229], v[206:209]
	v_mfma_f32_16x16x32_bf16 v[198:201], v[88:91], v[234:237], v[210:213]
	v_mfma_f32_16x16x32_bf16 v[202:205], v[92:95], v[234:237], v[214:217]
	v_mfma_f32_16x16x32_bf16 v[156:159], v[80:83], v[148:151], v[100:103]
	v_mfma_f32_16x16x32_bf16 v[148:151], v[84:87], v[148:151], v[108:111]
	v_mfma_f32_16x16x32_bf16 v[140:143], v[80:83], v[222:225], v[116:119]
	v_mfma_f32_16x16x32_bf16 v[132:135], v[84:87], v[222:225], v[124:127]
	v_mfma_f32_16x16x32_bf16 v[124:127], v[80:83], v[230:233], v[160:163]
	v_mfma_f32_16x16x32_bf16 v[116:119], v[84:87], v[230:233], v[194:197]
	v_mfma_f32_16x16x32_bf16 v[108:111], v[80:83], v[238:241], v[198:201]
	v_mfma_f32_16x16x32_bf16 v[100:103], v[84:87], v[238:241], v[202:205]
	s_setprio 0
	s_lshl_b64 s[58:59], s[56:57], 2
	s_barrier
	v_mbcnt_lo_u32_b32 v162, -1, 0
	v_mbcnt_hi_u32_b32 v162, -1, v162
	s_add_u32 s58, s87, s58
	v_add_u32_e32 v160, s64, v162
	s_addc_u32 s59, s88, s59
	v_and_b32_e32 v164, 0x100, v160
	v_and_b32_e32 v162, 15, v162
	v_lshl_add_u64 v[160:161], s[58:59], 0, v[164:165]
	v_lshlrev_b32_e32 v164, 2, v162
	v_lshl_add_u64 v[160:161], v[160:161], 0, v[164:165]
	global_load_dword v180, v[160:161], off
	global_load_dword v178, v[160:161], off offset:64
	global_load_dword v176, v[160:161], off offset:128
	global_load_dword v174, v[160:161], off offset:192
	global_load_dword v172, v[160:161], off offset:512
	global_load_dword v170, v[160:161], off offset:576
	global_load_dword v168, v[160:161], off offset:640
	global_load_dword v166, v[160:161], off offset:704
	v_mbcnt_lo_u32_b32 v194, -1, 0
	v_mbcnt_hi_u32_b32 v194, -1, v194
	s_cmp_lg_u32 s81, 0
	v_add_u32_e32 v160, s64, v194
	v_bfe_u32 v196, v160, 8, 1
	v_ashrrev_i32_e32 v199, 6, v160
	v_bfe_u32 v160, v194, 4, 2
	s_cselect_b64 s[58:59], -1, 0
	v_and_b32_e32 v197, 3, v199
	v_and_b32_e32 v195, 15, v194
	s_and_b64 vcc, exec, s[58:59]
	v_lshlrev_b32_e32 v198, 4, v160
	s_cbranch_vccz .LBB0_246
	s_lshl_b32 s14, s80, 22
	s_lshl_b32 s57, s82, 14
	s_add_i32 s57, s57, s14
	v_lshlrev_b32_e32 v160, 6, v195
	v_or3_b32 v160, s57, v160, v198
	v_lshl_add_u32 v160, v197, 20, v160
	v_lshl_or_b32 v164, v196, 12, v160
	s_waitcnt vmcnt(0)
	v_pk_mul_f32 v[160:161], v[154:155], v[180:181] op_sel_hi:[1,0]
	v_pk_mul_f32 v[200:201], v[146:147], v[180:181] op_sel_hi:[1,0]
	v_max_f32_e32 v160, 0, v160
	v_mul_f32_e32 v204, v160, v160
	v_max_f32_e32 v160, 0, v200
	v_pk_mul_f32 v[162:163], v[152:153], v[180:181] op_sel_hi:[1,0]
	v_mul_f32_e32 v200, v160, v160
	v_max_f32_e32 v160, 0, v161
	v_pk_mul_f32 v[202:203], v[144:145], v[180:181] op_sel_hi:[1,0]
	v_max_f32_e32 v162, 0, v162
	v_max_f32_e32 v163, 0, v163
	v_mul_f32_e32 v161, v160, v160
	v_max_f32_e32 v160, 0, v201
	v_mul_f32_e32 v162, v162, v162
	v_max_f32_e32 v202, 0, v202
	v_mul_f32_e32 v163, v163, v163
	v_max_f32_e32 v203, 0, v203
	v_mul_f32_e32 v201, v160, v160
	v_cvt_pk_bf16_f32 v160, v162, v163
	v_cvt_pk_bf16_f32 v161, v204, v161
	v_mul_f32_e32 v202, v202, v202
	v_mul_f32_e32 v203, v203, v203
	v_cvt_pk_bf16_f32 v162, v202, v203
	v_cvt_pk_bf16_f32 v163, v200, v201
	global_store_dwordx4 v164, v[160:163], s[0:1]
	v_pk_mul_f32 v[202:203], v[150:151], v[180:181] op_sel_hi:[1,0]
	v_lshl_add_u64 v[200:201], s[0:1], 0, v[164:165]
	v_pk_mul_f32 v[160:161], v[158:159], v[180:181] op_sel_hi:[1,0]
	v_pk_mul_f32 v[162:163], v[156:157], v[180:181] op_sel_hi:[1,0]
	v_max_f32_e32 v160, 0, v160
	v_mul_f32_e32 v206, v160, v160
	v_max_f32_e32 v160, 0, v202
	v_mul_f32_e32 v202, v160, v160
	v_max_f32_e32 v160, 0, v161
	v_pk_mul_f32 v[204:205], v[148:149], v[180:181] op_sel_hi:[1,0]
	v_max_f32_e32 v162, 0, v162
	v_max_f32_e32 v163, 0, v163
	v_mul_f32_e32 v161, v160, v160
	v_max_f32_e32 v160, 0, v203
	v_add_co_u32_e32 v200, vcc, s74, v200
	v_mul_f32_e32 v162, v162, v162
	v_max_f32_e32 v204, 0, v204
	v_mul_f32_e32 v163, v163, v163
	v_max_f32_e32 v205, 0, v205
	v_mul_f32_e32 v203, v160, v160
	v_cvt_pk_bf16_f32 v160, v162, v163
	v_cvt_pk_bf16_f32 v161, v206, v161
	v_addc_co_u32_e32 v201, vcc, 0, v201, vcc
	v_mul_f32_e32 v204, v204, v204
	v_mul_f32_e32 v205, v205, v205
	v_cvt_pk_bf16_f32 v162, v204, v205
	v_cvt_pk_bf16_f32 v163, v202, v203
	global_store_dwordx4 v[200:201], v[160:163], off
	v_pk_mul_f32 v[202:203], v[130:131], v[178:179] op_sel_hi:[1,0]
	v_pk_mul_f32 v[204:205], v[128:129], v[178:179] op_sel_hi:[1,0]
	v_pk_mul_f32 v[160:161], v[138:139], v[178:179] op_sel_hi:[1,0]
	v_pk_mul_f32 v[162:163], v[136:137], v[178:179] op_sel_hi:[1,0]
	v_max_f32_e32 v160, 0, v160
	v_mul_f32_e32 v206, v160, v160
	v_max_f32_e32 v160, 0, v202
	v_mul_f32_e32 v202, v160, v160
	v_max_f32_e32 v160, 0, v161
	v_max_f32_e32 v162, 0, v162
	v_max_f32_e32 v163, 0, v163
	v_mul_f32_e32 v161, v160, v160
	v_max_f32_e32 v160, 0, v203
	v_mul_f32_e32 v162, v162, v162
	v_max_f32_e32 v204, 0, v204
	v_mul_f32_e32 v163, v163, v163
	v_max_f32_e32 v205, 0, v205
	v_mul_f32_e32 v203, v160, v160
	v_cvt_pk_bf16_f32 v160, v162, v163
	v_cvt_pk_bf16_f32 v161, v206, v161
	v_mul_f32_e32 v204, v204, v204
	v_mul_f32_e32 v205, v205, v205
	v_cvt_pk_bf16_f32 v162, v204, v205
	v_cvt_pk_bf16_f32 v163, v202, v203
	global_store_dwordx4 v164, v[160:163], s[0:1] offset:1024
	v_pk_mul_f32 v[202:203], v[134:135], v[178:179] op_sel_hi:[1,0]
	v_pk_mul_f32 v[204:205], v[132:133], v[178:179] op_sel_hi:[1,0]
	v_pk_mul_f32 v[160:161], v[142:143], v[178:179] op_sel_hi:[1,0]
	v_pk_mul_f32 v[162:163], v[140:141], v[178:179] op_sel_hi:[1,0]
	v_max_f32_e32 v160, 0, v160
	v_mul_f32_e32 v206, v160, v160
	v_max_f32_e32 v160, 0, v202
	v_mul_f32_e32 v202, v160, v160
	v_max_f32_e32 v160, 0, v161
	v_max_f32_e32 v162, 0, v162
	v_max_f32_e32 v163, 0, v163
	v_mul_f32_e32 v161, v160, v160
	v_max_f32_e32 v160, 0, v203
	v_mul_f32_e32 v162, v162, v162
	v_max_f32_e32 v204, 0, v204
	v_mul_f32_e32 v163, v163, v163
	v_max_f32_e32 v205, 0, v205
	v_mul_f32_e32 v203, v160, v160
	v_cvt_pk_bf16_f32 v160, v162, v163
	v_cvt_pk_bf16_f32 v161, v206, v161
	v_mul_f32_e32 v204, v204, v204
	v_mul_f32_e32 v205, v205, v205
	v_cvt_pk_bf16_f32 v162, v204, v205
	v_cvt_pk_bf16_f32 v163, v202, v203
	global_store_dwordx4 v[200:201], v[160:163], off offset:1024
	v_pk_mul_f32 v[202:203], v[114:115], v[176:177] op_sel_hi:[1,0]
	v_pk_mul_f32 v[204:205], v[112:113], v[176:177] op_sel_hi:[1,0]
	v_pk_mul_f32 v[160:161], v[122:123], v[176:177] op_sel_hi:[1,0]
	v_pk_mul_f32 v[162:163], v[120:121], v[176:177] op_sel_hi:[1,0]
	v_max_f32_e32 v160, 0, v160
	v_mul_f32_e32 v206, v160, v160
	v_max_f32_e32 v160, 0, v202
	v_mul_f32_e32 v202, v160, v160
	v_max_f32_e32 v160, 0, v161
	v_max_f32_e32 v162, 0, v162
	v_max_f32_e32 v163, 0, v163
	v_mul_f32_e32 v161, v160, v160
	v_max_f32_e32 v160, 0, v203
	v_mul_f32_e32 v162, v162, v162
	v_max_f32_e32 v204, 0, v204
	v_mul_f32_e32 v163, v163, v163
	v_max_f32_e32 v205, 0, v205
	v_mul_f32_e32 v203, v160, v160
	v_cvt_pk_bf16_f32 v160, v162, v163
	v_cvt_pk_bf16_f32 v161, v206, v161
	v_mul_f32_e32 v204, v204, v204
	v_mul_f32_e32 v205, v205, v205
	v_cvt_pk_bf16_f32 v162, v204, v205
	v_cvt_pk_bf16_f32 v163, v202, v203
	global_store_dwordx4 v164, v[160:163], s[0:1] offset:2048
	v_pk_mul_f32 v[202:203], v[118:119], v[176:177] op_sel_hi:[1,0]
	v_pk_mul_f32 v[204:205], v[116:117], v[176:177] op_sel_hi:[1,0]
	v_pk_mul_f32 v[160:161], v[126:127], v[176:177] op_sel_hi:[1,0]
	v_pk_mul_f32 v[162:163], v[124:125], v[176:177] op_sel_hi:[1,0]
	v_max_f32_e32 v160, 0, v160
	v_mul_f32_e32 v206, v160, v160
	v_max_f32_e32 v160, 0, v202
	v_mul_f32_e32 v202, v160, v160
	v_max_f32_e32 v160, 0, v161
	v_max_f32_e32 v162, 0, v162
	v_max_f32_e32 v163, 0, v163
	v_mul_f32_e32 v161, v160, v160
	v_max_f32_e32 v160, 0, v203
	v_mul_f32_e32 v162, v162, v162
	v_max_f32_e32 v204, 0, v204
	v_mul_f32_e32 v163, v163, v163
	v_max_f32_e32 v205, 0, v205
	v_mul_f32_e32 v203, v160, v160
	v_cvt_pk_bf16_f32 v160, v162, v163
	v_cvt_pk_bf16_f32 v161, v206, v161
	v_mul_f32_e32 v204, v204, v204
	v_mul_f32_e32 v205, v205, v205
	v_cvt_pk_bf16_f32 v162, v204, v205
	v_cvt_pk_bf16_f32 v163, v202, v203
	global_store_dwordx4 v[200:201], v[160:163], off offset:2048
	v_pk_mul_f32 v[200:201], v[98:99], v[174:175] op_sel_hi:[1,0]
	v_pk_mul_f32 v[202:203], v[96:97], v[174:175] op_sel_hi:[1,0]
	v_pk_mul_f32 v[160:161], v[106:107], v[174:175] op_sel_hi:[1,0]
	v_pk_mul_f32 v[162:163], v[104:105], v[174:175] op_sel_hi:[1,0]
	v_max_f32_e32 v160, 0, v160
	v_mul_f32_e32 v204, v160, v160
	v_max_f32_e32 v160, 0, v200
	v_mul_f32_e32 v200, v160, v160
	v_max_f32_e32 v160, 0, v161
	v_max_f32_e32 v162, 0, v162
	v_max_f32_e32 v163, 0, v163
	v_mul_f32_e32 v161, v160, v160
	v_max_f32_e32 v160, 0, v201
	v_mul_f32_e32 v162, v162, v162
	v_max_f32_e32 v202, 0, v202
	v_mul_f32_e32 v163, v163, v163
	v_max_f32_e32 v203, 0, v203
	v_mul_f32_e32 v201, v160, v160
	v_cvt_pk_bf16_f32 v160, v162, v163
	v_cvt_pk_bf16_f32 v161, v204, v161
	v_mul_f32_e32 v202, v202, v202
	v_mul_f32_e32 v203, v203, v203
	v_cvt_pk_bf16_f32 v162, v202, v203
	v_cvt_pk_bf16_f32 v163, v200, v201
	global_store_dwordx4 v164, v[160:163], s[0:1] offset:3072
	v_pk_mul_f32 v[200:201], v[102:103], v[174:175] op_sel_hi:[1,0]
	v_pk_mul_f32 v[202:203], v[100:101], v[174:175] op_sel_hi:[1,0]
	v_pk_mul_f32 v[160:161], v[110:111], v[174:175] op_sel_hi:[1,0]
	v_pk_mul_f32 v[162:163], v[108:109], v[174:175] op_sel_hi:[1,0]
	v_max_f32_e32 v160, 0, v160
	v_mul_f32_e32 v204, v160, v160
	v_max_f32_e32 v160, 0, v200
	v_max_f32_e32 v162, 0, v162
	v_max_f32_e32 v163, 0, v163
	v_mul_f32_e32 v200, v160, v160
	v_max_f32_e32 v160, 0, v161
	v_mul_f32_e32 v162, v162, v162
	v_max_f32_e32 v202, 0, v202
	v_mul_f32_e32 v163, v163, v163
	v_max_f32_e32 v203, 0, v203
	v_mul_f32_e32 v161, v160, v160
	v_max_f32_e32 v160, 0, v201
	v_mul_f32_e32 v202, v202, v202
	v_mul_f32_e32 v203, v203, v203
	v_mul_f32_e32 v201, v160, v160
	v_cvt_pk_bf16_f32 v160, v162, v163
	v_cvt_pk_bf16_f32 v161, v204, v161
	v_cvt_pk_bf16_f32 v162, v202, v203
	v_cvt_pk_bf16_f32 v163, v200, v201
	v_add_u32_e32 v164, 0x80c00, v164
	s_cbranch_execnz .LBB0_238

.LBB0_274:
	ds_read_b128 v[162:165], v161
	ds_read_b128 v[166:169], v161 offset:1024
	ds_read_b128 v[170:173], v161 offset:2048
	ds_read_b128 v[174:177], v161 offset:3072
	ds_read_b128 v[178:181], v152
	ds_read_b128 v[182:185], v152 offset:1024
	ds_read_b128 v[186:189], v151
	ds_read_b128 v[190:193], v151 offset:1024
	ds_read_b128 v[194:197], v150
	ds_read_b128 v[198:201], v150 offset:1024
	ds_read_b128 v[202:205], v149
	ds_read_b128 v[206:209], v149 offset:1024
	s_waitcnt lgkmcnt(8)
	s_waitcnt vmcnt(10)
	s_barrier
	s_waitcnt lgkmcnt(0)
	s_setprio 1
	s_waitcnt lgkmcnt(0)
	v_mfma_f32_16x16x32_bf16 v[124:127], v[162:165], v[178:181], v[124:127]
	v_mfma_f32_16x16x32_bf16 v[120:123], v[170:173], v[178:181], v[120:123]
	v_mfma_f32_16x16x32_bf16 v[116:119], v[162:165], v[186:189], v[116:119]
	v_mfma_f32_16x16x32_bf16 v[112:115], v[170:173], v[186:189], v[112:115]
	v_mfma_f32_16x16x32_bf16 v[108:111], v[162:165], v[194:197], v[108:111]
	v_mfma_f32_16x16x32_bf16 v[104:107], v[170:173], v[194:197], v[104:107]
	v_mfma_f32_16x16x32_bf16 v[100:103], v[162:165], v[202:205], v[100:103]
	v_mfma_f32_16x16x32_bf16 v[96:99], v[170:173], v[202:205], v[96:99]
	v_mfma_f32_16x16x32_bf16 v[124:127], v[166:169], v[182:185], v[124:127]
	v_mfma_f32_16x16x32_bf16 v[120:123], v[174:177], v[182:185], v[120:123]
	v_mfma_f32_16x16x32_bf16 v[116:119], v[166:169], v[190:193], v[116:119]
	v_mfma_f32_16x16x32_bf16 v[112:115], v[174:177], v[190:193], v[112:115]
	v_mfma_f32_16x16x32_bf16 v[108:111], v[166:169], v[198:201], v[108:111]
	v_mfma_f32_16x16x32_bf16 v[104:107], v[174:177], v[198:201], v[104:107]
	v_mfma_f32_16x16x32_bf16 v[100:103], v[166:169], v[206:209], v[100:103]
	v_mfma_f32_16x16x32_bf16 v[96:99], v[174:177], v[206:209], v[96:99]
	s_setprio 0
	s_barrier
	s_mov_b32 vcc_lo, 0xfffbd000
	s_mov_b32 vcc_hi, -1
	v_readfirstlane_b32 s67, v148
	v_lshl_add_u64 v[226:227], v[130:131], 0, vcc
	s_mov_b32 m0, s67
	v_readfirstlane_b32 s67, v147
	ds_read_b128 v[210:213], v158
	ds_read_b128 v[214:217], v158 offset:1024
	ds_read_b128 v[218:221], v158 offset:2048
	ds_read_b128 v[222:225], v158 offset:3072
	global_load_lds_dwordx4 v[226:227], off
	v_lshl_add_u64 v[226:227], v[130:131], 0, s[22:23]
	s_mov_b32 m0, s67
	s_add_i32 s66, s66, 2
	global_load_lds_dwordx4 v[226:227], off
	v_readfirstlane_b32 s67, v134
	v_lshl_add_u64 v[226:227], v[132:133], 0, s[24:25]
	s_mov_b32 m0, s67
	v_readfirstlane_b32 s67, v146
	global_load_lds_dwordx4 v[226:227], off
	v_lshl_add_u64 v[226:227], v[132:133], 0, s[26:27]
	s_mov_b32 m0, s67
	s_nop 0
	global_load_lds_dwordx4 v[226:227], off
	s_waitcnt vmcnt(12)
	s_barrier
	s_waitcnt lgkmcnt(0)
	s_setprio 1
	s_waitcnt lgkmcnt(0)
	v_mfma_f32_16x16x32_bf16 v[92:95], v[210:213], v[178:181], v[92:95]
	v_mfma_f32_16x16x32_bf16 v[88:91], v[218:221], v[178:181], v[88:91]
	v_mfma_f32_16x16x32_bf16 v[84:87], v[210:213], v[186:189], v[84:87]
	v_mfma_f32_16x16x32_bf16 v[80:83], v[218:221], v[186:189], v[80:83]
	v_mfma_f32_16x16x32_bf16 v[76:79], v[210:213], v[194:197], v[76:79]
	v_mfma_f32_16x16x32_bf16 v[72:75], v[218:221], v[194:197], v[72:75]
	v_mfma_f32_16x16x32_bf16 v[68:71], v[210:213], v[202:205], v[68:71]
	v_mfma_f32_16x16x32_bf16 v[64:67], v[218:221], v[202:205], v[64:67]
	v_mfma_f32_16x16x32_bf16 v[92:95], v[214:217], v[182:185], v[92:95]
	v_mfma_f32_16x16x32_bf16 v[88:91], v[222:225], v[182:185], v[88:91]
	v_mfma_f32_16x16x32_bf16 v[84:87], v[214:217], v[190:193], v[84:87]
	v_mfma_f32_16x16x32_bf16 v[80:83], v[222:225], v[190:193], v[80:83]
	v_mfma_f32_16x16x32_bf16 v[76:79], v[214:217], v[198:201], v[76:79]
	v_mfma_f32_16x16x32_bf16 v[72:75], v[222:225], v[198:201], v[72:75]
	v_mfma_f32_16x16x32_bf16 v[68:71], v[214:217], v[206:209], v[68:71]
	v_mfma_f32_16x16x32_bf16 v[64:67], v[222:225], v[206:209], v[64:67]
	s_setprio 0
	s_barrier
	ds_read_b128 v[178:181], v152 offset:16384
	ds_read_b128 v[182:185], v152 offset:17408
	ds_read_b128 v[186:189], v151 offset:16384
	ds_read_b128 v[190:193], v151 offset:17408
	ds_read_b128 v[194:197], v150 offset:16384
	ds_read_b128 v[198:201], v150 offset:17408
	ds_read_b128 v[202:205], v149 offset:16384
	ds_read_b128 v[206:209], v149 offset:17408
	v_readfirstlane_b32 s67, v145
	v_lshl_add_u64 v[226:227], v[130:131], 0, s[28:29]
	s_mov_b32 m0, s67
	v_readfirstlane_b32 s67, v144
	global_load_lds_dwordx4 v[226:227], off
	v_lshl_add_u64 v[226:227], v[130:131], 0, s[30:31]
	s_mov_b32 m0, s67
	s_nop 0
	global_load_lds_dwordx4 v[226:227], off
	s_barrier
	s_waitcnt lgkmcnt(0)
	s_setprio 1
	s_waitcnt lgkmcnt(0)
	v_mfma_f32_16x16x32_bf16 v[60:63], v[162:165], v[178:181], v[60:63]
	v_mfma_f32_16x16x32_bf16 v[56:59], v[170:173], v[178:181], v[56:59]
	v_mfma_f32_16x16x32_bf16 v[52:55], v[162:165], v[186:189], v[52:55]
	v_mfma_f32_16x16x32_bf16 v[48:51], v[170:173], v[186:189], v[48:51]
	v_mfma_f32_16x16x32_bf16 v[44:47], v[162:165], v[194:197], v[44:47]
	v_mfma_f32_16x16x32_bf16 v[40:43], v[170:173], v[194:197], v[40:43]
	v_mfma_f32_16x16x32_bf16 v[36:39], v[162:165], v[202:205], v[36:39]
	v_mfma_f32_16x16x32_bf16 v[32:35], v[170:173], v[202:205], v[32:35]
	v_mfma_f32_16x16x32_bf16 v[60:63], v[166:169], v[182:185], v[60:63]
	v_mfma_f32_16x16x32_bf16 v[56:59], v[174:177], v[182:185], v[56:59]
	v_mfma_f32_16x16x32_bf16 v[52:55], v[166:169], v[190:193], v[52:55]
	v_mfma_f32_16x16x32_bf16 v[48:51], v[174:177], v[190:193], v[48:51]
	v_mfma_f32_16x16x32_bf16 v[44:47], v[166:169], v[198:201], v[44:47]
	v_mfma_f32_16x16x32_bf16 v[40:43], v[174:177], v[198:201], v[40:43]
	v_mfma_f32_16x16x32_bf16 v[36:39], v[166:169], v[206:209], v[36:39]
	v_mfma_f32_16x16x32_bf16 v[32:35], v[174:177], v[206:209], v[32:35]
	s_setprio 0
	s_barrier
	v_readfirstlane_b32 s67, v143
	v_lshl_add_u64 v[164:165], v[132:133], 0, s[34:35]
	s_mov_b32 m0, s67
	v_readfirstlane_b32 s67, v142
	global_load_lds_dwordx4 v[164:165], off
	v_lshl_add_u64 v[164:165], v[132:133], 0, s[44:45]
	s_mov_b32 m0, s67
	s_nop 0
	global_load_lds_dwordx4 v[164:165], off
	s_waitcnt vmcnt(12)
	s_barrier
	s_setprio 1
	v_mfma_f32_16x16x32_bf16 v[28:31], v[210:213], v[178:181], v[28:31]
	v_mfma_f32_16x16x32_bf16 v[24:27], v[218:221], v[178:181], v[24:27]
	v_mfma_f32_16x16x32_bf16 v[20:23], v[210:213], v[186:189], v[20:23]
	v_mfma_f32_16x16x32_bf16 v[16:19], v[218:221], v[186:189], v[16:19]
	v_mfma_f32_16x16x32_bf16 v[12:15], v[210:213], v[194:197], v[12:15]
	v_mfma_f32_16x16x32_bf16 v[8:11], v[218:221], v[194:197], v[8:11]
	v_mfma_f32_16x16x32_bf16 v[4:7], v[210:213], v[202:205], v[4:7]
	v_mfma_f32_16x16x32_bf16 v[0:3], v[218:221], v[202:205], v[0:3]
	v_mfma_f32_16x16x32_bf16 v[28:31], v[214:217], v[182:185], v[28:31]
	v_mfma_f32_16x16x32_bf16 v[24:27], v[222:225], v[182:185], v[24:27]
	v_mfma_f32_16x16x32_bf16 v[20:23], v[214:217], v[190:193], v[20:23]
	v_mfma_f32_16x16x32_bf16 v[16:19], v[222:225], v[190:193], v[16:19]
	v_mfma_f32_16x16x32_bf16 v[12:15], v[214:217], v[198:201], v[12:15]
	v_mfma_f32_16x16x32_bf16 v[8:11], v[222:225], v[198:201], v[8:11]
	v_mfma_f32_16x16x32_bf16 v[4:7], v[214:217], v[206:209], v[4:7]
	v_mfma_f32_16x16x32_bf16 v[0:3], v[222:225], v[206:209], v[0:3]
	s_setprio 0
	s_barrier
	ds_read_b128 v[162:165], v154
	ds_read_b128 v[166:169], v154 offset:1024
	ds_read_b128 v[170:173], v154 offset:2048
	ds_read_b128 v[174:177], v154 offset:3072
	ds_read_b128 v[178:181], v152 offset:32768
	ds_read_b128 v[182:185], v152 offset:33792
	ds_read_b128 v[186:189], v151 offset:32768
	ds_read_b128 v[190:193], v151 offset:33792
	ds_read_b128 v[194:197], v150 offset:32768
	ds_read_b128 v[198:201], v150 offset:33792
	ds_read_b128 v[202:205], v149 offset:32768
	ds_read_b128 v[206:209], v149 offset:33792
	s_waitcnt lgkmcnt(8)
	s_waitcnt vmcnt(10)
	s_barrier
	s_waitcnt lgkmcnt(0)
	s_setprio 1
	s_waitcnt lgkmcnt(0)
	v_mfma_f32_16x16x32_bf16 v[124:127], v[162:165], v[178:181], v[124:127]
	v_mfma_f32_16x16x32_bf16 v[120:123], v[170:173], v[178:181], v[120:123]
	v_mfma_f32_16x16x32_bf16 v[116:119], v[162:165], v[186:189], v[116:119]
	v_mfma_f32_16x16x32_bf16 v[112:115], v[170:173], v[186:189], v[112:115]
	v_mfma_f32_16x16x32_bf16 v[108:111], v[162:165], v[194:197], v[108:111]
	v_mfma_f32_16x16x32_bf16 v[104:107], v[170:173], v[194:197], v[104:107]
	v_mfma_f32_16x16x32_bf16 v[100:103], v[162:165], v[202:205], v[100:103]
	v_mfma_f32_16x16x32_bf16 v[96:99], v[170:173], v[202:205], v[96:99]
	v_mfma_f32_16x16x32_bf16 v[124:127], v[166:169], v[182:185], v[124:127]
	v_mfma_f32_16x16x32_bf16 v[120:123], v[174:177], v[182:185], v[120:123]
	v_mfma_f32_16x16x32_bf16 v[116:119], v[166:169], v[190:193], v[116:119]
	v_mfma_f32_16x16x32_bf16 v[112:115], v[174:177], v[190:193], v[112:115]
	v_mfma_f32_16x16x32_bf16 v[108:111], v[166:169], v[198:201], v[108:111]
	v_mfma_f32_16x16x32_bf16 v[104:107], v[174:177], v[198:201], v[104:107]
	v_mfma_f32_16x16x32_bf16 v[100:103], v[166:169], v[206:209], v[100:103]
	v_mfma_f32_16x16x32_bf16 v[96:99], v[174:177], v[206:209], v[96:99]
	s_setprio 0
	s_barrier
	v_readfirstlane_b32 s67, v141
	v_lshl_add_u64 v[226:227], v[130:131], 0, s[46:47]
	s_mov_b32 m0, s67
	v_readfirstlane_b32 s67, v140
	ds_read_b128 v[210:213], v153
	ds_read_b128 v[214:217], v153 offset:1024
	ds_read_b128 v[218:221], v153 offset:2048
	ds_read_b128 v[222:225], v153 offset:3072
	global_load_lds_dwordx4 v[226:227], off
	v_lshl_add_u64 v[226:227], v[130:131], 0, s[56:57]
	s_mov_b32 m0, s67
	s_nop 0
	global_load_lds_dwordx4 v[226:227], off
	v_readfirstlane_b32 s67, v139
	v_lshl_add_u64 v[226:227], v[132:133], 0, s[58:59]
	s_mov_b32 m0, s67
	v_readfirstlane_b32 s67, v138
	global_load_lds_dwordx4 v[226:227], off
	s_mov_b32 m0, s67
	s_nop 0
	global_load_lds_dwordx4 v[132:133], off
	s_waitcnt vmcnt(12)
	s_barrier
	s_waitcnt lgkmcnt(0)
	s_setprio 1
	s_waitcnt lgkmcnt(0)
	v_mfma_f32_16x16x32_bf16 v[92:95], v[210:213], v[178:181], v[92:95]
	v_mfma_f32_16x16x32_bf16 v[88:91], v[218:221], v[178:181], v[88:91]
	v_mfma_f32_16x16x32_bf16 v[84:87], v[210:213], v[186:189], v[84:87]
	v_mfma_f32_16x16x32_bf16 v[80:83], v[218:221], v[186:189], v[80:83]
	v_mfma_f32_16x16x32_bf16 v[76:79], v[210:213], v[194:197], v[76:79]
	v_mfma_f32_16x16x32_bf16 v[72:75], v[218:221], v[194:197], v[72:75]
	v_mfma_f32_16x16x32_bf16 v[68:71], v[210:213], v[202:205], v[68:71]
	v_mfma_f32_16x16x32_bf16 v[64:67], v[218:221], v[202:205], v[64:67]
	v_mfma_f32_16x16x32_bf16 v[92:95], v[214:217], v[182:185], v[92:95]
	v_mfma_f32_16x16x32_bf16 v[88:91], v[222:225], v[182:185], v[88:91]
	v_mfma_f32_16x16x32_bf16 v[84:87], v[214:217], v[190:193], v[84:87]
	v_mfma_f32_16x16x32_bf16 v[80:83], v[222:225], v[190:193], v[80:83]
	v_mfma_f32_16x16x32_bf16 v[76:79], v[214:217], v[198:201], v[76:79]
	v_mfma_f32_16x16x32_bf16 v[72:75], v[222:225], v[198:201], v[72:75]
	v_mfma_f32_16x16x32_bf16 v[68:71], v[214:217], v[206:209], v[68:71]
	v_mfma_f32_16x16x32_bf16 v[64:67], v[222:225], v[206:209], v[64:67]
	s_setprio 0
	s_barrier
	ds_read_b128 v[178:181], v152 offset:49152
	ds_read_b128 v[182:185], v152 offset:50176
	ds_read_b128 v[186:189], v151 offset:49152
	ds_read_b128 v[190:193], v151 offset:50176
	ds_read_b128 v[194:197], v150 offset:49152
	ds_read_b128 v[198:201], v150 offset:50176
	ds_read_b128 v[202:205], v149 offset:49152
	ds_read_b128 v[206:209], v149 offset:50176
	v_readfirstlane_b32 s67, v137
	v_lshl_add_u64 v[226:227], v[130:131], 0, s[58:59]
	s_mov_b32 m0, s67
	v_readfirstlane_b32 s67, v136
	global_load_lds_dwordx4 v[226:227], off
	s_mov_b32 m0, s67
	s_nop 0
	global_load_lds_dwordx4 v[130:131], off
	s_barrier
	s_waitcnt lgkmcnt(0)
	s_setprio 1
	s_waitcnt lgkmcnt(0)
	v_mfma_f32_16x16x32_bf16 v[60:63], v[162:165], v[178:181], v[60:63]
	v_mfma_f32_16x16x32_bf16 v[56:59], v[170:173], v[178:181], v[56:59]
	v_mfma_f32_16x16x32_bf16 v[52:55], v[162:165], v[186:189], v[52:55]
	v_mfma_f32_16x16x32_bf16 v[48:51], v[170:173], v[186:189], v[48:51]
	v_mfma_f32_16x16x32_bf16 v[44:47], v[162:165], v[194:197], v[44:47]
	v_mfma_f32_16x16x32_bf16 v[40:43], v[170:173], v[194:197], v[40:43]
	v_mfma_f32_16x16x32_bf16 v[36:39], v[162:165], v[202:205], v[36:39]
	v_mfma_f32_16x16x32_bf16 v[32:35], v[170:173], v[202:205], v[32:35]
	v_mfma_f32_16x16x32_bf16 v[60:63], v[166:169], v[182:185], v[60:63]
	v_mfma_f32_16x16x32_bf16 v[56:59], v[174:177], v[182:185], v[56:59]
	v_mfma_f32_16x16x32_bf16 v[52:55], v[166:169], v[190:193], v[52:55]
	v_mfma_f32_16x16x32_bf16 v[48:51], v[174:177], v[190:193], v[48:51]
	v_mfma_f32_16x16x32_bf16 v[44:47], v[166:169], v[198:201], v[44:47]
	v_mfma_f32_16x16x32_bf16 v[40:43], v[174:177], v[198:201], v[40:43]
	v_mfma_f32_16x16x32_bf16 v[36:39], v[166:169], v[206:209], v[36:39]
	v_mfma_f32_16x16x32_bf16 v[32:35], v[174:177], v[206:209], v[32:35]
	s_setprio 0
	s_barrier
	v_lshl_add_u64 v[132:133], v[132:133], 0, s[62:63]
	s_mov_b32 vcc_lo, 0xffe01000
	s_mov_b32 vcc_hi, -1
	v_lshl_add_u64 v[164:165], v[132:133], 0, vcc
	v_readfirstlane_b32 s67, v160
	s_mov_b32 vcc_lo, 0xffe02000
	s_mov_b32 m0, s67
	s_mov_b32 vcc_hi, -1
	v_readfirstlane_b32 s67, v159
	global_load_lds_dwordx4 v[164:165], off
	v_lshl_add_u64 v[164:165], v[132:133], 0, vcc
	s_mov_b32 m0, s67
	s_nop 0
	global_load_lds_dwordx4 v[164:165], off
	s_waitcnt vmcnt(12)
	s_barrier
	s_setprio 1
	v_mfma_f32_16x16x32_bf16 v[28:31], v[210:213], v[178:181], v[28:31]
	v_mfma_f32_16x16x32_bf16 v[24:27], v[218:221], v[178:181], v[24:27]
	v_mfma_f32_16x16x32_bf16 v[20:23], v[210:213], v[186:189], v[20:23]
	v_mfma_f32_16x16x32_bf16 v[16:19], v[218:221], v[186:189], v[16:19]
	v_mfma_f32_16x16x32_bf16 v[12:15], v[210:213], v[194:197], v[12:15]
	v_mfma_f32_16x16x32_bf16 v[8:11], v[218:221], v[194:197], v[8:11]
	v_mfma_f32_16x16x32_bf16 v[4:7], v[210:213], v[202:205], v[4:7]
	v_mfma_f32_16x16x32_bf16 v[0:3], v[218:221], v[202:205], v[0:3]
	v_mfma_f32_16x16x32_bf16 v[28:31], v[214:217], v[182:185], v[28:31]
	v_mfma_f32_16x16x32_bf16 v[24:27], v[222:225], v[182:185], v[24:27]
	v_mfma_f32_16x16x32_bf16 v[20:23], v[214:217], v[190:193], v[20:23]
	v_mfma_f32_16x16x32_bf16 v[16:19], v[222:225], v[190:193], v[16:19]
	v_mfma_f32_16x16x32_bf16 v[12:15], v[214:217], v[198:201], v[12:15]
	v_mfma_f32_16x16x32_bf16 v[8:11], v[222:225], v[198:201], v[8:11]
	v_mfma_f32_16x16x32_bf16 v[4:7], v[214:217], v[206:209], v[4:7]
	v_mfma_f32_16x16x32_bf16 v[0:3], v[222:225], v[206:209], v[0:3]
	s_setprio 0
	v_lshl_add_u64 v[130:131], v[130:131], 0, s[60:61]
	s_cmp_lt_u32 s66, s65
	s_barrier
	s_cbranch_scc1 .LBB0_274
	s_lshl_b32 s65, s86, 5
	s_lshl_b32 s66, s86, 8
	s_and_b32 s65, s65, 0x1800
	s_and_b32 s66, s66, 0x700
	s_or_b32 s97, s66, s65
	s_lshl_b32 s65, s97, 6
	s_add_u32 s65, s68, s65
	s_addc_u32 s86, s69, 0
	s_add_i32 s20, s20, -1
	s_lshl_b64 s[66:67], s[20:21], 20
	v_add_u32_e32 v128, v156, v157
	s_add_u32 s66, s65, s66
	v_or_b32_e32 v128, v128, v155
	s_addc_u32 s67, s86, s67
	v_lshl_add_u64 v[156:157], s[66:67], 0, v[128:129]
	v_readfirstlane_b32 s20, v160
	v_lshl_add_u64 v[206:207], v[156:157], 0, s[4:5]
	s_mov_b32 m0, s20
	v_readfirstlane_b32 s20, v159
	ds_read_b128 v[130:133], v161
	ds_read_b128 v[162:165], v161 offset:1024
	ds_read_b128 v[166:169], v161 offset:2048
	ds_read_b128 v[170:173], v161 offset:3072
	ds_read_b128 v[174:177], v152
	ds_read_b128 v[178:181], v152 offset:1024
	ds_read_b128 v[182:185], v151
	ds_read_b128 v[186:189], v151 offset:1024
	ds_read_b128 v[190:193], v150
	ds_read_b128 v[194:197], v150 offset:1024
	ds_read_b128 v[198:201], v149
	ds_read_b128 v[202:205], v149 offset:1024
	global_load_lds_dwordx4 v[206:207], off
	v_lshl_add_u64 v[156:157], v[156:157], 0, s[6:7]
	s_mov_b32 m0, s20
	s_nop 0
	global_load_lds_dwordx4 v[156:157], off
	s_waitcnt vmcnt(10)
	s_barrier
	s_waitcnt lgkmcnt(0)
	s_setprio 1
	s_waitcnt lgkmcnt(0)
	v_mfma_f32_16x16x32_bf16 v[124:127], v[130:133], v[174:177], v[124:127]
	v_mfma_f32_16x16x32_bf16 v[120:123], v[166:169], v[174:177], v[120:123]
	v_mfma_f32_16x16x32_bf16 v[116:119], v[130:133], v[182:185], v[116:119]
	v_mfma_f32_16x16x32_bf16 v[112:115], v[166:169], v[182:185], v[112:115]
	v_mfma_f32_16x16x32_bf16 v[108:111], v[130:133], v[190:193], v[108:111]
	v_mfma_f32_16x16x32_bf16 v[104:107], v[166:169], v[190:193], v[104:107]
	v_mfma_f32_16x16x32_bf16 v[100:103], v[130:133], v[198:201], v[100:103]
	v_mfma_f32_16x16x32_bf16 v[96:99], v[166:169], v[198:201], v[96:99]
	v_mfma_f32_16x16x32_bf16 v[124:127], v[162:165], v[178:181], v[124:127]
	v_mfma_f32_16x16x32_bf16 v[120:123], v[170:173], v[178:181], v[120:123]
	v_mfma_f32_16x16x32_bf16 v[116:119], v[162:165], v[186:189], v[116:119]
	v_mfma_f32_16x16x32_bf16 v[112:115], v[170:173], v[186:189], v[112:115]
	v_mfma_f32_16x16x32_bf16 v[108:111], v[162:165], v[194:197], v[108:111]
	v_mfma_f32_16x16x32_bf16 v[104:107], v[170:173], v[194:197], v[104:107]
	v_mfma_f32_16x16x32_bf16 v[100:103], v[162:165], v[202:205], v[100:103]
	v_mfma_f32_16x16x32_bf16 v[96:99], v[170:173], v[202:205], v[96:99]
	s_setprio 0
	s_barrier
	ds_read_b128 v[206:209], v158
	ds_read_b128 v[210:213], v158 offset:1024
	ds_read_b128 v[214:217], v158 offset:2048
	ds_read_b128 v[156:159], v158 offset:3072
	s_barrier
	s_waitcnt lgkmcnt(0)
	s_setprio 1
	s_waitcnt lgkmcnt(0)
	v_mfma_f32_16x16x32_bf16 v[92:95], v[206:209], v[174:177], v[92:95]
	v_mfma_f32_16x16x32_bf16 v[88:91], v[214:217], v[174:177], v[88:91]
	v_mfma_f32_16x16x32_bf16 v[84:87], v[206:209], v[182:185], v[84:87]
	v_mfma_f32_16x16x32_bf16 v[80:83], v[214:217], v[182:185], v[80:83]
	v_mfma_f32_16x16x32_bf16 v[76:79], v[206:209], v[190:193], v[76:79]
	v_mfma_f32_16x16x32_bf16 v[72:75], v[214:217], v[190:193], v[72:75]
	v_mfma_f32_16x16x32_bf16 v[68:71], v[206:209], v[198:201], v[68:71]
	v_mfma_f32_16x16x32_bf16 v[64:67], v[214:217], v[198:201], v[64:67]
	v_mfma_f32_16x16x32_bf16 v[174:177], v[210:213], v[178:181], v[92:95]
	v_mfma_f32_16x16x32_bf16 v[178:181], v[156:159], v[178:181], v[88:91]
	v_mfma_f32_16x16x32_bf16 v[182:185], v[210:213], v[186:189], v[84:87]
	v_mfma_f32_16x16x32_bf16 v[186:189], v[156:159], v[186:189], v[80:83]
	v_mfma_f32_16x16x32_bf16 v[190:193], v[210:213], v[194:197], v[76:79]
	v_mfma_f32_16x16x32_bf16 v[194:197], v[156:159], v[194:197], v[72:75]
	v_mfma_f32_16x16x32_bf16 v[198:201], v[210:213], v[202:205], v[68:71]
	v_mfma_f32_16x16x32_bf16 v[202:205], v[156:159], v[202:205], v[64:67]
	s_setprio 0
	s_barrier
	s_nop 0
	ds_read_b128 v[64:67], v152 offset:16384
	ds_read_b128 v[68:71], v152 offset:17408
	ds_read_b128 v[72:75], v151 offset:16384
	ds_read_b128 v[76:79], v151 offset:17408
	ds_read_b128 v[80:83], v150 offset:16384
	ds_read_b128 v[84:87], v150 offset:17408
	ds_read_b128 v[88:91], v149 offset:16384
	ds_read_b128 v[92:95], v149 offset:17408
	s_waitcnt vmcnt(4)
	s_barrier
	s_waitcnt lgkmcnt(0)
	s_setprio 1
	s_waitcnt lgkmcnt(0)
	v_mfma_f32_16x16x32_bf16 v[60:63], v[130:133], v[64:67], v[60:63]
	v_mfma_f32_16x16x32_bf16 v[56:59], v[166:169], v[64:67], v[56:59]
	v_mfma_f32_16x16x32_bf16 v[52:55], v[130:133], v[72:75], v[52:55]
	v_mfma_f32_16x16x32_bf16 v[48:51], v[166:169], v[72:75], v[48:51]
	v_mfma_f32_16x16x32_bf16 v[218:221], v[130:133], v[80:83], v[44:47]
	v_mfma_f32_16x16x32_bf16 v[222:225], v[166:169], v[80:83], v[40:43]
	v_mfma_f32_16x16x32_bf16 v[130:133], v[130:133], v[88:91], v[36:39]
	v_mfma_f32_16x16x32_bf16 v[166:169], v[166:169], v[88:91], v[32:35]
	v_mfma_f32_16x16x32_bf16 v[32:35], v[162:165], v[68:71], v[60:63]
	v_mfma_f32_16x16x32_bf16 v[36:39], v[170:173], v[68:71], v[56:59]
	v_mfma_f32_16x16x32_bf16 v[40:43], v[162:165], v[76:79], v[52:55]
	v_mfma_f32_16x16x32_bf16 v[44:47], v[170:173], v[76:79], v[48:51]
	v_mfma_f32_16x16x32_bf16 v[48:51], v[162:165], v[84:87], v[218:221]
	v_mfma_f32_16x16x32_bf16 v[52:55], v[170:173], v[84:87], v[222:225]
	v_mfma_f32_16x16x32_bf16 v[56:59], v[162:165], v[92:95], v[130:133]
	v_mfma_f32_16x16x32_bf16 v[60:63], v[170:173], v[92:95], v[166:169]
	s_setprio 0
	s_setprio 1
	v_mfma_f32_16x16x32_bf16 v[28:31], v[206:209], v[64:67], v[28:31]
	v_mfma_f32_16x16x32_bf16 v[24:27], v[214:217], v[64:67], v[24:27]
	v_mfma_f32_16x16x32_bf16 v[20:23], v[206:209], v[72:75], v[20:23]
	v_mfma_f32_16x16x32_bf16 v[64:67], v[214:217], v[72:75], v[16:19]
	v_mfma_f32_16x16x32_bf16 v[72:75], v[206:209], v[80:83], v[12:15]
	v_mfma_f32_16x16x32_bf16 v[8:11], v[214:217], v[80:83], v[8:11]
	v_mfma_f32_16x16x32_bf16 v[80:83], v[206:209], v[88:91], v[4:7]
	v_mfma_f32_16x16x32_bf16 v[0:3], v[214:217], v[88:91], v[0:3]
	v_mfma_f32_16x16x32_bf16 v[4:7], v[210:213], v[68:71], v[28:31]
	v_mfma_f32_16x16x32_bf16 v[12:15], v[156:159], v[68:71], v[24:27]
	v_mfma_f32_16x16x32_bf16 v[16:19], v[210:213], v[76:79], v[20:23]
	v_mfma_f32_16x16x32_bf16 v[20:23], v[156:159], v[76:79], v[64:67]
	v_mfma_f32_16x16x32_bf16 v[24:27], v[210:213], v[84:87], v[72:75]
	v_mfma_f32_16x16x32_bf16 v[28:31], v[156:159], v[84:87], v[8:11]
	v_mfma_f32_16x16x32_bf16 v[64:67], v[210:213], v[92:95], v[80:83]
	v_mfma_f32_16x16x32_bf16 v[68:71], v[156:159], v[92:95], v[0:3]
	s_setprio 0
	s_barrier
	ds_read_b128 v[8:11], v154
	ds_read_b128 v[0:3], v154 offset:1024
	ds_read_b128 v[76:79], v154 offset:2048
	ds_read_b128 v[72:75], v154 offset:3072
	ds_read_b128 v[130:133], v152 offset:32768
	ds_read_b128 v[154:157], v152 offset:33792
	ds_read_b128 v[158:161], v151 offset:32768
	ds_read_b128 v[162:165], v151 offset:33792
	ds_read_b128 v[166:169], v150 offset:32768
	ds_read_b128 v[170:173], v150 offset:33792
	ds_read_b128 v[206:209], v149 offset:32768
	ds_read_b128 v[210:213], v149 offset:33792
	s_waitcnt vmcnt(2)
	s_barrier
	s_waitcnt lgkmcnt(0)
	s_setprio 1
	s_waitcnt lgkmcnt(0)
	v_mfma_f32_16x16x32_bf16 v[80:83], v[8:11], v[130:133], v[124:127]
	v_mfma_f32_16x16x32_bf16 v[84:87], v[76:79], v[130:133], v[120:123]
	v_mfma_f32_16x16x32_bf16 v[88:91], v[8:11], v[158:161], v[116:119]
	v_mfma_f32_16x16x32_bf16 v[92:95], v[76:79], v[158:161], v[112:115]
	v_mfma_f32_16x16x32_bf16 v[108:111], v[8:11], v[166:169], v[108:111]
	v_mfma_f32_16x16x32_bf16 v[104:107], v[76:79], v[166:169], v[104:107]
	v_mfma_f32_16x16x32_bf16 v[100:103], v[8:11], v[206:209], v[100:103]
	v_mfma_f32_16x16x32_bf16 v[96:99], v[76:79], v[206:209], v[96:99]
	v_mfma_f32_16x16x32_bf16 v[112:115], v[0:3], v[154:157], v[80:83]
	v_mfma_f32_16x16x32_bf16 v[116:119], v[72:75], v[154:157], v[84:87]
	v_mfma_f32_16x16x32_bf16 v[120:123], v[0:3], v[162:165], v[88:91]
	v_mfma_f32_16x16x32_bf16 v[124:127], v[72:75], v[162:165], v[92:95]
	v_mfma_f32_16x16x32_bf16 v[108:111], v[0:3], v[170:173], v[108:111]
	v_mfma_f32_16x16x32_bf16 v[104:107], v[72:75], v[170:173], v[104:107]
	v_mfma_f32_16x16x32_bf16 v[100:103], v[0:3], v[210:213], v[100:103]
	v_mfma_f32_16x16x32_bf16 v[96:99], v[72:75], v[210:213], v[96:99]
	s_setprio 0
	s_barrier
	ds_read_b128 v[88:91], v153
	ds_read_b128 v[80:83], v153 offset:1024
	ds_read_b128 v[92:95], v153 offset:2048
	ds_read_b128 v[84:87], v153 offset:3072
	s_waitcnt vmcnt(0)
	s_barrier
	s_waitcnt lgkmcnt(0)
	s_setprio 1
	s_waitcnt lgkmcnt(0)
	v_mfma_f32_16x16x32_bf16 v[174:177], v[88:91], v[130:133], v[174:177]
	v_mfma_f32_16x16x32_bf16 v[130:133], v[92:95], v[130:133], v[178:181]
	v_mfma_f32_16x16x32_bf16 v[178:181], v[88:91], v[158:161], v[182:185]
	v_mfma_f32_16x16x32_bf16 v[158:161], v[92:95], v[158:161], v[186:189]
	v_mfma_f32_16x16x32_bf16 v[182:185], v[88:91], v[166:169], v[190:193]
	v_mfma_f32_16x16x32_bf16 v[166:169], v[92:95], v[166:169], v[194:197]
	v_mfma_f32_16x16x32_bf16 v[186:189], v[88:91], v[206:209], v[198:201]
	v_mfma_f32_16x16x32_bf16 v[190:193], v[92:95], v[206:209], v[202:205]
	v_mfma_f32_16x16x32_bf16 v[174:177], v[80:83], v[154:157], v[174:177]
	v_mfma_f32_16x16x32_bf16 v[130:133], v[84:87], v[154:157], v[130:133]
	v_mfma_f32_16x16x32_bf16 v[154:157], v[80:83], v[162:165], v[178:181]
	v_mfma_f32_16x16x32_bf16 v[158:161], v[84:87], v[162:165], v[158:161]
	v_mfma_f32_16x16x32_bf16 v[162:165], v[80:83], v[170:173], v[182:185]
	v_mfma_f32_16x16x32_bf16 v[166:169], v[84:87], v[170:173], v[166:169]
	v_mfma_f32_16x16x32_bf16 v[170:173], v[80:83], v[210:213], v[186:189]
	v_mfma_f32_16x16x32_bf16 v[178:181], v[84:87], v[210:213], v[190:193]
	s_setprio 0
	s_barrier
	v_mbcnt_lo_u32_b32 v128, -1, 0
	v_mbcnt_hi_u32_b32 v128, -1, v128
	v_cvt_pk_bf16_f32 v112, v112, v113
	v_cvt_pk_bf16_f32 v113, v114, v115
	v_cvt_pk_bf16_f32 v114, v116, v117
	v_cvt_pk_bf16_f32 v115, v118, v119
	s_lshl_b32 s89, s64, 9
	v_add_u32_e32 v153, s72, v128
	v_ashrrev_i32_e32 v182, 6, v153
	v_and_b32_e32 v183, 15, v128
	v_and_b32_e32 v184, 48, v128
	v_mul_lo_u32 v185, v182, s77
	v_bfe_u32 v186, v128, 3, 3
	v_lshlrev_b32_e32 v128, 4, v128
	v_add_u32_e32 v185, 0x20000, v185
	v_lshrrev_b32_e32 v153, 2, v153
	v_and_b32_e32 v128, 0x70, v128
	v_mul_u32_u24_e32 v183, 0x90, v183
	v_and_b32_e32 v153, 64, v153
	v_add3_u32 v183, v185, v183, v184
	v_or_b32_e32 v184, v185, v128
	v_or3_b32 v153, s97, v153, v186
	v_mad_u32_u24 v184, v186, s79, v184
	ds_write_b128 v183, v[112:115]
	v_cvt_pk_bf16_f32 v112, v174, v175
	v_cvt_pk_bf16_f32 v113, v176, v177
	v_cvt_pk_bf16_f32 v114, v130, v131
	v_cvt_pk_bf16_f32 v115, v132, v133
	ds_write_b128 v183, v[112:115] offset:64
	v_lshlrev_b32_e32 v182, 7, v182
	ds_read_b128 v[112:115], v184
	v_lshlrev_b32_e32 v116, 12, v153
	v_and_or_b32 v116, v182, s80, v116
	v_or3_b32 v128, v116, s89, v128
	ds_read_b128 v[116:119], v184 offset:1152
	v_lshl_add_u64 v[130:131], s[0:1], 0, v[128:129]
	s_mov_b32 s20, 0x8000
	s_waitcnt lgkmcnt(0)
	global_store_dwordx4 v128, v[112:115], s[0:1]
	v_cvt_pk_bf16_f32 v108, v108, v109
	v_cvt_pk_bf16_f32 v109, v110, v111
	v_cvt_pk_bf16_f32 v110, v104, v105
	v_cvt_pk_bf16_f32 v111, v106, v107
	v_cvt_pk_bf16_f32 v104, v162, v163
	s_nop 1
	v_add_co_u32_e32 v112, vcc, s20, v130
	v_cvt_pk_bf16_f32 v114, v124, v125
	v_cvt_pk_bf16_f32 v115, v126, v127
	v_cvt_pk_bf16_f32 v105, v164, v165
	v_cvt_pk_bf16_f32 v106, v166, v167
	s_nop 1
	v_addc_co_u32_e32 v113, vcc, 0, v131, vcc
	global_store_dwordx4 v[112:113], v[116:119], off
	v_cvt_pk_bf16_f32 v112, v120, v121
	v_cvt_pk_bf16_f32 v113, v122, v123
	ds_write_b128 v183, v[112:115]
	v_cvt_pk_bf16_f32 v112, v154, v155
	v_cvt_pk_bf16_f32 v113, v156, v157
	v_cvt_pk_bf16_f32 v114, v158, v159
	v_cvt_pk_bf16_f32 v115, v160, v161
	ds_write_b128 v183, v[112:115] offset:64
	ds_read_b128 v[112:115], v184
	ds_read_b128 v[116:119], v184 offset:1152
	v_add_co_u32_e32 v120, vcc, s74, v130
	ds_write_b128 v183, v[108:111]
	v_cvt_pk_bf16_f32 v107, v168, v169
	ds_write_b128 v183, v[104:107] offset:64
	v_addc_co_u32_e32 v121, vcc, 0, v131, vcc
	ds_read_b128 v[104:107], v184
	ds_read_b128 v[108:111], v184 offset:1152
	s_waitcnt lgkmcnt(0)
	global_store_dwordx4 v[120:121], v[112:115], off
	v_cvt_pk_bf16_f32 v100, v100, v101
	v_cvt_pk_bf16_f32 v101, v102, v103
	v_cvt_pk_bf16_f32 v102, v96, v97
	v_cvt_pk_bf16_f32 v103, v98, v99
	ds_write_b128 v183, v[100:103]
	s_nop 0
	v_add_co_u32_e32 v112, vcc, s75, v130
	v_cvt_pk_bf16_f32 v96, v170, v171
	v_cvt_pk_bf16_f32 v97, v172, v173
	v_cvt_pk_bf16_f32 v98, v178, v179
	v_cvt_pk_bf16_f32 v99, v180, v181
	s_nop 1
	v_addc_co_u32_e32 v113, vcc, 0, v131, vcc
	global_store_dwordx4 v[112:113], v[116:119], off
	v_add_co_u32_e32 v112, vcc, s78, v130
	ds_write_b128 v183, v[96:99] offset:64
	s_nop 0
	v_addc_co_u32_e32 v113, vcc, 0, v131, vcc
	ds_read_b128 v[96:99], v184
	ds_read_b128 v[100:103], v184 offset:1152
	global_store_dwordx4 v[112:113], v[104:107], off
	s_nop 1
	v_add_co_u32_e32 v104, vcc, s81, v130
	s_nop 1
	v_addc_co_u32_e32 v105, vcc, 0, v131, vcc
	global_store_dwordx4 v[104:105], v[108:111], off
	v_add_co_u32_e32 v104, vcc, s82, v130
	s_nop 1
	v_addc_co_u32_e32 v105, vcc, 0, v131, vcc
	s_waitcnt lgkmcnt(0)
	global_store_dwordx4 v[104:105], v[96:99], off
	s_nop 1
	v_add_co_u32_e32 v96, vcc, s83, v130
	s_nop 1
	v_addc_co_u32_e32 v97, vcc, 0, v131, vcc
	global_store_dwordx4 v[96:97], v[100:103], off
	ds_read_b128 v[96:99], v152 offset:49152
	ds_read_b128 v[100:103], v152 offset:50176
	ds_read_b128 v[104:107], v151 offset:49152
	ds_read_b128 v[108:111], v151 offset:50176
	ds_read_b128 v[112:115], v150 offset:49152
	ds_read_b128 v[116:119], v150 offset:50176
	ds_read_b128 v[120:123], v149 offset:49152
	ds_read_b128 v[124:127], v149 offset:50176
	s_barrier
	s_waitcnt lgkmcnt(0)
	s_setprio 1
	s_waitcnt lgkmcnt(0)
	v_mfma_f32_16x16x32_bf16 v[32:35], v[8:11], v[96:99], v[32:35]
	v_mfma_f32_16x16x32_bf16 v[36:39], v[76:79], v[96:99], v[36:39]
	v_mfma_f32_16x16x32_bf16 v[40:43], v[8:11], v[104:107], v[40:43]
	v_mfma_f32_16x16x32_bf16 v[130:133], v[76:79], v[104:107], v[44:47]
	v_mfma_f32_16x16x32_bf16 v[150:153], v[8:11], v[112:115], v[48:51]
	v_mfma_f32_16x16x32_bf16 v[52:55], v[76:79], v[112:115], v[52:55]
	v_mfma_f32_16x16x32_bf16 v[8:11], v[8:11], v[120:123], v[56:59]
	v_mfma_f32_16x16x32_bf16 v[60:63], v[76:79], v[120:123], v[60:63]
	v_mfma_f32_16x16x32_bf16 v[56:59], v[0:3], v[100:103], v[32:35]
	v_mfma_f32_16x16x32_bf16 v[48:51], v[72:75], v[100:103], v[36:39]
	v_mfma_f32_16x16x32_bf16 v[44:47], v[0:3], v[108:111], v[40:43]
	v_mfma_f32_16x16x32_bf16 v[40:43], v[72:75], v[108:111], v[130:133]
	v_mfma_f32_16x16x32_bf16 v[36:39], v[0:3], v[116:119], v[150:153]
	v_mfma_f32_16x16x32_bf16 v[32:35], v[72:75], v[116:119], v[52:55]
	v_mfma_f32_16x16x32_bf16 v[8:11], v[0:3], v[124:127], v[8:11]
	v_mfma_f32_16x16x32_bf16 v[0:3], v[72:75], v[124:127], v[60:63]
	s_setprio 0
	s_setprio 1
	v_mfma_f32_16x16x32_bf16 v[4:7], v[88:91], v[96:99], v[4:7]
	v_mfma_f32_16x16x32_bf16 v[12:15], v[92:95], v[96:99], v[12:15]
	v_mfma_f32_16x16x32_bf16 v[16:19], v[88:91], v[104:107], v[16:19]
	v_mfma_f32_16x16x32_bf16 v[20:23], v[92:95], v[104:107], v[20:23]
	v_mfma_f32_16x16x32_bf16 v[72:75], v[88:91], v[112:115], v[24:27]
	v_mfma_f32_16x16x32_bf16 v[76:79], v[92:95], v[112:115], v[28:31]
	v_mfma_f32_16x16x32_bf16 v[64:67], v[88:91], v[120:123], v[64:67]
	v_mfma_f32_16x16x32_bf16 v[68:71], v[92:95], v[120:123], v[68:71]
	v_mfma_f32_16x16x32_bf16 v[60:63], v[80:83], v[100:103], v[4:7]
	v_mfma_f32_16x16x32_bf16 v[52:55], v[84:87], v[100:103], v[12:15]
	v_mfma_f32_16x16x32_bf16 v[28:31], v[80:83], v[108:111], v[16:19]
	v_mfma_f32_16x16x32_bf16 v[24:27], v[84:87], v[108:111], v[20:23]
	v_mfma_f32_16x16x32_bf16 v[20:23], v[80:83], v[116:119], v[72:75]
	v_mfma_f32_16x16x32_bf16 v[16:19], v[84:87], v[116:119], v[76:79]
	v_mfma_f32_16x16x32_bf16 v[12:15], v[80:83], v[124:127], v[64:67]
	v_mfma_f32_16x16x32_bf16 v[4:7], v[84:87], v[124:127], v[68:71]
	s_setprio 0
	v_cmp_gt_u32_e32 vcc, s85, v135
	s_barrier
	s_and_saveexec_b64 s[64:65], vcc
	s_cbranch_execz .LBB0_277
	s_barrier

.LBB0_465:
	ds_read_b128 v[164:167], v162
	ds_read_b128 v[168:171], v162 offset:1024
	ds_read_b128 v[172:175], v162 offset:2048
	ds_read_b128 v[176:179], v162 offset:3072
	ds_read_b128 v[180:183], v153
	ds_read_b128 v[184:187], v153 offset:1024
	ds_read_b128 v[188:191], v152
	ds_read_b128 v[192:195], v152 offset:1024
	ds_read_b128 v[196:199], v151
	ds_read_b128 v[200:203], v151 offset:1024
	ds_read_b128 v[204:207], v150
	ds_read_b128 v[208:211], v150 offset:1024
	s_waitcnt lgkmcnt(8)
	s_waitcnt vmcnt(10)
	s_barrier
	s_waitcnt lgkmcnt(0)
	s_setprio 1
	s_waitcnt lgkmcnt(0)
	v_mfma_f32_16x16x32_bf16 v[124:127], v[164:167], v[180:183], v[124:127]
	v_mfma_f32_16x16x32_bf16 v[120:123], v[172:175], v[180:183], v[120:123]
	v_mfma_f32_16x16x32_bf16 v[116:119], v[164:167], v[188:191], v[116:119]
	v_mfma_f32_16x16x32_bf16 v[112:115], v[172:175], v[188:191], v[112:115]
	v_mfma_f32_16x16x32_bf16 v[108:111], v[164:167], v[196:199], v[108:111]
	v_mfma_f32_16x16x32_bf16 v[104:107], v[172:175], v[196:199], v[104:107]
	v_mfma_f32_16x16x32_bf16 v[100:103], v[164:167], v[204:207], v[100:103]
	v_mfma_f32_16x16x32_bf16 v[96:99], v[172:175], v[204:207], v[96:99]
	v_mfma_f32_16x16x32_bf16 v[124:127], v[168:171], v[184:187], v[124:127]
	v_mfma_f32_16x16x32_bf16 v[120:123], v[176:179], v[184:187], v[120:123]
	v_mfma_f32_16x16x32_bf16 v[116:119], v[168:171], v[192:195], v[116:119]
	v_mfma_f32_16x16x32_bf16 v[112:115], v[176:179], v[192:195], v[112:115]
	v_mfma_f32_16x16x32_bf16 v[108:111], v[168:171], v[200:203], v[108:111]
	v_mfma_f32_16x16x32_bf16 v[104:107], v[176:179], v[200:203], v[104:107]
	v_mfma_f32_16x16x32_bf16 v[100:103], v[168:171], v[208:211], v[100:103]
	v_mfma_f32_16x16x32_bf16 v[96:99], v[176:179], v[208:211], v[96:99]
	s_setprio 0
	s_barrier
	v_lshl_add_u64 v[230:231], s[50:51], 0, v[130:131]
	s_mov_b64 s[68:69], 0x3880000
	v_readfirstlane_b32 s36, v149
	v_lshl_add_u64 v[232:233], v[230:231], 0, s[68:69]
	s_mov_b32 m0, s36
	s_mov_b64 s[68:69], 0x3881000
	v_readfirstlane_b32 s36, v148
	ds_read_b128 v[212:215], v159
	ds_read_b128 v[216:219], v159 offset:1024
	ds_read_b128 v[220:223], v159 offset:2048
	ds_read_b128 v[224:227], v159 offset:3072
	global_load_lds_dwordx4 v[232:233], off
	v_lshl_add_u64 v[232:233], v[230:231], 0, s[68:69]
	s_mov_b32 m0, s36
	s_nop 0
	global_load_lds_dwordx4 v[232:233], off
	s_mov_b64 s[68:69], 0xe000100
	v_readfirstlane_b32 s36, v135
	v_lshl_add_u64 v[232:233], v[228:229], 0, s[68:69]
	s_mov_b32 m0, s36
	s_mov_b64 s[68:69], 0xe040100
	v_readfirstlane_b32 s36, v147
	global_load_lds_dwordx4 v[232:233], off
	v_lshl_add_u64 v[232:233], v[228:229], 0, s[68:69]
	s_mov_b32 m0, s36
	s_nop 0
	global_load_lds_dwordx4 v[232:233], off
	s_waitcnt vmcnt(12)
	s_barrier
	s_waitcnt lgkmcnt(0)
	s_setprio 1
	s_waitcnt lgkmcnt(0)
	v_mfma_f32_16x16x32_bf16 v[92:95], v[212:215], v[180:183], v[92:95]
	v_mfma_f32_16x16x32_bf16 v[88:91], v[220:223], v[180:183], v[88:91]
	v_mfma_f32_16x16x32_bf16 v[84:87], v[212:215], v[188:191], v[84:87]
	v_mfma_f32_16x16x32_bf16 v[80:83], v[220:223], v[188:191], v[80:83]
	v_mfma_f32_16x16x32_bf16 v[76:79], v[212:215], v[196:199], v[76:79]
	v_mfma_f32_16x16x32_bf16 v[72:75], v[220:223], v[196:199], v[72:75]
	v_mfma_f32_16x16x32_bf16 v[68:71], v[212:215], v[204:207], v[68:71]
	v_mfma_f32_16x16x32_bf16 v[64:67], v[220:223], v[204:207], v[64:67]
	v_mfma_f32_16x16x32_bf16 v[92:95], v[216:219], v[184:187], v[92:95]
	v_mfma_f32_16x16x32_bf16 v[88:91], v[224:227], v[184:187], v[88:91]
	v_mfma_f32_16x16x32_bf16 v[84:87], v[216:219], v[192:195], v[84:87]
	v_mfma_f32_16x16x32_bf16 v[80:83], v[224:227], v[192:195], v[80:83]
	v_mfma_f32_16x16x32_bf16 v[76:79], v[216:219], v[200:203], v[76:79]
	v_mfma_f32_16x16x32_bf16 v[72:75], v[224:227], v[200:203], v[72:75]
	v_mfma_f32_16x16x32_bf16 v[68:71], v[216:219], v[208:211], v[68:71]
	v_mfma_f32_16x16x32_bf16 v[64:67], v[224:227], v[208:211], v[64:67]
	s_setprio 0
	s_barrier
	ds_read_b128 v[180:183], v153 offset:16384
	ds_read_b128 v[184:187], v153 offset:17408
	ds_read_b128 v[188:191], v152 offset:16384
	ds_read_b128 v[192:195], v152 offset:17408
	ds_read_b128 v[196:199], v151 offset:16384
	ds_read_b128 v[200:203], v151 offset:17408
	ds_read_b128 v[204:207], v150 offset:16384
	ds_read_b128 v[208:211], v150 offset:17408
	s_mov_b64 s[68:69], 0x3882000
	v_readfirstlane_b32 s36, v146
	v_lshl_add_u64 v[232:233], v[230:231], 0, s[68:69]
	s_mov_b32 m0, s36
	s_mov_b64 s[68:69], 0x3883000
	v_readfirstlane_b32 s36, v145
	global_load_lds_dwordx4 v[232:233], off
	v_lshl_add_u64 v[232:233], v[230:231], 0, s[68:69]
	s_mov_b32 m0, s36
	s_nop 0
	global_load_lds_dwordx4 v[232:233], off
	s_barrier
	s_waitcnt lgkmcnt(0)
	s_setprio 1
	s_waitcnt lgkmcnt(0)
	v_mfma_f32_16x16x32_bf16 v[60:63], v[164:167], v[180:183], v[60:63]
	v_mfma_f32_16x16x32_bf16 v[56:59], v[172:175], v[180:183], v[56:59]
	v_mfma_f32_16x16x32_bf16 v[52:55], v[164:167], v[188:191], v[52:55]
	v_mfma_f32_16x16x32_bf16 v[48:51], v[172:175], v[188:191], v[48:51]
	v_mfma_f32_16x16x32_bf16 v[44:47], v[164:167], v[196:199], v[44:47]
	v_mfma_f32_16x16x32_bf16 v[40:43], v[172:175], v[196:199], v[40:43]
	v_mfma_f32_16x16x32_bf16 v[36:39], v[164:167], v[204:207], v[36:39]
	v_mfma_f32_16x16x32_bf16 v[32:35], v[172:175], v[204:207], v[32:35]
	v_mfma_f32_16x16x32_bf16 v[60:63], v[168:171], v[184:187], v[60:63]
	v_mfma_f32_16x16x32_bf16 v[56:59], v[176:179], v[184:187], v[56:59]
	v_mfma_f32_16x16x32_bf16 v[52:55], v[168:171], v[192:195], v[52:55]
	v_mfma_f32_16x16x32_bf16 v[48:51], v[176:179], v[192:195], v[48:51]
	v_mfma_f32_16x16x32_bf16 v[44:47], v[168:171], v[200:203], v[44:47]
	v_mfma_f32_16x16x32_bf16 v[40:43], v[176:179], v[200:203], v[40:43]
	v_mfma_f32_16x16x32_bf16 v[36:39], v[168:171], v[208:211], v[36:39]
	v_mfma_f32_16x16x32_bf16 v[32:35], v[176:179], v[208:211], v[32:35]
	s_setprio 0
	s_barrier
	v_readfirstlane_b32 s36, v144
	v_lshl_add_u64 v[166:167], v[228:229], 0, s[26:27]
	s_mov_b32 m0, s36
	v_readfirstlane_b32 s36, v143
	global_load_lds_dwordx4 v[166:167], off
	v_lshl_add_u64 v[166:167], v[228:229], 0, s[28:29]
	s_mov_b32 m0, s36
	s_nop 0
	global_load_lds_dwordx4 v[166:167], off
	s_waitcnt vmcnt(12)
	s_barrier
	s_setprio 1
	v_mfma_f32_16x16x32_bf16 v[28:31], v[212:215], v[180:183], v[28:31]
	v_mfma_f32_16x16x32_bf16 v[24:27], v[220:223], v[180:183], v[24:27]
	v_mfma_f32_16x16x32_bf16 v[20:23], v[212:215], v[188:191], v[20:23]
	v_mfma_f32_16x16x32_bf16 v[16:19], v[220:223], v[188:191], v[16:19]
	v_mfma_f32_16x16x32_bf16 v[12:15], v[212:215], v[196:199], v[12:15]
	v_mfma_f32_16x16x32_bf16 v[8:11], v[220:223], v[196:199], v[8:11]
	v_mfma_f32_16x16x32_bf16 v[4:7], v[212:215], v[204:207], v[4:7]
	v_mfma_f32_16x16x32_bf16 v[0:3], v[220:223], v[204:207], v[0:3]
	v_mfma_f32_16x16x32_bf16 v[28:31], v[216:219], v[184:187], v[28:31]
	v_mfma_f32_16x16x32_bf16 v[24:27], v[224:227], v[184:187], v[24:27]
	v_mfma_f32_16x16x32_bf16 v[20:23], v[216:219], v[192:195], v[20:23]
	v_mfma_f32_16x16x32_bf16 v[16:19], v[224:227], v[192:195], v[16:19]
	v_mfma_f32_16x16x32_bf16 v[12:15], v[216:219], v[200:203], v[12:15]
	v_mfma_f32_16x16x32_bf16 v[8:11], v[224:227], v[200:203], v[8:11]
	v_mfma_f32_16x16x32_bf16 v[4:7], v[216:219], v[208:211], v[4:7]
	v_mfma_f32_16x16x32_bf16 v[0:3], v[224:227], v[208:211], v[0:3]
	s_setprio 0
	s_barrier
	ds_read_b128 v[164:167], v155
	ds_read_b128 v[168:171], v155 offset:1024
	ds_read_b128 v[172:175], v155 offset:2048
	ds_read_b128 v[176:179], v155 offset:3072
	ds_read_b128 v[180:183], v153 offset:32768
	ds_read_b128 v[184:187], v153 offset:33792
	ds_read_b128 v[188:191], v152 offset:32768
	ds_read_b128 v[192:195], v152 offset:33792
	ds_read_b128 v[196:199], v151 offset:32768
	ds_read_b128 v[200:203], v151 offset:33792
	ds_read_b128 v[204:207], v150 offset:32768
	ds_read_b128 v[208:211], v150 offset:33792
	s_waitcnt lgkmcnt(8)
	s_waitcnt vmcnt(10)
	s_barrier
	s_waitcnt lgkmcnt(0)
	s_setprio 1
	s_waitcnt lgkmcnt(0)
	v_mfma_f32_16x16x32_bf16 v[124:127], v[164:167], v[180:183], v[124:127]
	v_mfma_f32_16x16x32_bf16 v[120:123], v[172:175], v[180:183], v[120:123]
	v_mfma_f32_16x16x32_bf16 v[116:119], v[164:167], v[188:191], v[116:119]
	v_mfma_f32_16x16x32_bf16 v[112:115], v[172:175], v[188:191], v[112:115]
	v_mfma_f32_16x16x32_bf16 v[108:111], v[164:167], v[196:199], v[108:111]
	v_mfma_f32_16x16x32_bf16 v[104:107], v[172:175], v[196:199], v[104:107]
	v_mfma_f32_16x16x32_bf16 v[100:103], v[164:167], v[204:207], v[100:103]
	v_mfma_f32_16x16x32_bf16 v[96:99], v[172:175], v[204:207], v[96:99]
	v_mfma_f32_16x16x32_bf16 v[124:127], v[168:171], v[184:187], v[124:127]
	v_mfma_f32_16x16x32_bf16 v[120:123], v[176:179], v[184:187], v[120:123]
	v_mfma_f32_16x16x32_bf16 v[116:119], v[168:171], v[192:195], v[116:119]
	v_mfma_f32_16x16x32_bf16 v[112:115], v[176:179], v[192:195], v[112:115]
	v_mfma_f32_16x16x32_bf16 v[108:111], v[168:171], v[200:203], v[108:111]
	v_mfma_f32_16x16x32_bf16 v[104:107], v[176:179], v[200:203], v[104:107]
	v_mfma_f32_16x16x32_bf16 v[100:103], v[168:171], v[208:211], v[100:103]
	v_mfma_f32_16x16x32_bf16 v[96:99], v[176:179], v[208:211], v[96:99]
	s_setprio 0
	s_barrier
	v_readfirstlane_b32 s36, v142
	v_lshl_add_u64 v[232:233], v[230:231], 0, s[30:31]
	s_mov_b32 m0, s36
	v_readfirstlane_b32 s36, v141
	ds_read_b128 v[212:215], v154
	ds_read_b128 v[216:219], v154 offset:1024
	ds_read_b128 v[220:223], v154 offset:2048
	ds_read_b128 v[224:227], v154 offset:3072
	global_load_lds_dwordx4 v[232:233], off
	v_lshl_add_u64 v[232:233], v[230:231], 0, s[34:35]
	s_mov_b32 m0, s36
	s_nop 0
	global_load_lds_dwordx4 v[232:233], off
	v_readfirstlane_b32 s36, v140
	v_lshl_add_u64 v[232:233], v[228:229], 0, s[44:45]
	s_mov_b32 m0, s36
	v_readfirstlane_b32 s36, v139
	global_load_lds_dwordx4 v[232:233], off
	v_lshl_add_u64 v[228:229], v[228:229], 0, s[46:47]
	s_mov_b32 m0, s36
	s_nop 0
	global_load_lds_dwordx4 v[228:229], off
	s_waitcnt vmcnt(12)
	s_barrier
	s_waitcnt lgkmcnt(0)
	s_setprio 1
	s_waitcnt lgkmcnt(0)
	v_mfma_f32_16x16x32_bf16 v[92:95], v[212:215], v[180:183], v[92:95]
	v_mfma_f32_16x16x32_bf16 v[88:91], v[220:223], v[180:183], v[88:91]
	v_mfma_f32_16x16x32_bf16 v[84:87], v[212:215], v[188:191], v[84:87]
	v_mfma_f32_16x16x32_bf16 v[80:83], v[220:223], v[188:191], v[80:83]
	v_mfma_f32_16x16x32_bf16 v[76:79], v[212:215], v[196:199], v[76:79]
	v_mfma_f32_16x16x32_bf16 v[72:75], v[220:223], v[196:199], v[72:75]
	v_mfma_f32_16x16x32_bf16 v[68:71], v[212:215], v[204:207], v[68:71]
	v_mfma_f32_16x16x32_bf16 v[64:67], v[220:223], v[204:207], v[64:67]
	v_mfma_f32_16x16x32_bf16 v[92:95], v[216:219], v[184:187], v[92:95]
	v_mfma_f32_16x16x32_bf16 v[88:91], v[224:227], v[184:187], v[88:91]
	v_mfma_f32_16x16x32_bf16 v[84:87], v[216:219], v[192:195], v[84:87]
	v_mfma_f32_16x16x32_bf16 v[80:83], v[224:227], v[192:195], v[80:83]
	v_mfma_f32_16x16x32_bf16 v[76:79], v[216:219], v[200:203], v[76:79]
	v_mfma_f32_16x16x32_bf16 v[72:75], v[224:227], v[200:203], v[72:75]
	v_mfma_f32_16x16x32_bf16 v[68:71], v[216:219], v[208:211], v[68:71]
	v_mfma_f32_16x16x32_bf16 v[64:67], v[224:227], v[208:211], v[64:67]
	s_setprio 0
	s_barrier
	ds_read_b128 v[180:183], v153 offset:49152
	ds_read_b128 v[184:187], v153 offset:50176
	ds_read_b128 v[188:191], v152 offset:49152
	ds_read_b128 v[192:195], v152 offset:50176
	ds_read_b128 v[196:199], v151 offset:49152
	ds_read_b128 v[200:203], v151 offset:50176
	ds_read_b128 v[204:207], v150 offset:49152
	ds_read_b128 v[208:211], v150 offset:50176
	v_readfirstlane_b32 s36, v138
	v_lshl_add_u64 v[232:233], v[230:231], 0, s[56:57]
	s_mov_b32 m0, s36
	v_readfirstlane_b32 s36, v137
	global_load_lds_dwordx4 v[232:233], off
	v_lshl_add_u64 v[232:233], v[230:231], 0, s[58:59]
	s_mov_b32 m0, s36
	s_nop 0
	global_load_lds_dwordx4 v[232:233], off
	s_barrier
	s_waitcnt lgkmcnt(0)
	s_setprio 1
	s_waitcnt lgkmcnt(0)
	v_mfma_f32_16x16x32_bf16 v[60:63], v[164:167], v[180:183], v[60:63]
	v_mfma_f32_16x16x32_bf16 v[56:59], v[172:175], v[180:183], v[56:59]
	v_mfma_f32_16x16x32_bf16 v[52:55], v[164:167], v[188:191], v[52:55]
	v_mfma_f32_16x16x32_bf16 v[48:51], v[172:175], v[188:191], v[48:51]
	v_mfma_f32_16x16x32_bf16 v[44:47], v[164:167], v[196:199], v[44:47]
	v_mfma_f32_16x16x32_bf16 v[40:43], v[172:175], v[196:199], v[40:43]
	v_mfma_f32_16x16x32_bf16 v[36:39], v[164:167], v[204:207], v[36:39]
	v_mfma_f32_16x16x32_bf16 v[32:35], v[172:175], v[204:207], v[32:35]
	v_mfma_f32_16x16x32_bf16 v[60:63], v[168:171], v[184:187], v[60:63]
	v_mfma_f32_16x16x32_bf16 v[56:59], v[176:179], v[184:187], v[56:59]
	v_mfma_f32_16x16x32_bf16 v[52:55], v[168:171], v[192:195], v[52:55]
	v_mfma_f32_16x16x32_bf16 v[48:51], v[176:179], v[192:195], v[48:51]
	v_mfma_f32_16x16x32_bf16 v[44:47], v[168:171], v[200:203], v[44:47]
	v_mfma_f32_16x16x32_bf16 v[40:43], v[176:179], v[200:203], v[40:43]
	v_mfma_f32_16x16x32_bf16 v[36:39], v[168:171], v[208:211], v[36:39]
	v_mfma_f32_16x16x32_bf16 v[32:35], v[176:179], v[208:211], v[32:35]
	s_setprio 0
	s_barrier
	v_lshl_add_u64 v[132:133], v[132:133], 0, s[60:61]
	v_lshl_add_u64 v[228:229], s[50:51], 0, v[132:133]
	s_mov_b64 s[68:69], 0xe080080
	v_readfirstlane_b32 s36, v161
	v_lshl_add_u64 v[166:167], v[228:229], 0, s[68:69]
	s_mov_b32 m0, s36
	s_mov_b64 s[68:69], 0xe0c0080
	v_readfirstlane_b32 s36, v160
	global_load_lds_dwordx4 v[166:167], off
	v_lshl_add_u64 v[166:167], v[228:229], 0, s[68:69]
	s_mov_b32 m0, s36
	s_nop 0
	global_load_lds_dwordx4 v[166:167], off
	s_waitcnt vmcnt(12)
	s_barrier
	s_setprio 1
	v_mfma_f32_16x16x32_bf16 v[28:31], v[212:215], v[180:183], v[28:31]
	v_mfma_f32_16x16x32_bf16 v[24:27], v[220:223], v[180:183], v[24:27]
	v_mfma_f32_16x16x32_bf16 v[20:23], v[212:215], v[188:191], v[20:23]
	v_mfma_f32_16x16x32_bf16 v[16:19], v[220:223], v[188:191], v[16:19]
	v_mfma_f32_16x16x32_bf16 v[12:15], v[212:215], v[196:199], v[12:15]
	v_mfma_f32_16x16x32_bf16 v[8:11], v[220:223], v[196:199], v[8:11]
	v_mfma_f32_16x16x32_bf16 v[4:7], v[212:215], v[204:207], v[4:7]
	v_mfma_f32_16x16x32_bf16 v[0:3], v[220:223], v[204:207], v[0:3]
	v_mfma_f32_16x16x32_bf16 v[28:31], v[216:219], v[184:187], v[28:31]
	v_mfma_f32_16x16x32_bf16 v[24:27], v[224:227], v[184:187], v[24:27]
	v_mfma_f32_16x16x32_bf16 v[20:23], v[216:219], v[192:195], v[20:23]
	v_mfma_f32_16x16x32_bf16 v[16:19], v[224:227], v[192:195], v[16:19]
	v_mfma_f32_16x16x32_bf16 v[12:15], v[216:219], v[200:203], v[12:15]
	v_mfma_f32_16x16x32_bf16 v[8:11], v[224:227], v[200:203], v[8:11]
	v_mfma_f32_16x16x32_bf16 v[4:7], v[216:219], v[208:211], v[4:7]
	v_mfma_f32_16x16x32_bf16 v[0:3], v[224:227], v[208:211], v[0:3]
	s_setprio 0
	s_add_i32 s24, s24, 2
	v_lshl_add_u64 v[130:131], v[130:131], 0, s[10:11]
	s_cmp_lt_u32 s24, 28
	s_barrier
	s_cbranch_scc1 .LBB0_465
	s_lshl_b32 s24, s86, 5
	s_lshl_b32 s36, s86, 8
	s_and_b32 s24, s24, 0x1800
	s_and_b32 s36, s36, 0x700
	s_or_b32 s24, s36, s24
	v_lshlrev_b32_e32 v128, 3, v156
	v_lshlrev_b32_e32 v130, 5, v156
	v_and_b32_e32 v128, 0xffff0, v128
	v_and_b32_e32 v130, 32, v130
	s_lshl_b32 s36, s24, 12
	v_add_u32_e32 v130, v130, v158
	v_add_lshl_u32 v128, v157, v128, 12
	s_add_u32 s68, s70, s36
	v_lshl_add_u32 v128, v130, 1, v128
	s_addc_u32 s69, s71, 0
	v_lshl_add_u64 v[156:157], s[68:69], 0, v[128:129]
	v_readfirstlane_b32 s36, v161
	ds_read_b128 v[130:133], v162
	ds_read_b128 v[164:167], v162 offset:1024
	ds_read_b128 v[168:171], v162 offset:2048
	ds_read_b128 v[172:175], v162 offset:3072
	ds_read_b128 v[176:179], v153
	ds_read_b128 v[180:183], v153 offset:1024
	ds_read_b128 v[184:187], v152
	ds_read_b128 v[188:191], v152 offset:1024
	ds_read_b128 v[192:195], v151
	ds_read_b128 v[196:199], v151 offset:1024
	ds_read_b128 v[200:203], v150
	ds_read_b128 v[204:207], v150 offset:1024
	v_lshl_add_u64 v[162:163], v[156:157], 0, s[62:63]
	s_mov_b32 m0, s36
	v_readfirstlane_b32 s36, v160
	global_load_lds_dwordx4 v[162:163], off
	v_lshl_add_u64 v[156:157], v[156:157], 0, s[64:65]
	s_mov_b32 m0, s36
	s_nop 0
	global_load_lds_dwordx4 v[156:157], off
	s_waitcnt vmcnt(10)
	s_barrier
	s_waitcnt lgkmcnt(0)
	s_setprio 1
	s_waitcnt lgkmcnt(0)
	v_mfma_f32_16x16x32_bf16 v[124:127], v[130:133], v[176:179], v[124:127]
	v_mfma_f32_16x16x32_bf16 v[120:123], v[168:171], v[176:179], v[120:123]
	v_mfma_f32_16x16x32_bf16 v[116:119], v[130:133], v[184:187], v[116:119]
	v_mfma_f32_16x16x32_bf16 v[112:115], v[168:171], v[184:187], v[112:115]
	v_mfma_f32_16x16x32_bf16 v[108:111], v[130:133], v[192:195], v[108:111]
	v_mfma_f32_16x16x32_bf16 v[104:107], v[168:171], v[192:195], v[104:107]
	v_mfma_f32_16x16x32_bf16 v[100:103], v[130:133], v[200:203], v[100:103]
	v_mfma_f32_16x16x32_bf16 v[96:99], v[168:171], v[200:203], v[96:99]
	v_mfma_f32_16x16x32_bf16 v[124:127], v[164:167], v[180:183], v[124:127]
	v_mfma_f32_16x16x32_bf16 v[120:123], v[172:175], v[180:183], v[120:123]
	v_mfma_f32_16x16x32_bf16 v[116:119], v[164:167], v[188:191], v[116:119]
	v_mfma_f32_16x16x32_bf16 v[112:115], v[172:175], v[188:191], v[112:115]
	v_mfma_f32_16x16x32_bf16 v[108:111], v[164:167], v[196:199], v[108:111]
	v_mfma_f32_16x16x32_bf16 v[104:107], v[172:175], v[196:199], v[104:107]
	v_mfma_f32_16x16x32_bf16 v[100:103], v[164:167], v[204:207], v[100:103]
	v_mfma_f32_16x16x32_bf16 v[96:99], v[172:175], v[204:207], v[96:99]
	s_setprio 0
	s_barrier
	ds_read_b128 v[160:163], v159
	ds_read_b128 v[208:211], v159 offset:1024
	ds_read_b128 v[212:215], v159 offset:2048
	ds_read_b128 v[156:159], v159 offset:3072
	s_barrier
	s_waitcnt lgkmcnt(0)
	s_setprio 1
	s_waitcnt lgkmcnt(0)
	v_mfma_f32_16x16x32_bf16 v[92:95], v[160:163], v[176:179], v[92:95]
	v_mfma_f32_16x16x32_bf16 v[88:91], v[212:215], v[176:179], v[88:91]
	v_mfma_f32_16x16x32_bf16 v[84:87], v[160:163], v[184:187], v[84:87]
	v_mfma_f32_16x16x32_bf16 v[80:83], v[212:215], v[184:187], v[80:83]
	v_mfma_f32_16x16x32_bf16 v[76:79], v[160:163], v[192:195], v[76:79]
	v_mfma_f32_16x16x32_bf16 v[72:75], v[212:215], v[192:195], v[72:75]
	v_mfma_f32_16x16x32_bf16 v[68:71], v[160:163], v[200:203], v[68:71]
	v_mfma_f32_16x16x32_bf16 v[64:67], v[212:215], v[200:203], v[64:67]
	v_mfma_f32_16x16x32_bf16 v[176:179], v[208:211], v[180:183], v[92:95]
	v_mfma_f32_16x16x32_bf16 v[180:183], v[156:159], v[180:183], v[88:91]
	v_mfma_f32_16x16x32_bf16 v[184:187], v[208:211], v[188:191], v[84:87]
	v_mfma_f32_16x16x32_bf16 v[188:191], v[156:159], v[188:191], v[80:83]
	v_mfma_f32_16x16x32_bf16 v[192:195], v[208:211], v[196:199], v[76:79]
	v_mfma_f32_16x16x32_bf16 v[196:199], v[156:159], v[196:199], v[72:75]
	v_mfma_f32_16x16x32_bf16 v[200:203], v[208:211], v[204:207], v[68:71]
	v_mfma_f32_16x16x32_bf16 v[204:207], v[156:159], v[204:207], v[64:67]
	s_setprio 0
	s_barrier
	s_nop 0
	ds_read_b128 v[64:67], v153 offset:16384
	ds_read_b128 v[68:71], v153 offset:17408
	ds_read_b128 v[72:75], v152 offset:16384
	ds_read_b128 v[76:79], v152 offset:17408
	ds_read_b128 v[80:83], v151 offset:16384
	ds_read_b128 v[84:87], v151 offset:17408
	ds_read_b128 v[88:91], v150 offset:16384
	ds_read_b128 v[92:95], v150 offset:17408
	s_waitcnt vmcnt(4)
	s_barrier
	s_waitcnt lgkmcnt(0)
	s_setprio 1
	s_waitcnt lgkmcnt(0)
	v_mfma_f32_16x16x32_bf16 v[60:63], v[130:133], v[64:67], v[60:63]
	v_mfma_f32_16x16x32_bf16 v[56:59], v[168:171], v[64:67], v[56:59]
	v_mfma_f32_16x16x32_bf16 v[52:55], v[130:133], v[72:75], v[52:55]
	v_mfma_f32_16x16x32_bf16 v[48:51], v[168:171], v[72:75], v[48:51]
	v_mfma_f32_16x16x32_bf16 v[216:219], v[130:133], v[80:83], v[44:47]
	v_mfma_f32_16x16x32_bf16 v[220:223], v[168:171], v[80:83], v[40:43]
	v_mfma_f32_16x16x32_bf16 v[130:133], v[130:133], v[88:91], v[36:39]
	v_mfma_f32_16x16x32_bf16 v[168:171], v[168:171], v[88:91], v[32:35]
	v_mfma_f32_16x16x32_bf16 v[32:35], v[164:167], v[68:71], v[60:63]
	v_mfma_f32_16x16x32_bf16 v[36:39], v[172:175], v[68:71], v[56:59]
	v_mfma_f32_16x16x32_bf16 v[40:43], v[164:167], v[76:79], v[52:55]
	v_mfma_f32_16x16x32_bf16 v[44:47], v[172:175], v[76:79], v[48:51]
	v_mfma_f32_16x16x32_bf16 v[48:51], v[164:167], v[84:87], v[216:219]
	v_mfma_f32_16x16x32_bf16 v[52:55], v[172:175], v[84:87], v[220:223]
	v_mfma_f32_16x16x32_bf16 v[56:59], v[164:167], v[92:95], v[130:133]
	v_mfma_f32_16x16x32_bf16 v[60:63], v[172:175], v[92:95], v[168:171]
	s_setprio 0
	s_setprio 1
	v_mfma_f32_16x16x32_bf16 v[28:31], v[160:163], v[64:67], v[28:31]
	v_mfma_f32_16x16x32_bf16 v[24:27], v[212:215], v[64:67], v[24:27]
	v_mfma_f32_16x16x32_bf16 v[20:23], v[160:163], v[72:75], v[20:23]
	v_mfma_f32_16x16x32_bf16 v[64:67], v[212:215], v[72:75], v[16:19]
	v_mfma_f32_16x16x32_bf16 v[72:75], v[160:163], v[80:83], v[12:15]
	v_mfma_f32_16x16x32_bf16 v[8:11], v[212:215], v[80:83], v[8:11]
	v_mfma_f32_16x16x32_bf16 v[80:83], v[160:163], v[88:91], v[4:7]
	v_mfma_f32_16x16x32_bf16 v[0:3], v[212:215], v[88:91], v[0:3]
	v_mfma_f32_16x16x32_bf16 v[4:7], v[208:211], v[68:71], v[28:31]
	v_mfma_f32_16x16x32_bf16 v[12:15], v[156:159], v[68:71], v[24:27]
	v_mfma_f32_16x16x32_bf16 v[16:19], v[208:211], v[76:79], v[20:23]
	v_mfma_f32_16x16x32_bf16 v[20:23], v[156:159], v[76:79], v[64:67]
	v_mfma_f32_16x16x32_bf16 v[24:27], v[208:211], v[84:87], v[72:75]
	v_mfma_f32_16x16x32_bf16 v[28:31], v[156:159], v[84:87], v[8:11]
	v_mfma_f32_16x16x32_bf16 v[64:67], v[208:211], v[92:95], v[80:83]
	v_mfma_f32_16x16x32_bf16 v[68:71], v[156:159], v[92:95], v[0:3]
	s_setprio 0
	s_barrier
	ds_read_b128 v[8:11], v155
	ds_read_b128 v[0:3], v155 offset:1024
	ds_read_b128 v[76:79], v155 offset:2048
	ds_read_b128 v[72:75], v155 offset:3072
	ds_read_b128 v[130:133], v153 offset:32768
	ds_read_b128 v[156:159], v153 offset:33792
	ds_read_b128 v[160:163], v152 offset:32768
	ds_read_b128 v[164:167], v152 offset:33792
	ds_read_b128 v[168:171], v151 offset:32768
	ds_read_b128 v[172:175], v151 offset:33792
	ds_read_b128 v[208:211], v150 offset:32768
	ds_read_b128 v[212:215], v150 offset:33792
	s_waitcnt vmcnt(2)
	s_barrier
	s_waitcnt lgkmcnt(0)
	s_setprio 1
	s_waitcnt lgkmcnt(0)
	v_mfma_f32_16x16x32_bf16 v[80:83], v[8:11], v[130:133], v[124:127]
	v_mfma_f32_16x16x32_bf16 v[84:87], v[76:79], v[130:133], v[120:123]
	v_mfma_f32_16x16x32_bf16 v[88:91], v[8:11], v[160:163], v[116:119]
	v_mfma_f32_16x16x32_bf16 v[92:95], v[76:79], v[160:163], v[112:115]
	v_mfma_f32_16x16x32_bf16 v[108:111], v[8:11], v[168:171], v[108:111]
	v_mfma_f32_16x16x32_bf16 v[104:107], v[76:79], v[168:171], v[104:107]
	v_mfma_f32_16x16x32_bf16 v[100:103], v[8:11], v[208:211], v[100:103]
	v_mfma_f32_16x16x32_bf16 v[96:99], v[76:79], v[208:211], v[96:99]
	v_mfma_f32_16x16x32_bf16 v[112:115], v[0:3], v[156:159], v[80:83]
	v_mfma_f32_16x16x32_bf16 v[116:119], v[72:75], v[156:159], v[84:87]
	v_mfma_f32_16x16x32_bf16 v[120:123], v[0:3], v[164:167], v[88:91]
	v_mfma_f32_16x16x32_bf16 v[124:127], v[72:75], v[164:167], v[92:95]
	v_mfma_f32_16x16x32_bf16 v[108:111], v[0:3], v[172:175], v[108:111]
	v_mfma_f32_16x16x32_bf16 v[104:107], v[72:75], v[172:175], v[104:107]
	v_mfma_f32_16x16x32_bf16 v[100:103], v[0:3], v[212:215], v[100:103]
	v_mfma_f32_16x16x32_bf16 v[96:99], v[72:75], v[212:215], v[96:99]
	s_setprio 0
	s_barrier
	ds_read_b128 v[88:91], v154
	ds_read_b128 v[80:83], v154 offset:1024
	ds_read_b128 v[92:95], v154 offset:2048
	ds_read_b128 v[84:87], v154 offset:3072
	s_waitcnt vmcnt(0)
	s_barrier
	s_waitcnt lgkmcnt(0)
	s_setprio 1
	s_waitcnt lgkmcnt(0)
	v_mfma_f32_16x16x32_bf16 v[176:179], v[88:91], v[130:133], v[176:179]
	v_mfma_f32_16x16x32_bf16 v[130:133], v[92:95], v[130:133], v[180:183]
	v_mfma_f32_16x16x32_bf16 v[180:183], v[88:91], v[160:163], v[184:187]
	v_mfma_f32_16x16x32_bf16 v[160:163], v[92:95], v[160:163], v[188:191]
	v_mfma_f32_16x16x32_bf16 v[184:187], v[88:91], v[168:171], v[192:195]
	v_mfma_f32_16x16x32_bf16 v[168:171], v[92:95], v[168:171], v[196:199]
	v_mfma_f32_16x16x32_bf16 v[188:191], v[88:91], v[208:211], v[200:203]
	v_mfma_f32_16x16x32_bf16 v[192:195], v[92:95], v[208:211], v[204:207]
	v_mfma_f32_16x16x32_bf16 v[176:179], v[80:83], v[156:159], v[176:179]
	v_mfma_f32_16x16x32_bf16 v[130:133], v[84:87], v[156:159], v[130:133]
	v_mfma_f32_16x16x32_bf16 v[154:157], v[80:83], v[164:167], v[180:183]
	v_mfma_f32_16x16x32_bf16 v[158:161], v[84:87], v[164:167], v[160:163]
	v_mfma_f32_16x16x32_bf16 v[162:165], v[80:83], v[172:175], v[184:187]
	v_mfma_f32_16x16x32_bf16 v[166:169], v[84:87], v[172:175], v[168:171]
	v_mfma_f32_16x16x32_bf16 v[170:173], v[80:83], v[212:215], v[188:191]
	v_mfma_f32_16x16x32_bf16 v[180:183], v[84:87], v[212:215], v[192:195]
	s_setprio 0
	s_barrier
	v_mbcnt_lo_u32_b32 v128, -1, 0
	v_mbcnt_hi_u32_b32 v128, -1, v128
	v_cvt_pk_bf16_f32 v112, v112, v113
	v_cvt_pk_bf16_f32 v113, v114, v115
	v_cvt_pk_bf16_f32 v114, v116, v117
	v_cvt_pk_bf16_f32 v115, v118, v119
	s_lshl_b32 s68, s66, 9
	v_add_u32_e32 v174, s74, v128
	v_ashrrev_i32_e32 v175, 6, v174
	v_and_b32_e32 v184, 15, v128
	v_and_b32_e32 v185, 48, v128
	v_mul_lo_u32 v186, v175, s79
	v_bfe_u32 v187, v128, 3, 3
	v_lshlrev_b32_e32 v128, 4, v128
	v_add_u32_e32 v186, 0x20000, v186
	v_lshrrev_b32_e32 v174, 2, v174
	v_and_b32_e32 v128, 0x70, v128
	v_mul_u32_u24_e32 v184, 0x90, v184
	v_and_b32_e32 v174, 64, v174
	v_add3_u32 v184, v186, v184, v185
	v_or_b32_e32 v185, v186, v128
	v_or3_b32 v174, s24, v174, v187
	v_mad_u32_u24 v185, v187, s80, v185
	ds_write_b128 v184, v[112:115]
	v_cvt_pk_bf16_f32 v112, v176, v177
	v_cvt_pk_bf16_f32 v113, v178, v179
	v_cvt_pk_bf16_f32 v114, v130, v131
	v_cvt_pk_bf16_f32 v115, v132, v133
	ds_write_b128 v184, v[112:115] offset:64
	v_lshlrev_b32_e32 v175, 7, v175
	ds_read_b128 v[112:115], v185
	v_lshlrev_b32_e32 v116, 12, v174
	v_and_or_b32 v116, v175, s81, v116
	v_or3_b32 v128, v116, s68, v128
	ds_read_b128 v[116:119], v185 offset:1152
	v_lshl_add_u64 v[130:131], s[0:1], 0, v[128:129]
	s_mov_b32 s36, 0x8000
	s_waitcnt lgkmcnt(0)
	global_store_dwordx4 v128, v[112:115], s[0:1]
	v_cvt_pk_bf16_f32 v108, v108, v109
	v_cvt_pk_bf16_f32 v109, v110, v111
	v_cvt_pk_bf16_f32 v110, v104, v105
	v_cvt_pk_bf16_f32 v111, v106, v107
	v_cvt_pk_bf16_f32 v104, v162, v163
	s_nop 1
	v_add_co_u32_e32 v112, vcc, s36, v130
	v_cvt_pk_bf16_f32 v114, v124, v125
	v_cvt_pk_bf16_f32 v115, v126, v127
	v_cvt_pk_bf16_f32 v105, v164, v165
	v_cvt_pk_bf16_f32 v106, v166, v167
	s_nop 1
	v_addc_co_u32_e32 v113, vcc, 0, v131, vcc
	global_store_dwordx4 v[112:113], v[116:119], off
	v_cvt_pk_bf16_f32 v112, v120, v121
	v_cvt_pk_bf16_f32 v113, v122, v123
	ds_write_b128 v184, v[112:115]
	v_cvt_pk_bf16_f32 v112, v154, v155
	v_cvt_pk_bf16_f32 v113, v156, v157
	v_cvt_pk_bf16_f32 v114, v158, v159
	v_cvt_pk_bf16_f32 v115, v160, v161
	ds_write_b128 v184, v[112:115] offset:64
	ds_read_b128 v[112:115], v185
	ds_read_b128 v[116:119], v185 offset:1152
	v_add_co_u32_e32 v120, vcc, s76, v130
	ds_write_b128 v184, v[108:111]
	v_cvt_pk_bf16_f32 v107, v168, v169
	ds_write_b128 v184, v[104:107] offset:64
	v_addc_co_u32_e32 v121, vcc, 0, v131, vcc
	ds_read_b128 v[104:107], v185
	ds_read_b128 v[108:111], v185 offset:1152
	s_waitcnt lgkmcnt(0)
	global_store_dwordx4 v[120:121], v[112:115], off
	v_cvt_pk_bf16_f32 v100, v100, v101
	v_cvt_pk_bf16_f32 v101, v102, v103
	v_cvt_pk_bf16_f32 v102, v96, v97
	v_cvt_pk_bf16_f32 v103, v98, v99
	ds_write_b128 v184, v[100:103]
	s_nop 0
	v_add_co_u32_e32 v112, vcc, s77, v130
	v_cvt_pk_bf16_f32 v96, v170, v171
	v_cvt_pk_bf16_f32 v97, v172, v173
	v_cvt_pk_bf16_f32 v98, v180, v181
	v_cvt_pk_bf16_f32 v99, v182, v183
	s_nop 1
	v_addc_co_u32_e32 v113, vcc, 0, v131, vcc
	global_store_dwordx4 v[112:113], v[116:119], off
	v_add_co_u32_e32 v112, vcc, s78, v130
	ds_write_b128 v184, v[96:99] offset:64
	s_nop 0
	v_addc_co_u32_e32 v113, vcc, 0, v131, vcc
	ds_read_b128 v[96:99], v185
	ds_read_b128 v[100:103], v185 offset:1152
	global_store_dwordx4 v[112:113], v[104:107], off
	s_nop 1
	v_add_co_u32_e32 v104, vcc, s82, v130
	s_nop 1
	v_addc_co_u32_e32 v105, vcc, 0, v131, vcc
	global_store_dwordx4 v[104:105], v[108:111], off
	v_add_co_u32_e32 v104, vcc, s83, v130
	s_nop 1
	v_addc_co_u32_e32 v105, vcc, 0, v131, vcc
	s_waitcnt lgkmcnt(0)
	global_store_dwordx4 v[104:105], v[96:99], off
	s_nop 1
	v_add_co_u32_e32 v96, vcc, s91, v130
	s_nop 1
	v_addc_co_u32_e32 v97, vcc, 0, v131, vcc
	global_store_dwordx4 v[96:97], v[100:103], off
	ds_read_b128 v[96:99], v153 offset:49152
	ds_read_b128 v[100:103], v153 offset:50176
	ds_read_b128 v[104:107], v152 offset:49152
	ds_read_b128 v[108:111], v152 offset:50176
	ds_read_b128 v[112:115], v151 offset:49152
	ds_read_b128 v[116:119], v151 offset:50176
	ds_read_b128 v[120:123], v150 offset:49152
	ds_read_b128 v[124:127], v150 offset:50176
	s_barrier
	s_waitcnt lgkmcnt(0)
	s_setprio 1
	s_waitcnt lgkmcnt(0)
	v_mfma_f32_16x16x32_bf16 v[32:35], v[8:11], v[96:99], v[32:35]
	v_mfma_f32_16x16x32_bf16 v[36:39], v[76:79], v[96:99], v[36:39]
	v_mfma_f32_16x16x32_bf16 v[40:43], v[8:11], v[104:107], v[40:43]
	v_mfma_f32_16x16x32_bf16 v[130:133], v[76:79], v[104:107], v[44:47]
	v_mfma_f32_16x16x32_bf16 v[150:153], v[8:11], v[112:115], v[48:51]
	v_mfma_f32_16x16x32_bf16 v[52:55], v[76:79], v[112:115], v[52:55]
	v_mfma_f32_16x16x32_bf16 v[8:11], v[8:11], v[120:123], v[56:59]
	v_mfma_f32_16x16x32_bf16 v[60:63], v[76:79], v[120:123], v[60:63]
	v_mfma_f32_16x16x32_bf16 v[56:59], v[0:3], v[100:103], v[32:35]
	v_mfma_f32_16x16x32_bf16 v[48:51], v[72:75], v[100:103], v[36:39]
	v_mfma_f32_16x16x32_bf16 v[44:47], v[0:3], v[108:111], v[40:43]
	v_mfma_f32_16x16x32_bf16 v[40:43], v[72:75], v[108:111], v[130:133]
	v_mfma_f32_16x16x32_bf16 v[36:39], v[0:3], v[116:119], v[150:153]
	v_mfma_f32_16x16x32_bf16 v[32:35], v[72:75], v[116:119], v[52:55]
	v_mfma_f32_16x16x32_bf16 v[8:11], v[0:3], v[124:127], v[8:11]
	v_mfma_f32_16x16x32_bf16 v[0:3], v[72:75], v[124:127], v[60:63]
	s_setprio 0
	s_setprio 1
	v_mfma_f32_16x16x32_bf16 v[4:7], v[88:91], v[96:99], v[4:7]
	v_mfma_f32_16x16x32_bf16 v[12:15], v[92:95], v[96:99], v[12:15]
	v_mfma_f32_16x16x32_bf16 v[16:19], v[88:91], v[104:107], v[16:19]
	v_mfma_f32_16x16x32_bf16 v[20:23], v[92:95], v[104:107], v[20:23]
	v_mfma_f32_16x16x32_bf16 v[72:75], v[88:91], v[112:115], v[24:27]
	v_mfma_f32_16x16x32_bf16 v[76:79], v[92:95], v[112:115], v[28:31]
	v_mfma_f32_16x16x32_bf16 v[64:67], v[88:91], v[120:123], v[64:67]
	v_mfma_f32_16x16x32_bf16 v[68:71], v[92:95], v[120:123], v[68:71]
	v_mfma_f32_16x16x32_bf16 v[60:63], v[80:83], v[100:103], v[4:7]
	v_mfma_f32_16x16x32_bf16 v[52:55], v[84:87], v[100:103], v[12:15]
	v_mfma_f32_16x16x32_bf16 v[28:31], v[80:83], v[108:111], v[16:19]
	v_mfma_f32_16x16x32_bf16 v[24:27], v[84:87], v[108:111], v[20:23]
	v_mfma_f32_16x16x32_bf16 v[20:23], v[80:83], v[116:119], v[72:75]
	v_mfma_f32_16x16x32_bf16 v[16:19], v[84:87], v[116:119], v[76:79]
	v_mfma_f32_16x16x32_bf16 v[12:15], v[80:83], v[124:127], v[64:67]
	v_mfma_f32_16x16x32_bf16 v[4:7], v[84:87], v[124:127], v[68:71]
	s_setprio 0
	v_cmp_gt_u32_e32 vcc, s92, v136
	s_barrier
	s_and_saveexec_b64 s[66:67], vcc
	s_cbranch_execz .LBB0_468
	s_barrier

.LBB0_521:
	ds_read_b128 v[140:143], v138
	ds_read_b128 v[144:147], v138 offset:1024
	ds_read_b128 v[148:151], v138 offset:2048
	ds_read_b128 v[152:155], v138 offset:3072
	ds_read_b128 v[156:159], v193
	ds_read_b128 v[160:163], v193 offset:1024
	ds_read_b128 v[194:197], v192
	ds_read_b128 v[198:201], v192 offset:1024
	ds_read_b128 v[202:205], v191
	ds_read_b128 v[206:209], v191 offset:1024
	ds_read_b128 v[210:213], v190
	ds_read_b128 v[214:217], v190 offset:1024
	s_waitcnt lgkmcnt(8)
	s_waitcnt vmcnt(10)
	s_barrier
	s_waitcnt lgkmcnt(0)
	s_setprio 1
	s_waitcnt lgkmcnt(0)
	v_mfma_f32_16x16x32_bf16 v[124:127], v[140:143], v[156:159], v[124:127]
	v_mfma_f32_16x16x32_bf16 v[120:123], v[148:151], v[156:159], v[120:123]
	v_mfma_f32_16x16x32_bf16 v[116:119], v[140:143], v[194:197], v[116:119]
	v_mfma_f32_16x16x32_bf16 v[112:115], v[148:151], v[194:197], v[112:115]
	v_mfma_f32_16x16x32_bf16 v[108:111], v[140:143], v[202:205], v[108:111]
	v_mfma_f32_16x16x32_bf16 v[104:107], v[148:151], v[202:205], v[104:107]
	v_mfma_f32_16x16x32_bf16 v[100:103], v[140:143], v[210:213], v[100:103]
	v_mfma_f32_16x16x32_bf16 v[96:99], v[148:151], v[210:213], v[96:99]
	v_mfma_f32_16x16x32_bf16 v[124:127], v[144:147], v[160:163], v[124:127]
	v_mfma_f32_16x16x32_bf16 v[120:123], v[152:155], v[160:163], v[120:123]
	v_mfma_f32_16x16x32_bf16 v[116:119], v[144:147], v[198:201], v[116:119]
	v_mfma_f32_16x16x32_bf16 v[112:115], v[152:155], v[198:201], v[112:115]
	v_mfma_f32_16x16x32_bf16 v[108:111], v[144:147], v[206:209], v[108:111]
	v_mfma_f32_16x16x32_bf16 v[104:107], v[152:155], v[206:209], v[104:107]
	v_mfma_f32_16x16x32_bf16 v[100:103], v[144:147], v[214:217], v[100:103]
	v_mfma_f32_16x16x32_bf16 v[96:99], v[152:155], v[214:217], v[96:99]
	s_setprio 0
	s_barrier
	v_readfirstlane_b32 s36, v189
	v_lshl_add_u64 v[234:235], s[58:59], 0, v[164:165]
	s_mov_b32 m0, s36
	v_readfirstlane_b32 s36, v188
	ds_read_b128 v[218:221], v135
	ds_read_b128 v[222:225], v135 offset:1024
	ds_read_b128 v[226:229], v135 offset:2048
	ds_read_b128 v[230:233], v135 offset:3072
	global_load_lds_dwordx4 v[234:235], off
	v_lshl_add_u64 v[236:237], v[234:235], 0, s[2:3]
	s_mov_b32 m0, s36
	s_nop 0
	global_load_lds_dwordx4 v[236:237], off
	v_readfirstlane_b32 s36, v169
	v_lshl_add_u64 v[236:237], v[128:129], 0, s[22:23]
	s_mov_b32 m0, s36
	v_readfirstlane_b32 s36, v187
	global_load_lds_dwordx4 v[236:237], off
	v_lshl_add_u64 v[236:237], v[128:129], 0, s[24:25]
	s_mov_b32 m0, s36
	s_nop 0
	global_load_lds_dwordx4 v[236:237], off
	s_waitcnt vmcnt(12)
	s_barrier
	s_waitcnt lgkmcnt(0)
	s_setprio 1
	s_waitcnt lgkmcnt(0)
	v_mfma_f32_16x16x32_bf16 v[92:95], v[218:221], v[156:159], v[92:95]
	v_mfma_f32_16x16x32_bf16 v[88:91], v[226:229], v[156:159], v[88:91]
	v_mfma_f32_16x16x32_bf16 v[84:87], v[218:221], v[194:197], v[84:87]
	v_mfma_f32_16x16x32_bf16 v[80:83], v[226:229], v[194:197], v[80:83]
	v_mfma_f32_16x16x32_bf16 v[76:79], v[218:221], v[202:205], v[76:79]
	v_mfma_f32_16x16x32_bf16 v[72:75], v[226:229], v[202:205], v[72:75]
	v_mfma_f32_16x16x32_bf16 v[68:71], v[218:221], v[210:213], v[68:71]
	v_mfma_f32_16x16x32_bf16 v[64:67], v[226:229], v[210:213], v[64:67]
	v_mfma_f32_16x16x32_bf16 v[92:95], v[222:225], v[160:163], v[92:95]
	v_mfma_f32_16x16x32_bf16 v[88:91], v[230:233], v[160:163], v[88:91]
	v_mfma_f32_16x16x32_bf16 v[84:87], v[222:225], v[198:201], v[84:87]
	v_mfma_f32_16x16x32_bf16 v[80:83], v[230:233], v[198:201], v[80:83]
	v_mfma_f32_16x16x32_bf16 v[76:79], v[222:225], v[206:209], v[76:79]
	v_mfma_f32_16x16x32_bf16 v[72:75], v[230:233], v[206:209], v[72:75]
	v_mfma_f32_16x16x32_bf16 v[68:71], v[222:225], v[214:217], v[68:71]
	v_mfma_f32_16x16x32_bf16 v[64:67], v[230:233], v[214:217], v[64:67]
	s_setprio 0
	s_barrier
	ds_read_b128 v[156:159], v193 offset:16384
	ds_read_b128 v[160:163], v193 offset:17408
	ds_read_b128 v[194:197], v192 offset:16384
	ds_read_b128 v[198:201], v192 offset:17408
	ds_read_b128 v[202:205], v191 offset:16384
	ds_read_b128 v[206:209], v191 offset:17408
	ds_read_b128 v[210:213], v190 offset:16384
	ds_read_b128 v[214:217], v190 offset:17408
	v_readfirstlane_b32 s36, v186
	v_lshl_add_u64 v[236:237], v[234:235], 0, s[6:7]
	s_mov_b32 m0, s36
	v_readfirstlane_b32 s36, v185
	global_load_lds_dwordx4 v[236:237], off
	v_lshl_add_u64 v[236:237], v[234:235], 0, s[8:9]
	s_mov_b32 m0, s36
	s_nop 0
	global_load_lds_dwordx4 v[236:237], off
	s_barrier
	s_waitcnt lgkmcnt(0)
	s_setprio 1
	s_waitcnt lgkmcnt(0)
	v_mfma_f32_16x16x32_bf16 v[60:63], v[140:143], v[156:159], v[60:63]
	v_mfma_f32_16x16x32_bf16 v[56:59], v[148:151], v[156:159], v[56:59]
	v_mfma_f32_16x16x32_bf16 v[52:55], v[140:143], v[194:197], v[52:55]
	v_mfma_f32_16x16x32_bf16 v[48:51], v[148:151], v[194:197], v[48:51]
	v_mfma_f32_16x16x32_bf16 v[44:47], v[140:143], v[202:205], v[44:47]
	v_mfma_f32_16x16x32_bf16 v[40:43], v[148:151], v[202:205], v[40:43]
	v_mfma_f32_16x16x32_bf16 v[36:39], v[140:143], v[210:213], v[36:39]
	v_mfma_f32_16x16x32_bf16 v[32:35], v[148:151], v[210:213], v[32:35]
	v_mfma_f32_16x16x32_bf16 v[60:63], v[144:147], v[160:163], v[60:63]
	v_mfma_f32_16x16x32_bf16 v[56:59], v[152:155], v[160:163], v[56:59]
	v_mfma_f32_16x16x32_bf16 v[52:55], v[144:147], v[198:201], v[52:55]
	v_mfma_f32_16x16x32_bf16 v[48:51], v[152:155], v[198:201], v[48:51]
	v_mfma_f32_16x16x32_bf16 v[44:47], v[144:147], v[206:209], v[44:47]
	v_mfma_f32_16x16x32_bf16 v[40:43], v[152:155], v[206:209], v[40:43]
	v_mfma_f32_16x16x32_bf16 v[36:39], v[144:147], v[214:217], v[36:39]
	v_mfma_f32_16x16x32_bf16 v[32:35], v[152:155], v[214:217], v[32:35]
	s_setprio 0
	s_barrier
	v_readfirstlane_b32 s36, v184
	v_lshl_add_u64 v[142:143], v[128:129], 0, s[26:27]
	s_mov_b32 m0, s36
	v_readfirstlane_b32 s36, v183
	global_load_lds_dwordx4 v[142:143], off
	s_mov_b32 m0, s36
	s_nop 0
	global_load_lds_dwordx4 v[128:129], off
	s_waitcnt vmcnt(12)
	s_barrier
	s_setprio 1
	v_mfma_f32_16x16x32_bf16 v[28:31], v[218:221], v[156:159], v[28:31]
	v_mfma_f32_16x16x32_bf16 v[24:27], v[226:229], v[156:159], v[24:27]
	v_mfma_f32_16x16x32_bf16 v[20:23], v[218:221], v[194:197], v[20:23]
	v_mfma_f32_16x16x32_bf16 v[16:19], v[226:229], v[194:197], v[16:19]
	v_mfma_f32_16x16x32_bf16 v[12:15], v[218:221], v[202:205], v[12:15]
	v_mfma_f32_16x16x32_bf16 v[8:11], v[226:229], v[202:205], v[8:11]
	v_mfma_f32_16x16x32_bf16 v[4:7], v[218:221], v[210:213], v[4:7]
	v_mfma_f32_16x16x32_bf16 v[0:3], v[226:229], v[210:213], v[0:3]
	v_mfma_f32_16x16x32_bf16 v[28:31], v[222:225], v[160:163], v[28:31]
	v_mfma_f32_16x16x32_bf16 v[24:27], v[230:233], v[160:163], v[24:27]
	v_mfma_f32_16x16x32_bf16 v[20:23], v[222:225], v[198:201], v[20:23]
	v_mfma_f32_16x16x32_bf16 v[16:19], v[230:233], v[198:201], v[16:19]
	v_mfma_f32_16x16x32_bf16 v[12:15], v[222:225], v[206:209], v[12:15]
	v_mfma_f32_16x16x32_bf16 v[8:11], v[230:233], v[206:209], v[8:11]
	v_mfma_f32_16x16x32_bf16 v[4:7], v[222:225], v[214:217], v[4:7]
	v_mfma_f32_16x16x32_bf16 v[0:3], v[230:233], v[214:217], v[0:3]
	s_setprio 0
	s_barrier
	ds_read_b128 v[140:143], v130
	ds_read_b128 v[144:147], v130 offset:1024
	ds_read_b128 v[148:151], v130 offset:2048
	ds_read_b128 v[152:155], v130 offset:3072
	ds_read_b128 v[156:159], v193 offset:32768
	ds_read_b128 v[160:163], v193 offset:33792
	ds_read_b128 v[194:197], v192 offset:32768
	ds_read_b128 v[198:201], v192 offset:33792
	ds_read_b128 v[202:205], v191 offset:32768
	ds_read_b128 v[206:209], v191 offset:33792
	ds_read_b128 v[210:213], v190 offset:32768
	ds_read_b128 v[214:217], v190 offset:33792
	s_waitcnt lgkmcnt(8)
	s_waitcnt vmcnt(10)
	s_barrier
	s_waitcnt lgkmcnt(0)
	s_setprio 1
	s_waitcnt lgkmcnt(0)
	v_mfma_f32_16x16x32_bf16 v[124:127], v[140:143], v[156:159], v[124:127]
	v_mfma_f32_16x16x32_bf16 v[120:123], v[148:151], v[156:159], v[120:123]
	v_mfma_f32_16x16x32_bf16 v[116:119], v[140:143], v[194:197], v[116:119]
	v_mfma_f32_16x16x32_bf16 v[112:115], v[148:151], v[194:197], v[112:115]
	v_mfma_f32_16x16x32_bf16 v[108:111], v[140:143], v[202:205], v[108:111]
	v_mfma_f32_16x16x32_bf16 v[104:107], v[148:151], v[202:205], v[104:107]
	v_mfma_f32_16x16x32_bf16 v[100:103], v[140:143], v[210:213], v[100:103]
	v_mfma_f32_16x16x32_bf16 v[96:99], v[148:151], v[210:213], v[96:99]
	v_mfma_f32_16x16x32_bf16 v[124:127], v[144:147], v[160:163], v[124:127]
	v_mfma_f32_16x16x32_bf16 v[120:123], v[152:155], v[160:163], v[120:123]
	v_mfma_f32_16x16x32_bf16 v[116:119], v[144:147], v[198:201], v[116:119]
	v_mfma_f32_16x16x32_bf16 v[112:115], v[152:155], v[198:201], v[112:115]
	v_mfma_f32_16x16x32_bf16 v[108:111], v[144:147], v[206:209], v[108:111]
	v_mfma_f32_16x16x32_bf16 v[104:107], v[152:155], v[206:209], v[104:107]
	v_mfma_f32_16x16x32_bf16 v[100:103], v[144:147], v[214:217], v[100:103]
	v_mfma_f32_16x16x32_bf16 v[96:99], v[152:155], v[214:217], v[96:99]
	s_setprio 0
	s_barrier
	v_readfirstlane_b32 s36, v182
	v_lshl_add_u64 v[234:235], s[46:47], 0, v[164:165]
	s_mov_b32 m0, s36
	v_readfirstlane_b32 s36, v181
	ds_read_b128 v[218:221], v132
	ds_read_b128 v[222:225], v132 offset:1024
	ds_read_b128 v[226:229], v132 offset:2048
	ds_read_b128 v[230:233], v132 offset:3072
	global_load_lds_dwordx4 v[234:235], off
	v_lshl_add_u64 v[236:237], v[234:235], 0, s[2:3]
	s_mov_b32 m0, s36
	s_nop 0
	global_load_lds_dwordx4 v[236:237], off
	v_readfirstlane_b32 s36, v177
	v_lshl_add_u64 v[236:237], v[128:129], 0, s[28:29]
	s_mov_b32 m0, s36
	v_readfirstlane_b32 s36, v175
	global_load_lds_dwordx4 v[236:237], off
	v_lshl_add_u64 v[236:237], v[128:129], 0, s[30:31]
	s_mov_b32 m0, s36
	s_nop 0
	global_load_lds_dwordx4 v[236:237], off
	s_waitcnt vmcnt(12)
	s_barrier
	s_waitcnt lgkmcnt(0)
	s_setprio 1
	s_waitcnt lgkmcnt(0)
	v_mfma_f32_16x16x32_bf16 v[92:95], v[218:221], v[156:159], v[92:95]
	v_mfma_f32_16x16x32_bf16 v[88:91], v[226:229], v[156:159], v[88:91]
	v_mfma_f32_16x16x32_bf16 v[84:87], v[218:221], v[194:197], v[84:87]
	v_mfma_f32_16x16x32_bf16 v[80:83], v[226:229], v[194:197], v[80:83]
	v_mfma_f32_16x16x32_bf16 v[76:79], v[218:221], v[202:205], v[76:79]
	v_mfma_f32_16x16x32_bf16 v[72:75], v[226:229], v[202:205], v[72:75]
	v_mfma_f32_16x16x32_bf16 v[68:71], v[218:221], v[210:213], v[68:71]
	v_mfma_f32_16x16x32_bf16 v[64:67], v[226:229], v[210:213], v[64:67]
	v_mfma_f32_16x16x32_bf16 v[92:95], v[222:225], v[160:163], v[92:95]
	v_mfma_f32_16x16x32_bf16 v[88:91], v[230:233], v[160:163], v[88:91]
	v_mfma_f32_16x16x32_bf16 v[84:87], v[222:225], v[198:201], v[84:87]
	v_mfma_f32_16x16x32_bf16 v[80:83], v[230:233], v[198:201], v[80:83]
	v_mfma_f32_16x16x32_bf16 v[76:79], v[222:225], v[206:209], v[76:79]
	v_mfma_f32_16x16x32_bf16 v[72:75], v[230:233], v[206:209], v[72:75]
	v_mfma_f32_16x16x32_bf16 v[68:71], v[222:225], v[214:217], v[68:71]
	v_mfma_f32_16x16x32_bf16 v[64:67], v[230:233], v[214:217], v[64:67]
	s_setprio 0
	s_barrier
	ds_read_b128 v[156:159], v193 offset:49152
	ds_read_b128 v[160:163], v193 offset:50176
	ds_read_b128 v[194:197], v192 offset:49152
	ds_read_b128 v[198:201], v192 offset:50176
	ds_read_b128 v[202:205], v191 offset:49152
	ds_read_b128 v[206:209], v191 offset:50176
	ds_read_b128 v[210:213], v190 offset:49152
	ds_read_b128 v[214:217], v190 offset:50176
	v_readfirstlane_b32 s36, v173
	v_lshl_add_u64 v[236:237], v[234:235], 0, s[6:7]
	s_mov_b32 m0, s36
	v_readfirstlane_b32 s36, v171
	global_load_lds_dwordx4 v[236:237], off
	v_lshl_add_u64 v[236:237], v[234:235], 0, s[8:9]
	s_mov_b32 m0, s36
	s_nop 0
	global_load_lds_dwordx4 v[236:237], off
	s_barrier
	s_waitcnt lgkmcnt(0)
	s_setprio 1
	s_waitcnt lgkmcnt(0)
	v_mfma_f32_16x16x32_bf16 v[60:63], v[140:143], v[156:159], v[60:63]
	v_mfma_f32_16x16x32_bf16 v[56:59], v[148:151], v[156:159], v[56:59]
	v_mfma_f32_16x16x32_bf16 v[52:55], v[140:143], v[194:197], v[52:55]
	v_mfma_f32_16x16x32_bf16 v[48:51], v[148:151], v[194:197], v[48:51]
	v_mfma_f32_16x16x32_bf16 v[44:47], v[140:143], v[202:205], v[44:47]
	v_mfma_f32_16x16x32_bf16 v[40:43], v[148:151], v[202:205], v[40:43]
	v_mfma_f32_16x16x32_bf16 v[36:39], v[140:143], v[210:213], v[36:39]
	v_mfma_f32_16x16x32_bf16 v[32:35], v[148:151], v[210:213], v[32:35]
	v_mfma_f32_16x16x32_bf16 v[60:63], v[144:147], v[160:163], v[60:63]
	v_mfma_f32_16x16x32_bf16 v[56:59], v[152:155], v[160:163], v[56:59]
	v_mfma_f32_16x16x32_bf16 v[52:55], v[144:147], v[198:201], v[52:55]
	v_mfma_f32_16x16x32_bf16 v[48:51], v[152:155], v[198:201], v[48:51]
	v_mfma_f32_16x16x32_bf16 v[44:47], v[144:147], v[206:209], v[44:47]
	v_mfma_f32_16x16x32_bf16 v[40:43], v[152:155], v[206:209], v[40:43]
	v_mfma_f32_16x16x32_bf16 v[36:39], v[144:147], v[214:217], v[36:39]
	v_mfma_f32_16x16x32_bf16 v[32:35], v[152:155], v[214:217], v[32:35]
	s_setprio 0
	s_barrier
	v_lshl_add_u64 v[128:129], v[128:129], 0, s[34:35]
	v_readfirstlane_b32 s36, v137
	v_lshl_add_u64 v[142:143], v[128:129], 0, s[18:19]
	s_mov_b32 m0, s36
	v_readfirstlane_b32 s36, v136
	global_load_lds_dwordx4 v[142:143], off
	v_lshl_add_u64 v[142:143], v[128:129], 0, s[20:21]
	s_mov_b32 m0, s36
	s_nop 0
	global_load_lds_dwordx4 v[142:143], off
	s_waitcnt vmcnt(12)
	s_barrier
	s_setprio 1
	v_mfma_f32_16x16x32_bf16 v[28:31], v[218:221], v[156:159], v[28:31]
	v_mfma_f32_16x16x32_bf16 v[24:27], v[226:229], v[156:159], v[24:27]
	v_mfma_f32_16x16x32_bf16 v[20:23], v[218:221], v[194:197], v[20:23]
	v_mfma_f32_16x16x32_bf16 v[16:19], v[226:229], v[194:197], v[16:19]
	v_mfma_f32_16x16x32_bf16 v[12:15], v[218:221], v[202:205], v[12:15]
	v_mfma_f32_16x16x32_bf16 v[8:11], v[226:229], v[202:205], v[8:11]
	v_mfma_f32_16x16x32_bf16 v[4:7], v[218:221], v[210:213], v[4:7]
	v_mfma_f32_16x16x32_bf16 v[0:3], v[226:229], v[210:213], v[0:3]
	v_mfma_f32_16x16x32_bf16 v[28:31], v[222:225], v[160:163], v[28:31]
	v_mfma_f32_16x16x32_bf16 v[24:27], v[230:233], v[160:163], v[24:27]
	v_mfma_f32_16x16x32_bf16 v[20:23], v[222:225], v[198:201], v[20:23]
	v_mfma_f32_16x16x32_bf16 v[16:19], v[230:233], v[198:201], v[16:19]
	v_mfma_f32_16x16x32_bf16 v[12:15], v[222:225], v[206:209], v[12:15]
	v_mfma_f32_16x16x32_bf16 v[8:11], v[230:233], v[206:209], v[8:11]
	v_mfma_f32_16x16x32_bf16 v[4:7], v[222:225], v[214:217], v[4:7]
	v_mfma_f32_16x16x32_bf16 v[0:3], v[230:233], v[214:217], v[0:3]
	s_setprio 0
	s_add_i32 s14, s14, 2
	s_add_u32 s46, s46, s56
	s_addc_u32 s47, s47, s57
	s_add_u32 s58, s58, s56
	s_addc_u32 s59, s59, s57
	s_cmp_lt_u32 s14, 28
	s_barrier
	s_cbranch_scc1 .LBB0_521
	s_lshl_b32 s14, s60, 3
	s_or_b32 s80, s61, s14
	s_lshl_b32 s46, s80, 8
	v_lshlrev_b32_e32 v128, 3, v131
	v_lshlrev_b32_e32 v129, 5, v131
	s_or_b32 s14, s46, 0x80
	v_and_b32_e32 v128, 0x7fff0, v128
	v_and_b32_e32 v129, 32, v129
	s_lshl_b64 s[56:57], s[14:15], 13
	v_add_u32_e32 v129, v129, v134
	v_add_lshl_u32 v128, v133, v128, 13
	s_add_u32 s56, s40, s56
	v_lshl_add_u32 v164, v129, 1, v128
	s_addc_u32 s57, s41, s57
	v_lshl_add_u64 v[128:129], s[56:57], 0, v[164:165]
	v_readfirstlane_b32 s14, v137
	ds_read_b128 v[140:143], v138
	ds_read_b128 v[144:147], v138 offset:1024
	ds_read_b128 v[148:151], v138 offset:2048
	ds_read_b128 v[152:155], v138 offset:3072
	ds_read_b128 v[156:159], v193
	ds_read_b128 v[160:163], v193 offset:1024
	ds_read_b128 v[194:197], v192
	ds_read_b128 v[198:201], v192 offset:1024
	ds_read_b128 v[202:205], v191
	ds_read_b128 v[206:209], v191 offset:1024
	ds_read_b128 v[210:213], v190
	ds_read_b128 v[214:217], v190 offset:1024
	v_lshl_add_u64 v[138:139], v[128:129], 0, s[38:39]
	s_mov_b32 m0, s14
	v_readfirstlane_b32 s14, v136
	global_load_lds_dwordx4 v[138:139], off
	v_lshl_add_u64 v[128:129], v[128:129], 0, s[44:45]
	s_mov_b32 m0, s14
	s_mov_b32 s47, s15
	global_load_lds_dwordx4 v[128:129], off
	s_waitcnt vmcnt(10)
	s_barrier
	s_waitcnt lgkmcnt(0)
	s_setprio 1
	s_waitcnt lgkmcnt(0)
	v_mfma_f32_16x16x32_bf16 v[124:127], v[140:143], v[156:159], v[124:127]
	v_mfma_f32_16x16x32_bf16 v[120:123], v[148:151], v[156:159], v[120:123]
	v_mfma_f32_16x16x32_bf16 v[116:119], v[140:143], v[194:197], v[116:119]
	v_mfma_f32_16x16x32_bf16 v[112:115], v[148:151], v[194:197], v[112:115]
	v_mfma_f32_16x16x32_bf16 v[108:111], v[140:143], v[202:205], v[108:111]
	v_mfma_f32_16x16x32_bf16 v[104:107], v[148:151], v[202:205], v[104:107]
	v_mfma_f32_16x16x32_bf16 v[100:103], v[140:143], v[210:213], v[100:103]
	v_mfma_f32_16x16x32_bf16 v[96:99], v[148:151], v[210:213], v[96:99]
	v_mfma_f32_16x16x32_bf16 v[124:127], v[144:147], v[160:163], v[124:127]
	v_mfma_f32_16x16x32_bf16 v[120:123], v[152:155], v[160:163], v[120:123]
	v_mfma_f32_16x16x32_bf16 v[116:119], v[144:147], v[198:201], v[116:119]
	v_mfma_f32_16x16x32_bf16 v[112:115], v[152:155], v[198:201], v[112:115]
	v_mfma_f32_16x16x32_bf16 v[108:111], v[144:147], v[206:209], v[108:111]
	v_mfma_f32_16x16x32_bf16 v[104:107], v[152:155], v[206:209], v[104:107]
	v_mfma_f32_16x16x32_bf16 v[100:103], v[144:147], v[214:217], v[100:103]
	v_mfma_f32_16x16x32_bf16 v[96:99], v[152:155], v[214:217], v[96:99]
	s_setprio 0
	s_barrier
	ds_read_b128 v[136:139], v135
	ds_read_b128 v[218:221], v135 offset:1024
	ds_read_b128 v[222:225], v135 offset:2048
	ds_read_b128 v[226:229], v135 offset:3072
	s_barrier
	s_waitcnt lgkmcnt(0)
	s_setprio 1
	s_waitcnt lgkmcnt(0)
	v_mfma_f32_16x16x32_bf16 v[92:95], v[136:139], v[156:159], v[92:95]
	v_mfma_f32_16x16x32_bf16 v[84:87], v[136:139], v[194:197], v[84:87]
	v_mfma_f32_16x16x32_bf16 v[80:83], v[222:225], v[194:197], v[80:83]
	v_mfma_f32_16x16x32_bf16 v[88:91], v[222:225], v[156:159], v[88:91]
	v_mfma_f32_16x16x32_bf16 v[76:79], v[136:139], v[202:205], v[76:79]
	v_mfma_f32_16x16x32_bf16 v[72:75], v[222:225], v[202:205], v[72:75]
	v_mfma_f32_16x16x32_bf16 v[68:71], v[136:139], v[210:213], v[68:71]
	v_mfma_f32_16x16x32_bf16 v[64:67], v[222:225], v[210:213], v[64:67]
	v_mfma_f32_16x16x32_bf16 v[156:159], v[218:221], v[160:163], v[92:95]
	v_mfma_f32_16x16x32_bf16 v[194:197], v[218:221], v[198:201], v[84:87]
	v_mfma_f32_16x16x32_bf16 v[198:201], v[226:229], v[198:201], v[80:83]
	v_mfma_f32_16x16x32_bf16 v[160:163], v[226:229], v[160:163], v[88:91]
	v_mfma_f32_16x16x32_bf16 v[202:205], v[218:221], v[206:209], v[76:79]
	v_mfma_f32_16x16x32_bf16 v[206:209], v[226:229], v[206:209], v[72:75]
	v_mfma_f32_16x16x32_bf16 v[210:213], v[218:221], v[214:217], v[68:71]
	v_mfma_f32_16x16x32_bf16 v[214:217], v[226:229], v[214:217], v[64:67]
	s_setprio 0
	s_barrier
	s_nop 0
	ds_read_b128 v[64:67], v193 offset:16384
	ds_read_b128 v[68:71], v193 offset:17408
	ds_read_b128 v[72:75], v192 offset:16384
	ds_read_b128 v[76:79], v192 offset:17408
	ds_read_b128 v[80:83], v191 offset:16384
	ds_read_b128 v[84:87], v191 offset:17408
	ds_read_b128 v[88:91], v190 offset:16384
	ds_read_b128 v[92:95], v190 offset:17408
	s_waitcnt vmcnt(4)
	s_barrier
	s_waitcnt lgkmcnt(0)
	s_setprio 1
	s_waitcnt lgkmcnt(0)
	v_mfma_f32_16x16x32_bf16 v[60:63], v[140:143], v[64:67], v[60:63]
	v_mfma_f32_16x16x32_bf16 v[56:59], v[148:151], v[64:67], v[56:59]
	v_mfma_f32_16x16x32_bf16 v[52:55], v[140:143], v[72:75], v[52:55]
	v_mfma_f32_16x16x32_bf16 v[48:51], v[148:151], v[72:75], v[48:51]
	v_mfma_f32_16x16x32_bf16 v[230:233], v[140:143], v[80:83], v[44:47]
	v_mfma_f32_16x16x32_bf16 v[234:237], v[148:151], v[80:83], v[40:43]
	v_mfma_f32_16x16x32_bf16 v[140:143], v[140:143], v[88:91], v[36:39]
	v_mfma_f32_16x16x32_bf16 v[148:151], v[148:151], v[88:91], v[32:35]
	v_mfma_f32_16x16x32_bf16 v[32:35], v[144:147], v[68:71], v[60:63]
	v_mfma_f32_16x16x32_bf16 v[36:39], v[152:155], v[68:71], v[56:59]
	v_mfma_f32_16x16x32_bf16 v[40:43], v[144:147], v[76:79], v[52:55]
	v_mfma_f32_16x16x32_bf16 v[44:47], v[152:155], v[76:79], v[48:51]
	v_mfma_f32_16x16x32_bf16 v[48:51], v[144:147], v[84:87], v[230:233]
	v_mfma_f32_16x16x32_bf16 v[52:55], v[152:155], v[84:87], v[234:237]
	v_mfma_f32_16x16x32_bf16 v[56:59], v[144:147], v[92:95], v[140:143]
	v_mfma_f32_16x16x32_bf16 v[60:63], v[152:155], v[92:95], v[148:151]
	s_setprio 0
	s_setprio 1
	v_mfma_f32_16x16x32_bf16 v[28:31], v[136:139], v[64:67], v[28:31]
	v_mfma_f32_16x16x32_bf16 v[24:27], v[222:225], v[64:67], v[24:27]
	v_mfma_f32_16x16x32_bf16 v[20:23], v[136:139], v[72:75], v[20:23]
	v_mfma_f32_16x16x32_bf16 v[64:67], v[222:225], v[72:75], v[16:19]
	v_mfma_f32_16x16x32_bf16 v[12:15], v[136:139], v[80:83], v[12:15]
	v_mfma_f32_16x16x32_bf16 v[8:11], v[222:225], v[80:83], v[8:11]
	v_mfma_f32_16x16x32_bf16 v[72:75], v[136:139], v[88:91], v[4:7]
	v_mfma_f32_16x16x32_bf16 v[80:83], v[222:225], v[88:91], v[0:3]
	v_mfma_f32_16x16x32_bf16 v[0:3], v[218:221], v[68:71], v[28:31]
	v_mfma_f32_16x16x32_bf16 v[4:7], v[226:229], v[68:71], v[24:27]
	v_mfma_f32_16x16x32_bf16 v[16:19], v[218:221], v[76:79], v[20:23]
	v_mfma_f32_16x16x32_bf16 v[20:23], v[226:229], v[76:79], v[64:67]
	v_mfma_f32_16x16x32_bf16 v[24:27], v[218:221], v[84:87], v[12:15]
	v_mfma_f32_16x16x32_bf16 v[28:31], v[226:229], v[84:87], v[8:11]
	v_mfma_f32_16x16x32_bf16 v[64:67], v[218:221], v[92:95], v[72:75]
	v_mfma_f32_16x16x32_bf16 v[68:71], v[226:229], v[92:95], v[80:83]
	s_setprio 0
	s_barrier
	ds_read_b128 v[12:15], v130
	ds_read_b128 v[8:11], v130 offset:1024
	ds_read_b128 v[76:79], v130 offset:2048
	ds_read_b128 v[72:75], v130 offset:3072
	ds_read_b128 v[140:143], v193 offset:32768
	ds_read_b128 v[148:151], v193 offset:33792
	ds_read_b128 v[218:221], v192 offset:32768
	ds_read_b128 v[222:225], v192 offset:33792
	ds_read_b128 v[226:229], v191 offset:32768
	ds_read_b128 v[230:233], v191 offset:33792
	ds_read_b128 v[234:237], v190 offset:32768
	ds_read_b128 v[238:241], v190 offset:33792
	s_waitcnt vmcnt(2)
	s_barrier
	s_waitcnt lgkmcnt(0)
	s_setprio 1
	s_waitcnt lgkmcnt(0)
	v_mfma_f32_16x16x32_bf16 v[80:83], v[12:15], v[140:143], v[124:127]
	v_mfma_f32_16x16x32_bf16 v[84:87], v[76:79], v[140:143], v[120:123]
	v_mfma_f32_16x16x32_bf16 v[88:91], v[12:15], v[218:221], v[116:119]
	v_mfma_f32_16x16x32_bf16 v[92:95], v[76:79], v[218:221], v[112:115]
	v_mfma_f32_16x16x32_bf16 v[108:111], v[12:15], v[226:229], v[108:111]
	v_mfma_f32_16x16x32_bf16 v[104:107], v[76:79], v[226:229], v[104:107]
	v_mfma_f32_16x16x32_bf16 v[100:103], v[12:15], v[234:237], v[100:103]
	v_mfma_f32_16x16x32_bf16 v[96:99], v[76:79], v[234:237], v[96:99]
	v_mfma_f32_16x16x32_bf16 v[152:155], v[8:11], v[148:151], v[80:83]
	v_mfma_f32_16x16x32_bf16 v[144:147], v[72:75], v[148:151], v[84:87]
	v_mfma_f32_16x16x32_bf16 v[136:139], v[8:11], v[222:225], v[88:91]
	v_mfma_f32_16x16x32_bf16 v[128:131], v[72:75], v[222:225], v[92:95]
	v_mfma_f32_16x16x32_bf16 v[120:123], v[8:11], v[230:233], v[108:111]
	v_mfma_f32_16x16x32_bf16 v[112:115], v[72:75], v[230:233], v[104:107]
	v_mfma_f32_16x16x32_bf16 v[104:107], v[8:11], v[238:241], v[100:103]
	v_mfma_f32_16x16x32_bf16 v[96:99], v[72:75], v[238:241], v[96:99]
	s_setprio 0
	s_barrier
	ds_read_b128 v[88:91], v132
	ds_read_b128 v[80:83], v132 offset:1024
	ds_read_b128 v[92:95], v132 offset:2048
	ds_read_b128 v[84:87], v132 offset:3072
	s_waitcnt vmcnt(0)
	s_barrier
	s_waitcnt lgkmcnt(0)
	s_setprio 1
	s_waitcnt lgkmcnt(0)
	v_mfma_f32_16x16x32_bf16 v[100:103], v[88:91], v[140:143], v[156:159]
	v_mfma_f32_16x16x32_bf16 v[108:111], v[92:95], v[140:143], v[160:163]
	v_mfma_f32_16x16x32_bf16 v[116:119], v[88:91], v[218:221], v[194:197]
	v_mfma_f32_16x16x32_bf16 v[124:127], v[92:95], v[218:221], v[198:201]
	v_mfma_f32_16x16x32_bf16 v[160:163], v[88:91], v[226:229], v[202:205]
	v_mfma_f32_16x16x32_bf16 v[194:197], v[92:95], v[226:229], v[206:209]
	v_mfma_f32_16x16x32_bf16 v[198:201], v[88:91], v[234:237], v[210:213]
	v_mfma_f32_16x16x32_bf16 v[202:205], v[92:95], v[234:237], v[214:217]
	v_mfma_f32_16x16x32_bf16 v[156:159], v[80:83], v[148:151], v[100:103]
	v_mfma_f32_16x16x32_bf16 v[148:151], v[84:87], v[148:151], v[108:111]
	v_mfma_f32_16x16x32_bf16 v[140:143], v[80:83], v[222:225], v[116:119]
	v_mfma_f32_16x16x32_bf16 v[132:135], v[84:87], v[222:225], v[124:127]
	v_mfma_f32_16x16x32_bf16 v[124:127], v[80:83], v[230:233], v[160:163]
	v_mfma_f32_16x16x32_bf16 v[116:119], v[84:87], v[230:233], v[194:197]
	v_mfma_f32_16x16x32_bf16 v[108:111], v[80:83], v[238:241], v[198:201]
	v_mfma_f32_16x16x32_bf16 v[100:103], v[84:87], v[238:241], v[202:205]
	s_setprio 0
	s_lshl_b64 s[56:57], s[46:47], 2
	s_barrier
	v_mbcnt_lo_u32_b32 v162, -1, 0
	v_mbcnt_hi_u32_b32 v162, -1, v162
	s_add_u32 s56, s87, s56
	v_add_u32_e32 v160, s64, v162
	s_addc_u32 s57, s88, s57
	v_and_b32_e32 v164, 0x100, v160
	v_and_b32_e32 v162, 15, v162
	v_lshl_add_u64 v[160:161], s[56:57], 0, v[164:165]
	v_lshlrev_b32_e32 v164, 2, v162
	v_lshl_add_u64 v[160:161], v[160:161], 0, v[164:165]
	global_load_dword v180, v[160:161], off
	global_load_dword v178, v[160:161], off offset:64
	global_load_dword v176, v[160:161], off offset:128
	global_load_dword v174, v[160:161], off offset:192
	global_load_dword v172, v[160:161], off offset:512
	global_load_dword v170, v[160:161], off offset:576
	global_load_dword v168, v[160:161], off offset:640
	global_load_dword v166, v[160:161], off offset:704
	v_mbcnt_lo_u32_b32 v194, -1, 0
	v_mbcnt_hi_u32_b32 v194, -1, v194
	s_cmp_lg_u32 s79, 0
	v_add_u32_e32 v160, s64, v194
	v_bfe_u32 v196, v160, 8, 1
	v_ashrrev_i32_e32 v199, 6, v160
	v_bfe_u32 v160, v194, 4, 2
	s_cselect_b64 s[56:57], -1, 0
	v_and_b32_e32 v197, 3, v199
	v_and_b32_e32 v195, 15, v194
	s_and_b64 vcc, exec, s[56:57]
	v_lshlrev_b32_e32 v198, 4, v160
	s_cbranch_vccz .LBB0_533
	s_lshl_b32 s14, s78, 22
	s_lshl_b32 s36, s80, 14
	s_add_i32 s36, s36, s14
	v_lshlrev_b32_e32 v160, 6, v195
	v_or3_b32 v160, s36, v160, v198
	v_lshl_add_u32 v160, v197, 20, v160
	v_lshl_or_b32 v164, v196, 12, v160
	s_waitcnt vmcnt(0)
	v_pk_mul_f32 v[160:161], v[154:155], v[180:181] op_sel_hi:[1,0]
	v_pk_mul_f32 v[200:201], v[146:147], v[180:181] op_sel_hi:[1,0]
	v_max_f32_e32 v160, 0, v160
	v_mul_f32_e32 v204, v160, v160
	v_max_f32_e32 v160, 0, v200
	v_pk_mul_f32 v[162:163], v[152:153], v[180:181] op_sel_hi:[1,0]
	v_mul_f32_e32 v200, v160, v160
	v_max_f32_e32 v160, 0, v161
	v_pk_mul_f32 v[202:203], v[144:145], v[180:181] op_sel_hi:[1,0]
	v_max_f32_e32 v162, 0, v162
	v_max_f32_e32 v163, 0, v163
	v_mul_f32_e32 v161, v160, v160
	v_max_f32_e32 v160, 0, v201
	v_mul_f32_e32 v162, v162, v162
	v_max_f32_e32 v202, 0, v202
	v_mul_f32_e32 v163, v163, v163
	v_max_f32_e32 v203, 0, v203
	v_mul_f32_e32 v201, v160, v160
	v_cvt_pk_bf16_f32 v160, v162, v163
	v_cvt_pk_bf16_f32 v161, v204, v161
	v_mul_f32_e32 v202, v202, v202
	v_mul_f32_e32 v203, v203, v203
	v_cvt_pk_bf16_f32 v162, v202, v203
	v_cvt_pk_bf16_f32 v163, v200, v201
	global_store_dwordx4 v164, v[160:163], s[0:1]
	v_pk_mul_f32 v[202:203], v[150:151], v[180:181] op_sel_hi:[1,0]
	v_lshl_add_u64 v[200:201], s[0:1], 0, v[164:165]
	v_pk_mul_f32 v[160:161], v[158:159], v[180:181] op_sel_hi:[1,0]
	v_pk_mul_f32 v[162:163], v[156:157], v[180:181] op_sel_hi:[1,0]
	v_max_f32_e32 v160, 0, v160
	v_mul_f32_e32 v206, v160, v160
	v_max_f32_e32 v160, 0, v202
	v_mul_f32_e32 v202, v160, v160
	v_max_f32_e32 v160, 0, v161
	v_pk_mul_f32 v[204:205], v[148:149], v[180:181] op_sel_hi:[1,0]
	v_max_f32_e32 v162, 0, v162
	v_max_f32_e32 v163, 0, v163
	v_mul_f32_e32 v161, v160, v160
	v_max_f32_e32 v160, 0, v203
	v_add_co_u32_e32 v200, vcc, s72, v200
	v_mul_f32_e32 v162, v162, v162
	v_max_f32_e32 v204, 0, v204
	v_mul_f32_e32 v163, v163, v163
	v_max_f32_e32 v205, 0, v205
	v_mul_f32_e32 v203, v160, v160
	v_cvt_pk_bf16_f32 v160, v162, v163
	v_cvt_pk_bf16_f32 v161, v206, v161
	v_addc_co_u32_e32 v201, vcc, 0, v201, vcc
	v_mul_f32_e32 v204, v204, v204
	v_mul_f32_e32 v205, v205, v205
	v_cvt_pk_bf16_f32 v162, v204, v205
	v_cvt_pk_bf16_f32 v163, v202, v203
	global_store_dwordx4 v[200:201], v[160:163], off
	v_pk_mul_f32 v[202:203], v[130:131], v[178:179] op_sel_hi:[1,0]
	v_pk_mul_f32 v[204:205], v[128:129], v[178:179] op_sel_hi:[1,0]
	v_pk_mul_f32 v[160:161], v[138:139], v[178:179] op_sel_hi:[1,0]
	v_pk_mul_f32 v[162:163], v[136:137], v[178:179] op_sel_hi:[1,0]
	v_max_f32_e32 v160, 0, v160
	v_mul_f32_e32 v206, v160, v160
	v_max_f32_e32 v160, 0, v202
	v_mul_f32_e32 v202, v160, v160
	v_max_f32_e32 v160, 0, v161
	v_max_f32_e32 v162, 0, v162
	v_max_f32_e32 v163, 0, v163
	v_mul_f32_e32 v161, v160, v160
	v_max_f32_e32 v160, 0, v203
	v_mul_f32_e32 v162, v162, v162
	v_max_f32_e32 v204, 0, v204
	v_mul_f32_e32 v163, v163, v163
	v_max_f32_e32 v205, 0, v205
	v_mul_f32_e32 v203, v160, v160
	v_cvt_pk_bf16_f32 v160, v162, v163
	v_cvt_pk_bf16_f32 v161, v206, v161
	v_mul_f32_e32 v204, v204, v204
	v_mul_f32_e32 v205, v205, v205
	v_cvt_pk_bf16_f32 v162, v204, v205
	v_cvt_pk_bf16_f32 v163, v202, v203
	global_store_dwordx4 v164, v[160:163], s[0:1] offset:1024
	v_pk_mul_f32 v[202:203], v[134:135], v[178:179] op_sel_hi:[1,0]
	v_pk_mul_f32 v[204:205], v[132:133], v[178:179] op_sel_hi:[1,0]
	v_pk_mul_f32 v[160:161], v[142:143], v[178:179] op_sel_hi:[1,0]
	v_pk_mul_f32 v[162:163], v[140:141], v[178:179] op_sel_hi:[1,0]
	v_max_f32_e32 v160, 0, v160
	v_mul_f32_e32 v206, v160, v160
	v_max_f32_e32 v160, 0, v202
	v_mul_f32_e32 v202, v160, v160
	v_max_f32_e32 v160, 0, v161
	v_max_f32_e32 v162, 0, v162
	v_max_f32_e32 v163, 0, v163
	v_mul_f32_e32 v161, v160, v160
	v_max_f32_e32 v160, 0, v203
	v_mul_f32_e32 v162, v162, v162
	v_max_f32_e32 v204, 0, v204
	v_mul_f32_e32 v163, v163, v163
	v_max_f32_e32 v205, 0, v205
	v_mul_f32_e32 v203, v160, v160
	v_cvt_pk_bf16_f32 v160, v162, v163
	v_cvt_pk_bf16_f32 v161, v206, v161
	v_mul_f32_e32 v204, v204, v204
	v_mul_f32_e32 v205, v205, v205
	v_cvt_pk_bf16_f32 v162, v204, v205
	v_cvt_pk_bf16_f32 v163, v202, v203
	global_store_dwordx4 v[200:201], v[160:163], off offset:1024
	v_pk_mul_f32 v[202:203], v[114:115], v[176:177] op_sel_hi:[1,0]
	v_pk_mul_f32 v[204:205], v[112:113], v[176:177] op_sel_hi:[1,0]
	v_pk_mul_f32 v[160:161], v[122:123], v[176:177] op_sel_hi:[1,0]
	v_pk_mul_f32 v[162:163], v[120:121], v[176:177] op_sel_hi:[1,0]
	v_max_f32_e32 v160, 0, v160
	v_mul_f32_e32 v206, v160, v160
	v_max_f32_e32 v160, 0, v202
	v_mul_f32_e32 v202, v160, v160
	v_max_f32_e32 v160, 0, v161
	v_max_f32_e32 v162, 0, v162
	v_max_f32_e32 v163, 0, v163
	v_mul_f32_e32 v161, v160, v160
	v_max_f32_e32 v160, 0, v203
	v_mul_f32_e32 v162, v162, v162
	v_max_f32_e32 v204, 0, v204
	v_mul_f32_e32 v163, v163, v163
	v_max_f32_e32 v205, 0, v205
	v_mul_f32_e32 v203, v160, v160
	v_cvt_pk_bf16_f32 v160, v162, v163
	v_cvt_pk_bf16_f32 v161, v206, v161
	v_mul_f32_e32 v204, v204, v204
	v_mul_f32_e32 v205, v205, v205
	v_cvt_pk_bf16_f32 v162, v204, v205
	v_cvt_pk_bf16_f32 v163, v202, v203
	global_store_dwordx4 v164, v[160:163], s[0:1] offset:2048
	v_pk_mul_f32 v[202:203], v[118:119], v[176:177] op_sel_hi:[1,0]
	v_pk_mul_f32 v[204:205], v[116:117], v[176:177] op_sel_hi:[1,0]
	v_pk_mul_f32 v[160:161], v[126:127], v[176:177] op_sel_hi:[1,0]
	v_pk_mul_f32 v[162:163], v[124:125], v[176:177] op_sel_hi:[1,0]
	v_max_f32_e32 v160, 0, v160
	v_mul_f32_e32 v206, v160, v160
	v_max_f32_e32 v160, 0, v202
	v_mul_f32_e32 v202, v160, v160
	v_max_f32_e32 v160, 0, v161
	v_max_f32_e32 v162, 0, v162
	v_max_f32_e32 v163, 0, v163
	v_mul_f32_e32 v161, v160, v160
	v_max_f32_e32 v160, 0, v203
	v_mul_f32_e32 v162, v162, v162
	v_max_f32_e32 v204, 0, v204
	v_mul_f32_e32 v163, v163, v163
	v_max_f32_e32 v205, 0, v205
	v_mul_f32_e32 v203, v160, v160
	v_cvt_pk_bf16_f32 v160, v162, v163
	v_cvt_pk_bf16_f32 v161, v206, v161
	v_mul_f32_e32 v204, v204, v204
	v_mul_f32_e32 v205, v205, v205
	v_cvt_pk_bf16_f32 v162, v204, v205
	v_cvt_pk_bf16_f32 v163, v202, v203
	global_store_dwordx4 v[200:201], v[160:163], off offset:2048
	v_pk_mul_f32 v[200:201], v[98:99], v[174:175] op_sel_hi:[1,0]
	v_pk_mul_f32 v[202:203], v[96:97], v[174:175] op_sel_hi:[1,0]
	v_pk_mul_f32 v[160:161], v[106:107], v[174:175] op_sel_hi:[1,0]
	v_pk_mul_f32 v[162:163], v[104:105], v[174:175] op_sel_hi:[1,0]
	v_max_f32_e32 v160, 0, v160
	v_mul_f32_e32 v204, v160, v160
	v_max_f32_e32 v160, 0, v200
	v_mul_f32_e32 v200, v160, v160
	v_max_f32_e32 v160, 0, v161
	v_max_f32_e32 v162, 0, v162
	v_max_f32_e32 v163, 0, v163
	v_mul_f32_e32 v161, v160, v160
	v_max_f32_e32 v160, 0, v201
	v_mul_f32_e32 v162, v162, v162
	v_max_f32_e32 v202, 0, v202
	v_mul_f32_e32 v163, v163, v163
	v_max_f32_e32 v203, 0, v203
	v_mul_f32_e32 v201, v160, v160
	v_cvt_pk_bf16_f32 v160, v162, v163
	v_cvt_pk_bf16_f32 v161, v204, v161
	v_mul_f32_e32 v202, v202, v202
	v_mul_f32_e32 v203, v203, v203
	v_cvt_pk_bf16_f32 v162, v202, v203
	v_cvt_pk_bf16_f32 v163, v200, v201
	global_store_dwordx4 v164, v[160:163], s[0:1] offset:3072
	v_pk_mul_f32 v[200:201], v[102:103], v[174:175] op_sel_hi:[1,0]
	v_pk_mul_f32 v[202:203], v[100:101], v[174:175] op_sel_hi:[1,0]
	v_pk_mul_f32 v[160:161], v[110:111], v[174:175] op_sel_hi:[1,0]
	v_pk_mul_f32 v[162:163], v[108:109], v[174:175] op_sel_hi:[1,0]
	v_max_f32_e32 v160, 0, v160
	v_mul_f32_e32 v204, v160, v160
	v_max_f32_e32 v160, 0, v200
	v_max_f32_e32 v162, 0, v162
	v_max_f32_e32 v163, 0, v163
	v_mul_f32_e32 v200, v160, v160
	v_max_f32_e32 v160, 0, v161
	v_mul_f32_e32 v162, v162, v162
	v_max_f32_e32 v202, 0, v202
	v_mul_f32_e32 v163, v163, v163
	v_max_f32_e32 v203, 0, v203
	v_mul_f32_e32 v161, v160, v160
	v_max_f32_e32 v160, 0, v201
	v_mul_f32_e32 v202, v202, v202
	v_mul_f32_e32 v203, v203, v203
	v_mul_f32_e32 v201, v160, v160
	v_cvt_pk_bf16_f32 v160, v162, v163
	v_cvt_pk_bf16_f32 v161, v204, v161
	v_cvt_pk_bf16_f32 v162, v202, v203
	v_cvt_pk_bf16_f32 v163, v200, v201
	v_add_u32_e32 v164, 0x80c00, v164
	s_cbranch_execnz .LBB0_525

.LBB0_561:
	ds_read_b128 v[162:165], v161
	ds_read_b128 v[166:169], v161 offset:1024
	ds_read_b128 v[170:173], v161 offset:2048
	ds_read_b128 v[174:177], v161 offset:3072
	ds_read_b128 v[178:181], v152
	ds_read_b128 v[182:185], v152 offset:1024
	ds_read_b128 v[186:189], v151
	ds_read_b128 v[190:193], v151 offset:1024
	ds_read_b128 v[194:197], v150
	ds_read_b128 v[198:201], v150 offset:1024
	ds_read_b128 v[202:205], v149
	ds_read_b128 v[206:209], v149 offset:1024
	s_waitcnt lgkmcnt(8)
	s_waitcnt vmcnt(10)
	s_barrier
	s_waitcnt lgkmcnt(0)
	s_setprio 1
	s_waitcnt lgkmcnt(0)
	v_mfma_f32_16x16x32_bf16 v[124:127], v[162:165], v[178:181], v[124:127]
	v_mfma_f32_16x16x32_bf16 v[120:123], v[170:173], v[178:181], v[120:123]
	v_mfma_f32_16x16x32_bf16 v[116:119], v[162:165], v[186:189], v[116:119]
	v_mfma_f32_16x16x32_bf16 v[112:115], v[170:173], v[186:189], v[112:115]
	v_mfma_f32_16x16x32_bf16 v[108:111], v[162:165], v[194:197], v[108:111]
	v_mfma_f32_16x16x32_bf16 v[104:107], v[170:173], v[194:197], v[104:107]
	v_mfma_f32_16x16x32_bf16 v[100:103], v[162:165], v[202:205], v[100:103]
	v_mfma_f32_16x16x32_bf16 v[96:99], v[170:173], v[202:205], v[96:99]
	v_mfma_f32_16x16x32_bf16 v[124:127], v[166:169], v[182:185], v[124:127]
	v_mfma_f32_16x16x32_bf16 v[120:123], v[174:177], v[182:185], v[120:123]
	v_mfma_f32_16x16x32_bf16 v[116:119], v[166:169], v[190:193], v[116:119]
	v_mfma_f32_16x16x32_bf16 v[112:115], v[174:177], v[190:193], v[112:115]
	v_mfma_f32_16x16x32_bf16 v[108:111], v[166:169], v[198:201], v[108:111]
	v_mfma_f32_16x16x32_bf16 v[104:107], v[174:177], v[198:201], v[104:107]
	v_mfma_f32_16x16x32_bf16 v[100:103], v[166:169], v[206:209], v[100:103]
	v_mfma_f32_16x16x32_bf16 v[96:99], v[174:177], v[206:209], v[96:99]
	s_setprio 0
	s_barrier
	v_readfirstlane_b32 s36, v148
	v_lshl_add_u64 v[226:227], v[130:131], 0, s[26:27]
	s_mov_b32 m0, s36
	v_readfirstlane_b32 s36, v147
	ds_read_b128 v[210:213], v158
	ds_read_b128 v[214:217], v158 offset:1024
	ds_read_b128 v[218:221], v158 offset:2048
	ds_read_b128 v[222:225], v158 offset:3072
	global_load_lds_dwordx4 v[226:227], off
	v_lshl_add_u64 v[226:227], v[130:131], 0, s[28:29]
	s_mov_b32 m0, s36
	s_add_i32 s68, s68, 2
	global_load_lds_dwordx4 v[226:227], off
	v_readfirstlane_b32 s36, v134
	v_lshl_add_u64 v[226:227], v[132:133], 0, s[30:31]
	s_mov_b32 m0, s36
	v_readfirstlane_b32 s36, v146
	global_load_lds_dwordx4 v[226:227], off
	v_lshl_add_u64 v[226:227], v[132:133], 0, s[34:35]
	s_mov_b32 m0, s36
	s_nop 0
	global_load_lds_dwordx4 v[226:227], off
	s_waitcnt vmcnt(12)
	s_barrier
	s_waitcnt lgkmcnt(0)
	s_setprio 1
	s_waitcnt lgkmcnt(0)
	v_mfma_f32_16x16x32_bf16 v[92:95], v[210:213], v[178:181], v[92:95]
	v_mfma_f32_16x16x32_bf16 v[88:91], v[218:221], v[178:181], v[88:91]
	v_mfma_f32_16x16x32_bf16 v[84:87], v[210:213], v[186:189], v[84:87]
	v_mfma_f32_16x16x32_bf16 v[80:83], v[218:221], v[186:189], v[80:83]
	v_mfma_f32_16x16x32_bf16 v[76:79], v[210:213], v[194:197], v[76:79]
	v_mfma_f32_16x16x32_bf16 v[72:75], v[218:221], v[194:197], v[72:75]
	v_mfma_f32_16x16x32_bf16 v[68:71], v[210:213], v[202:205], v[68:71]
	v_mfma_f32_16x16x32_bf16 v[64:67], v[218:221], v[202:205], v[64:67]
	v_mfma_f32_16x16x32_bf16 v[92:95], v[214:217], v[182:185], v[92:95]
	v_mfma_f32_16x16x32_bf16 v[88:91], v[222:225], v[182:185], v[88:91]
	v_mfma_f32_16x16x32_bf16 v[84:87], v[214:217], v[190:193], v[84:87]
	v_mfma_f32_16x16x32_bf16 v[80:83], v[222:225], v[190:193], v[80:83]
	v_mfma_f32_16x16x32_bf16 v[76:79], v[214:217], v[198:201], v[76:79]
	v_mfma_f32_16x16x32_bf16 v[72:75], v[222:225], v[198:201], v[72:75]
	v_mfma_f32_16x16x32_bf16 v[68:71], v[214:217], v[206:209], v[68:71]
	v_mfma_f32_16x16x32_bf16 v[64:67], v[222:225], v[206:209], v[64:67]
	s_setprio 0
	s_barrier
	ds_read_b128 v[178:181], v152 offset:16384
	ds_read_b128 v[182:185], v152 offset:17408
	ds_read_b128 v[186:189], v151 offset:16384
	ds_read_b128 v[190:193], v151 offset:17408
	ds_read_b128 v[194:197], v150 offset:16384
	ds_read_b128 v[198:201], v150 offset:17408
	ds_read_b128 v[202:205], v149 offset:16384
	ds_read_b128 v[206:209], v149 offset:17408
	v_readfirstlane_b32 s36, v145
	v_lshl_add_u64 v[226:227], v[130:131], 0, s[38:39]
	s_mov_b32 m0, s36
	v_readfirstlane_b32 s36, v144
	global_load_lds_dwordx4 v[226:227], off
	v_lshl_add_u64 v[226:227], v[130:131], 0, s[44:45]
	s_mov_b32 m0, s36
	s_nop 0
	global_load_lds_dwordx4 v[226:227], off
	s_barrier
	s_waitcnt lgkmcnt(0)
	s_setprio 1
	s_waitcnt lgkmcnt(0)
	v_mfma_f32_16x16x32_bf16 v[60:63], v[162:165], v[178:181], v[60:63]
	v_mfma_f32_16x16x32_bf16 v[56:59], v[170:173], v[178:181], v[56:59]
	v_mfma_f32_16x16x32_bf16 v[52:55], v[162:165], v[186:189], v[52:55]
	v_mfma_f32_16x16x32_bf16 v[48:51], v[170:173], v[186:189], v[48:51]
	v_mfma_f32_16x16x32_bf16 v[44:47], v[162:165], v[194:197], v[44:47]
	v_mfma_f32_16x16x32_bf16 v[40:43], v[170:173], v[194:197], v[40:43]
	v_mfma_f32_16x16x32_bf16 v[36:39], v[162:165], v[202:205], v[36:39]
	v_mfma_f32_16x16x32_bf16 v[32:35], v[170:173], v[202:205], v[32:35]
	v_mfma_f32_16x16x32_bf16 v[60:63], v[166:169], v[182:185], v[60:63]
	v_mfma_f32_16x16x32_bf16 v[56:59], v[174:177], v[182:185], v[56:59]
	v_mfma_f32_16x16x32_bf16 v[52:55], v[166:169], v[190:193], v[52:55]
	v_mfma_f32_16x16x32_bf16 v[48:51], v[174:177], v[190:193], v[48:51]
	v_mfma_f32_16x16x32_bf16 v[44:47], v[166:169], v[198:201], v[44:47]
	v_mfma_f32_16x16x32_bf16 v[40:43], v[174:177], v[198:201], v[40:43]
	v_mfma_f32_16x16x32_bf16 v[36:39], v[166:169], v[206:209], v[36:39]
	v_mfma_f32_16x16x32_bf16 v[32:35], v[174:177], v[206:209], v[32:35]
	s_setprio 0
	s_barrier
	v_readfirstlane_b32 s36, v143
	v_lshl_add_u64 v[164:165], v[132:133], 0, s[46:47]
	s_mov_b32 m0, s36
	v_readfirstlane_b32 s36, v142
	global_load_lds_dwordx4 v[164:165], off
	v_lshl_add_u64 v[164:165], v[132:133], 0, s[50:51]
	s_mov_b32 m0, s36
	s_nop 0
	global_load_lds_dwordx4 v[164:165], off
	s_waitcnt vmcnt(12)
	s_barrier
	s_setprio 1
	v_mfma_f32_16x16x32_bf16 v[28:31], v[210:213], v[178:181], v[28:31]
	v_mfma_f32_16x16x32_bf16 v[24:27], v[218:221], v[178:181], v[24:27]
	v_mfma_f32_16x16x32_bf16 v[20:23], v[210:213], v[186:189], v[20:23]
	v_mfma_f32_16x16x32_bf16 v[16:19], v[218:221], v[186:189], v[16:19]
	v_mfma_f32_16x16x32_bf16 v[12:15], v[210:213], v[194:197], v[12:15]
	v_mfma_f32_16x16x32_bf16 v[8:11], v[218:221], v[194:197], v[8:11]
	v_mfma_f32_16x16x32_bf16 v[4:7], v[210:213], v[202:205], v[4:7]
	v_mfma_f32_16x16x32_bf16 v[0:3], v[218:221], v[202:205], v[0:3]
	v_mfma_f32_16x16x32_bf16 v[28:31], v[214:217], v[182:185], v[28:31]
	v_mfma_f32_16x16x32_bf16 v[24:27], v[222:225], v[182:185], v[24:27]
	v_mfma_f32_16x16x32_bf16 v[20:23], v[214:217], v[190:193], v[20:23]
	v_mfma_f32_16x16x32_bf16 v[16:19], v[222:225], v[190:193], v[16:19]
	v_mfma_f32_16x16x32_bf16 v[12:15], v[214:217], v[198:201], v[12:15]
	v_mfma_f32_16x16x32_bf16 v[8:11], v[222:225], v[198:201], v[8:11]
	v_mfma_f32_16x16x32_bf16 v[4:7], v[214:217], v[206:209], v[4:7]
	v_mfma_f32_16x16x32_bf16 v[0:3], v[222:225], v[206:209], v[0:3]
	s_setprio 0
	s_barrier
	ds_read_b128 v[162:165], v154
	ds_read_b128 v[166:169], v154 offset:1024
	ds_read_b128 v[170:173], v154 offset:2048
	ds_read_b128 v[174:177], v154 offset:3072
	ds_read_b128 v[178:181], v152 offset:32768
	ds_read_b128 v[182:185], v152 offset:33792
	ds_read_b128 v[186:189], v151 offset:32768
	ds_read_b128 v[190:193], v151 offset:33792
	ds_read_b128 v[194:197], v150 offset:32768
	ds_read_b128 v[198:201], v150 offset:33792
	ds_read_b128 v[202:205], v149 offset:32768
	ds_read_b128 v[206:209], v149 offset:33792
	s_waitcnt lgkmcnt(8)
	s_waitcnt vmcnt(10)
	s_barrier
	s_waitcnt lgkmcnt(0)
	s_setprio 1
	s_waitcnt lgkmcnt(0)
	v_mfma_f32_16x16x32_bf16 v[124:127], v[162:165], v[178:181], v[124:127]
	v_mfma_f32_16x16x32_bf16 v[120:123], v[170:173], v[178:181], v[120:123]
	v_mfma_f32_16x16x32_bf16 v[116:119], v[162:165], v[186:189], v[116:119]
	v_mfma_f32_16x16x32_bf16 v[112:115], v[170:173], v[186:189], v[112:115]
	v_mfma_f32_16x16x32_bf16 v[108:111], v[162:165], v[194:197], v[108:111]
	v_mfma_f32_16x16x32_bf16 v[104:107], v[170:173], v[194:197], v[104:107]
	v_mfma_f32_16x16x32_bf16 v[100:103], v[162:165], v[202:205], v[100:103]
	v_mfma_f32_16x16x32_bf16 v[96:99], v[170:173], v[202:205], v[96:99]
	v_mfma_f32_16x16x32_bf16 v[124:127], v[166:169], v[182:185], v[124:127]
	v_mfma_f32_16x16x32_bf16 v[120:123], v[174:177], v[182:185], v[120:123]
	v_mfma_f32_16x16x32_bf16 v[116:119], v[166:169], v[190:193], v[116:119]
	v_mfma_f32_16x16x32_bf16 v[112:115], v[174:177], v[190:193], v[112:115]
	v_mfma_f32_16x16x32_bf16 v[108:111], v[166:169], v[198:201], v[108:111]
	v_mfma_f32_16x16x32_bf16 v[104:107], v[174:177], v[198:201], v[104:107]
	v_mfma_f32_16x16x32_bf16 v[100:103], v[166:169], v[206:209], v[100:103]
	v_mfma_f32_16x16x32_bf16 v[96:99], v[174:177], v[206:209], v[96:99]
	s_setprio 0
	s_barrier
	v_readfirstlane_b32 s36, v141
	v_lshl_add_u64 v[226:227], v[130:131], 0, s[56:57]
	s_mov_b32 m0, s36
	v_readfirstlane_b32 s36, v140
	ds_read_b128 v[210:213], v153
	ds_read_b128 v[214:217], v153 offset:1024
	ds_read_b128 v[218:221], v153 offset:2048
	ds_read_b128 v[222:225], v153 offset:3072
	global_load_lds_dwordx4 v[226:227], off
	v_lshl_add_u64 v[226:227], v[130:131], 0, s[58:59]
	s_mov_b32 m0, s36
	s_nop 0
	global_load_lds_dwordx4 v[226:227], off
	v_readfirstlane_b32 s36, v139
	v_lshl_add_u64 v[226:227], v[132:133], 0, s[60:61]
	s_mov_b32 m0, s36
	v_readfirstlane_b32 s36, v138
	global_load_lds_dwordx4 v[226:227], off
	s_mov_b32 m0, s36
	s_nop 0
	global_load_lds_dwordx4 v[132:133], off
	s_waitcnt vmcnt(12)
	s_barrier
	s_waitcnt lgkmcnt(0)
	s_setprio 1
	s_waitcnt lgkmcnt(0)
	v_mfma_f32_16x16x32_bf16 v[92:95], v[210:213], v[178:181], v[92:95]
	v_mfma_f32_16x16x32_bf16 v[88:91], v[218:221], v[178:181], v[88:91]
	v_mfma_f32_16x16x32_bf16 v[84:87], v[210:213], v[186:189], v[84:87]
	v_mfma_f32_16x16x32_bf16 v[80:83], v[218:221], v[186:189], v[80:83]
	v_mfma_f32_16x16x32_bf16 v[76:79], v[210:213], v[194:197], v[76:79]
	v_mfma_f32_16x16x32_bf16 v[72:75], v[218:221], v[194:197], v[72:75]
	v_mfma_f32_16x16x32_bf16 v[68:71], v[210:213], v[202:205], v[68:71]
	v_mfma_f32_16x16x32_bf16 v[64:67], v[218:221], v[202:205], v[64:67]
	v_mfma_f32_16x16x32_bf16 v[92:95], v[214:217], v[182:185], v[92:95]
	v_mfma_f32_16x16x32_bf16 v[88:91], v[222:225], v[182:185], v[88:91]
	v_mfma_f32_16x16x32_bf16 v[84:87], v[214:217], v[190:193], v[84:87]
	v_mfma_f32_16x16x32_bf16 v[80:83], v[222:225], v[190:193], v[80:83]
	v_mfma_f32_16x16x32_bf16 v[76:79], v[214:217], v[198:201], v[76:79]
	v_mfma_f32_16x16x32_bf16 v[72:75], v[222:225], v[198:201], v[72:75]
	v_mfma_f32_16x16x32_bf16 v[68:71], v[214:217], v[206:209], v[68:71]
	v_mfma_f32_16x16x32_bf16 v[64:67], v[222:225], v[206:209], v[64:67]
	s_setprio 0
	s_barrier
	ds_read_b128 v[178:181], v152 offset:49152
	ds_read_b128 v[182:185], v152 offset:50176
	ds_read_b128 v[186:189], v151 offset:49152
	ds_read_b128 v[190:193], v151 offset:50176
	ds_read_b128 v[194:197], v150 offset:49152
	ds_read_b128 v[198:201], v150 offset:50176
	ds_read_b128 v[202:205], v149 offset:49152
	ds_read_b128 v[206:209], v149 offset:50176
	v_readfirstlane_b32 s36, v137
	v_lshl_add_u64 v[226:227], v[130:131], 0, s[60:61]
	s_mov_b32 m0, s36
	v_readfirstlane_b32 s36, v136
	global_load_lds_dwordx4 v[226:227], off
	s_mov_b32 m0, s36
	s_nop 0
	global_load_lds_dwordx4 v[130:131], off
	s_barrier
	s_waitcnt lgkmcnt(0)
	s_setprio 1
	s_waitcnt lgkmcnt(0)
	v_mfma_f32_16x16x32_bf16 v[60:63], v[162:165], v[178:181], v[60:63]
	v_mfma_f32_16x16x32_bf16 v[56:59], v[170:173], v[178:181], v[56:59]
	v_mfma_f32_16x16x32_bf16 v[52:55], v[162:165], v[186:189], v[52:55]
	v_mfma_f32_16x16x32_bf16 v[48:51], v[170:173], v[186:189], v[48:51]
	v_mfma_f32_16x16x32_bf16 v[44:47], v[162:165], v[194:197], v[44:47]
	v_mfma_f32_16x16x32_bf16 v[40:43], v[170:173], v[194:197], v[40:43]
	v_mfma_f32_16x16x32_bf16 v[36:39], v[162:165], v[202:205], v[36:39]
	v_mfma_f32_16x16x32_bf16 v[32:35], v[170:173], v[202:205], v[32:35]
	v_mfma_f32_16x16x32_bf16 v[60:63], v[166:169], v[182:185], v[60:63]
	v_mfma_f32_16x16x32_bf16 v[56:59], v[174:177], v[182:185], v[56:59]
	v_mfma_f32_16x16x32_bf16 v[52:55], v[166:169], v[190:193], v[52:55]
	v_mfma_f32_16x16x32_bf16 v[48:51], v[174:177], v[190:193], v[48:51]
	v_mfma_f32_16x16x32_bf16 v[44:47], v[166:169], v[198:201], v[44:47]
	v_mfma_f32_16x16x32_bf16 v[40:43], v[174:177], v[198:201], v[40:43]
	v_mfma_f32_16x16x32_bf16 v[36:39], v[166:169], v[206:209], v[36:39]
	v_mfma_f32_16x16x32_bf16 v[32:35], v[174:177], v[206:209], v[32:35]
	s_setprio 0
	s_barrier
	v_lshl_add_u64 v[132:133], v[132:133], 0, s[64:65]
	v_readfirstlane_b32 s36, v160
	v_lshl_add_u64 v[164:165], v[132:133], 0, s[22:23]
	s_mov_b32 m0, s36
	v_readfirstlane_b32 s36, v159
	global_load_lds_dwordx4 v[164:165], off
	v_lshl_add_u64 v[164:165], v[132:133], 0, s[24:25]
	s_mov_b32 m0, s36
	s_nop 0
	global_load_lds_dwordx4 v[164:165], off
	s_waitcnt vmcnt(12)
	s_barrier
	s_setprio 1
	v_mfma_f32_16x16x32_bf16 v[28:31], v[210:213], v[178:181], v[28:31]
	v_mfma_f32_16x16x32_bf16 v[24:27], v[218:221], v[178:181], v[24:27]
	v_mfma_f32_16x16x32_bf16 v[20:23], v[210:213], v[186:189], v[20:23]
	v_mfma_f32_16x16x32_bf16 v[16:19], v[218:221], v[186:189], v[16:19]
	v_mfma_f32_16x16x32_bf16 v[12:15], v[210:213], v[194:197], v[12:15]
	v_mfma_f32_16x16x32_bf16 v[8:11], v[218:221], v[194:197], v[8:11]
	v_mfma_f32_16x16x32_bf16 v[4:7], v[210:213], v[202:205], v[4:7]
	v_mfma_f32_16x16x32_bf16 v[0:3], v[218:221], v[202:205], v[0:3]
	v_mfma_f32_16x16x32_bf16 v[28:31], v[214:217], v[182:185], v[28:31]
	v_mfma_f32_16x16x32_bf16 v[24:27], v[222:225], v[182:185], v[24:27]
	v_mfma_f32_16x16x32_bf16 v[20:23], v[214:217], v[190:193], v[20:23]
	v_mfma_f32_16x16x32_bf16 v[16:19], v[222:225], v[190:193], v[16:19]
	v_mfma_f32_16x16x32_bf16 v[12:15], v[214:217], v[198:201], v[12:15]
	v_mfma_f32_16x16x32_bf16 v[8:11], v[222:225], v[198:201], v[8:11]
	v_mfma_f32_16x16x32_bf16 v[4:7], v[214:217], v[206:209], v[4:7]
	v_mfma_f32_16x16x32_bf16 v[0:3], v[222:225], v[206:209], v[0:3]
	s_setprio 0
	v_lshl_add_u64 v[130:131], v[130:131], 0, s[62:63]
	s_cmp_lt_u32 s68, s67
	s_barrier
	s_cbranch_scc1 .LBB0_561
	s_lshl_b32 s36, s86, 5
	s_lshl_b32 s37, s86, 8
	s_and_b32 s36, s36, 0x1800
	s_and_b32 s37, s37, 0x700
	s_or_b32 s96, s37, s36
	s_lshl_b32 s36, s96, 6
	s_add_u32 s36, s70, s36
	s_addc_u32 s37, s71, 0
	s_add_i32 s20, s20, -1
	s_lshl_b64 s[68:69], s[20:21], 20
	v_add_u32_e32 v128, v156, v157
	s_add_u32 s68, s36, s68
	v_or_b32_e32 v128, v128, v155
	s_addc_u32 s69, s37, s69
	v_lshl_add_u64 v[156:157], s[68:69], 0, v[128:129]
	v_readfirstlane_b32 s20, v160
	v_lshl_add_u64 v[206:207], v[156:157], 0, s[4:5]
	s_mov_b32 m0, s20
	v_readfirstlane_b32 s20, v159
	ds_read_b128 v[130:133], v161
	ds_read_b128 v[162:165], v161 offset:1024
	ds_read_b128 v[166:169], v161 offset:2048
	ds_read_b128 v[170:173], v161 offset:3072
	ds_read_b128 v[174:177], v152
	ds_read_b128 v[178:181], v152 offset:1024
	ds_read_b128 v[182:185], v151
	ds_read_b128 v[186:189], v151 offset:1024
	ds_read_b128 v[190:193], v150
	ds_read_b128 v[194:197], v150 offset:1024
	ds_read_b128 v[198:201], v149
	ds_read_b128 v[202:205], v149 offset:1024
	global_load_lds_dwordx4 v[206:207], off
	v_lshl_add_u64 v[156:157], v[156:157], 0, s[6:7]
	s_mov_b32 m0, s20
	s_nop 0
	global_load_lds_dwordx4 v[156:157], off
	s_waitcnt vmcnt(10)
	s_barrier
	s_waitcnt lgkmcnt(0)
	s_setprio 1
	s_waitcnt lgkmcnt(0)
	v_mfma_f32_16x16x32_bf16 v[124:127], v[130:133], v[174:177], v[124:127]
	v_mfma_f32_16x16x32_bf16 v[120:123], v[166:169], v[174:177], v[120:123]
	v_mfma_f32_16x16x32_bf16 v[116:119], v[130:133], v[182:185], v[116:119]
	v_mfma_f32_16x16x32_bf16 v[112:115], v[166:169], v[182:185], v[112:115]
	v_mfma_f32_16x16x32_bf16 v[108:111], v[130:133], v[190:193], v[108:111]
	v_mfma_f32_16x16x32_bf16 v[104:107], v[166:169], v[190:193], v[104:107]
	v_mfma_f32_16x16x32_bf16 v[100:103], v[130:133], v[198:201], v[100:103]
	v_mfma_f32_16x16x32_bf16 v[96:99], v[166:169], v[198:201], v[96:99]
	v_mfma_f32_16x16x32_bf16 v[124:127], v[162:165], v[178:181], v[124:127]
	v_mfma_f32_16x16x32_bf16 v[120:123], v[170:173], v[178:181], v[120:123]
	v_mfma_f32_16x16x32_bf16 v[116:119], v[162:165], v[186:189], v[116:119]
	v_mfma_f32_16x16x32_bf16 v[112:115], v[170:173], v[186:189], v[112:115]
	v_mfma_f32_16x16x32_bf16 v[108:111], v[162:165], v[194:197], v[108:111]
	v_mfma_f32_16x16x32_bf16 v[104:107], v[170:173], v[194:197], v[104:107]
	v_mfma_f32_16x16x32_bf16 v[100:103], v[162:165], v[202:205], v[100:103]
	v_mfma_f32_16x16x32_bf16 v[96:99], v[170:173], v[202:205], v[96:99]
	s_setprio 0
	s_barrier
	ds_read_b128 v[206:209], v158
	ds_read_b128 v[210:213], v158 offset:1024
	ds_read_b128 v[214:217], v158 offset:2048
	ds_read_b128 v[156:159], v158 offset:3072
	s_barrier
	s_waitcnt lgkmcnt(0)
	s_setprio 1
	s_waitcnt lgkmcnt(0)
	v_mfma_f32_16x16x32_bf16 v[92:95], v[206:209], v[174:177], v[92:95]
	v_mfma_f32_16x16x32_bf16 v[88:91], v[214:217], v[174:177], v[88:91]
	v_mfma_f32_16x16x32_bf16 v[84:87], v[206:209], v[182:185], v[84:87]
	v_mfma_f32_16x16x32_bf16 v[80:83], v[214:217], v[182:185], v[80:83]
	v_mfma_f32_16x16x32_bf16 v[76:79], v[206:209], v[190:193], v[76:79]
	v_mfma_f32_16x16x32_bf16 v[72:75], v[214:217], v[190:193], v[72:75]
	v_mfma_f32_16x16x32_bf16 v[68:71], v[206:209], v[198:201], v[68:71]
	v_mfma_f32_16x16x32_bf16 v[64:67], v[214:217], v[198:201], v[64:67]
	v_mfma_f32_16x16x32_bf16 v[174:177], v[210:213], v[178:181], v[92:95]
	v_mfma_f32_16x16x32_bf16 v[178:181], v[156:159], v[178:181], v[88:91]
	v_mfma_f32_16x16x32_bf16 v[182:185], v[210:213], v[186:189], v[84:87]
	v_mfma_f32_16x16x32_bf16 v[186:189], v[156:159], v[186:189], v[80:83]
	v_mfma_f32_16x16x32_bf16 v[190:193], v[210:213], v[194:197], v[76:79]
	v_mfma_f32_16x16x32_bf16 v[194:197], v[156:159], v[194:197], v[72:75]
	v_mfma_f32_16x16x32_bf16 v[198:201], v[210:213], v[202:205], v[68:71]
	v_mfma_f32_16x16x32_bf16 v[202:205], v[156:159], v[202:205], v[64:67]
	s_setprio 0
	s_barrier
	s_nop 0
	ds_read_b128 v[64:67], v152 offset:16384
	ds_read_b128 v[68:71], v152 offset:17408
	ds_read_b128 v[72:75], v151 offset:16384
	ds_read_b128 v[76:79], v151 offset:17408
	ds_read_b128 v[80:83], v150 offset:16384
	ds_read_b128 v[84:87], v150 offset:17408
	ds_read_b128 v[88:91], v149 offset:16384
	ds_read_b128 v[92:95], v149 offset:17408
	s_waitcnt vmcnt(4)
	s_barrier
	s_waitcnt lgkmcnt(0)
	s_setprio 1
	s_waitcnt lgkmcnt(0)
	v_mfma_f32_16x16x32_bf16 v[60:63], v[130:133], v[64:67], v[60:63]
	v_mfma_f32_16x16x32_bf16 v[56:59], v[166:169], v[64:67], v[56:59]
	v_mfma_f32_16x16x32_bf16 v[52:55], v[130:133], v[72:75], v[52:55]
	v_mfma_f32_16x16x32_bf16 v[48:51], v[166:169], v[72:75], v[48:51]
	v_mfma_f32_16x16x32_bf16 v[218:221], v[130:133], v[80:83], v[44:47]
	v_mfma_f32_16x16x32_bf16 v[222:225], v[166:169], v[80:83], v[40:43]
	v_mfma_f32_16x16x32_bf16 v[130:133], v[130:133], v[88:91], v[36:39]
	v_mfma_f32_16x16x32_bf16 v[166:169], v[166:169], v[88:91], v[32:35]
	v_mfma_f32_16x16x32_bf16 v[32:35], v[162:165], v[68:71], v[60:63]
	v_mfma_f32_16x16x32_bf16 v[36:39], v[170:173], v[68:71], v[56:59]
	v_mfma_f32_16x16x32_bf16 v[40:43], v[162:165], v[76:79], v[52:55]
	v_mfma_f32_16x16x32_bf16 v[44:47], v[170:173], v[76:79], v[48:51]
	v_mfma_f32_16x16x32_bf16 v[48:51], v[162:165], v[84:87], v[218:221]
	v_mfma_f32_16x16x32_bf16 v[52:55], v[170:173], v[84:87], v[222:225]
	v_mfma_f32_16x16x32_bf16 v[56:59], v[162:165], v[92:95], v[130:133]
	v_mfma_f32_16x16x32_bf16 v[60:63], v[170:173], v[92:95], v[166:169]
	s_setprio 0
	s_setprio 1
	v_mfma_f32_16x16x32_bf16 v[28:31], v[206:209], v[64:67], v[28:31]
	v_mfma_f32_16x16x32_bf16 v[24:27], v[214:217], v[64:67], v[24:27]
	v_mfma_f32_16x16x32_bf16 v[20:23], v[206:209], v[72:75], v[20:23]
	v_mfma_f32_16x16x32_bf16 v[64:67], v[214:217], v[72:75], v[16:19]
	v_mfma_f32_16x16x32_bf16 v[72:75], v[206:209], v[80:83], v[12:15]
	v_mfma_f32_16x16x32_bf16 v[8:11], v[214:217], v[80:83], v[8:11]
	v_mfma_f32_16x16x32_bf16 v[80:83], v[206:209], v[88:91], v[4:7]
	v_mfma_f32_16x16x32_bf16 v[0:3], v[214:217], v[88:91], v[0:3]
	v_mfma_f32_16x16x32_bf16 v[4:7], v[210:213], v[68:71], v[28:31]
	v_mfma_f32_16x16x32_bf16 v[12:15], v[156:159], v[68:71], v[24:27]
	v_mfma_f32_16x16x32_bf16 v[16:19], v[210:213], v[76:79], v[20:23]
	v_mfma_f32_16x16x32_bf16 v[20:23], v[156:159], v[76:79], v[64:67]
	v_mfma_f32_16x16x32_bf16 v[24:27], v[210:213], v[84:87], v[72:75]
	v_mfma_f32_16x16x32_bf16 v[28:31], v[156:159], v[84:87], v[8:11]
	v_mfma_f32_16x16x32_bf16 v[64:67], v[210:213], v[92:95], v[80:83]
	v_mfma_f32_16x16x32_bf16 v[68:71], v[156:159], v[92:95], v[0:3]
	s_setprio 0
	s_barrier
	ds_read_b128 v[8:11], v154
	ds_read_b128 v[0:3], v154 offset:1024
	ds_read_b128 v[76:79], v154 offset:2048
	ds_read_b128 v[72:75], v154 offset:3072
	ds_read_b128 v[130:133], v152 offset:32768
	ds_read_b128 v[154:157], v152 offset:33792
	ds_read_b128 v[158:161], v151 offset:32768
	ds_read_b128 v[162:165], v151 offset:33792
	ds_read_b128 v[166:169], v150 offset:32768
	ds_read_b128 v[170:173], v150 offset:33792
	ds_read_b128 v[206:209], v149 offset:32768
	ds_read_b128 v[210:213], v149 offset:33792
	s_waitcnt vmcnt(2)
	s_barrier
	s_waitcnt lgkmcnt(0)
	s_setprio 1
	s_waitcnt lgkmcnt(0)
	v_mfma_f32_16x16x32_bf16 v[80:83], v[8:11], v[130:133], v[124:127]
	v_mfma_f32_16x16x32_bf16 v[84:87], v[76:79], v[130:133], v[120:123]
	v_mfma_f32_16x16x32_bf16 v[88:91], v[8:11], v[158:161], v[116:119]
	v_mfma_f32_16x16x32_bf16 v[92:95], v[76:79], v[158:161], v[112:115]
	v_mfma_f32_16x16x32_bf16 v[108:111], v[8:11], v[166:169], v[108:111]
	v_mfma_f32_16x16x32_bf16 v[104:107], v[76:79], v[166:169], v[104:107]
	v_mfma_f32_16x16x32_bf16 v[100:103], v[8:11], v[206:209], v[100:103]
	v_mfma_f32_16x16x32_bf16 v[96:99], v[76:79], v[206:209], v[96:99]
	v_mfma_f32_16x16x32_bf16 v[112:115], v[0:3], v[154:157], v[80:83]
	v_mfma_f32_16x16x32_bf16 v[116:119], v[72:75], v[154:157], v[84:87]
	v_mfma_f32_16x16x32_bf16 v[120:123], v[0:3], v[162:165], v[88:91]
	v_mfma_f32_16x16x32_bf16 v[124:127], v[72:75], v[162:165], v[92:95]
	v_mfma_f32_16x16x32_bf16 v[108:111], v[0:3], v[170:173], v[108:111]
	v_mfma_f32_16x16x32_bf16 v[104:107], v[72:75], v[170:173], v[104:107]
	v_mfma_f32_16x16x32_bf16 v[100:103], v[0:3], v[210:213], v[100:103]
	v_mfma_f32_16x16x32_bf16 v[96:99], v[72:75], v[210:213], v[96:99]
	s_setprio 0
	s_barrier
	ds_read_b128 v[88:91], v153
	ds_read_b128 v[80:83], v153 offset:1024
	ds_read_b128 v[92:95], v153 offset:2048
	ds_read_b128 v[84:87], v153 offset:3072
	s_waitcnt vmcnt(0)
	s_barrier
	s_waitcnt lgkmcnt(0)
	s_setprio 1
	s_waitcnt lgkmcnt(0)
	v_mfma_f32_16x16x32_bf16 v[174:177], v[88:91], v[130:133], v[174:177]
	v_mfma_f32_16x16x32_bf16 v[130:133], v[92:95], v[130:133], v[178:181]
	v_mfma_f32_16x16x32_bf16 v[178:181], v[88:91], v[158:161], v[182:185]
	v_mfma_f32_16x16x32_bf16 v[158:161], v[92:95], v[158:161], v[186:189]
	v_mfma_f32_16x16x32_bf16 v[182:185], v[88:91], v[166:169], v[190:193]
	v_mfma_f32_16x16x32_bf16 v[166:169], v[92:95], v[166:169], v[194:197]
	v_mfma_f32_16x16x32_bf16 v[186:189], v[88:91], v[206:209], v[198:201]
	v_mfma_f32_16x16x32_bf16 v[190:193], v[92:95], v[206:209], v[202:205]
	v_mfma_f32_16x16x32_bf16 v[174:177], v[80:83], v[154:157], v[174:177]
	v_mfma_f32_16x16x32_bf16 v[130:133], v[84:87], v[154:157], v[130:133]
	v_mfma_f32_16x16x32_bf16 v[154:157], v[80:83], v[162:165], v[178:181]
	v_mfma_f32_16x16x32_bf16 v[158:161], v[84:87], v[162:165], v[158:161]
	v_mfma_f32_16x16x32_bf16 v[162:165], v[80:83], v[170:173], v[182:185]
	v_mfma_f32_16x16x32_bf16 v[166:169], v[84:87], v[170:173], v[166:169]
	v_mfma_f32_16x16x32_bf16 v[170:173], v[80:83], v[210:213], v[186:189]
	v_mfma_f32_16x16x32_bf16 v[178:181], v[84:87], v[210:213], v[190:193]
	s_setprio 0
	s_barrier
	v_mbcnt_lo_u32_b32 v128, -1, 0
	v_mbcnt_hi_u32_b32 v128, -1, v128
	v_cvt_pk_bf16_f32 v112, v112, v113
	v_cvt_pk_bf16_f32 v113, v114, v115
	v_cvt_pk_bf16_f32 v114, v116, v117
	v_cvt_pk_bf16_f32 v115, v118, v119
	s_lshl_b32 s89, s66, 9
	v_add_u32_e32 v153, s74, v128
	v_ashrrev_i32_e32 v182, 6, v153
	v_and_b32_e32 v183, 15, v128
	v_and_b32_e32 v184, 48, v128
	v_mul_lo_u32 v185, v182, s79
	v_bfe_u32 v186, v128, 3, 3
	v_lshlrev_b32_e32 v128, 4, v128
	v_add_u32_e32 v185, 0x20000, v185
	v_lshrrev_b32_e32 v153, 2, v153
	v_and_b32_e32 v128, 0x70, v128
	v_mul_u32_u24_e32 v183, 0x90, v183
	v_and_b32_e32 v153, 64, v153
	v_add3_u32 v183, v185, v183, v184
	v_or_b32_e32 v184, v185, v128
	v_or3_b32 v153, s96, v153, v186
	v_mad_u32_u24 v184, v186, s81, v184
	ds_write_b128 v183, v[112:115]
	v_cvt_pk_bf16_f32 v112, v174, v175
	v_cvt_pk_bf16_f32 v113, v176, v177
	v_cvt_pk_bf16_f32 v114, v130, v131
	v_cvt_pk_bf16_f32 v115, v132, v133
	ds_write_b128 v183, v[112:115] offset:64
	v_lshlrev_b32_e32 v182, 7, v182
	ds_read_b128 v[112:115], v184
	v_lshlrev_b32_e32 v116, 12, v153
	v_and_or_b32 v116, v182, s82, v116
	v_or3_b32 v128, v116, s89, v128
	ds_read_b128 v[116:119], v184 offset:1152
	v_lshl_add_u64 v[130:131], s[0:1], 0, v[128:129]
	s_mov_b32 s20, 0x8000
	s_waitcnt lgkmcnt(0)
	global_store_dwordx4 v128, v[112:115], s[0:1]
	v_cvt_pk_bf16_f32 v108, v108, v109
	v_cvt_pk_bf16_f32 v109, v110, v111
	v_cvt_pk_bf16_f32 v110, v104, v105
	v_cvt_pk_bf16_f32 v111, v106, v107
	v_cvt_pk_bf16_f32 v104, v162, v163
	s_nop 1
	v_add_co_u32_e32 v112, vcc, s20, v130
	v_cvt_pk_bf16_f32 v114, v124, v125
	v_cvt_pk_bf16_f32 v115, v126, v127
	v_cvt_pk_bf16_f32 v105, v164, v165
	v_cvt_pk_bf16_f32 v106, v166, v167
	s_nop 1
	v_addc_co_u32_e32 v113, vcc, 0, v131, vcc
	global_store_dwordx4 v[112:113], v[116:119], off
	v_cvt_pk_bf16_f32 v112, v120, v121
	v_cvt_pk_bf16_f32 v113, v122, v123
	ds_write_b128 v183, v[112:115]
	v_cvt_pk_bf16_f32 v112, v154, v155
	v_cvt_pk_bf16_f32 v113, v156, v157
	v_cvt_pk_bf16_f32 v114, v158, v159
	v_cvt_pk_bf16_f32 v115, v160, v161
	ds_write_b128 v183, v[112:115] offset:64
	ds_read_b128 v[112:115], v184
	ds_read_b128 v[116:119], v184 offset:1152
	v_add_co_u32_e32 v120, vcc, s76, v130
	ds_write_b128 v183, v[108:111]
	v_cvt_pk_bf16_f32 v107, v168, v169
	ds_write_b128 v183, v[104:107] offset:64
	v_addc_co_u32_e32 v121, vcc, 0, v131, vcc
	ds_read_b128 v[104:107], v184
	ds_read_b128 v[108:111], v184 offset:1152
	s_waitcnt lgkmcnt(0)
	global_store_dwordx4 v[120:121], v[112:115], off
	v_cvt_pk_bf16_f32 v100, v100, v101
	v_cvt_pk_bf16_f32 v101, v102, v103
	v_cvt_pk_bf16_f32 v102, v96, v97
	v_cvt_pk_bf16_f32 v103, v98, v99
	ds_write_b128 v183, v[100:103]
	s_nop 0
	v_add_co_u32_e32 v112, vcc, s77, v130
	v_cvt_pk_bf16_f32 v96, v170, v171
	v_cvt_pk_bf16_f32 v97, v172, v173
	v_cvt_pk_bf16_f32 v98, v178, v179
	v_cvt_pk_bf16_f32 v99, v180, v181
	s_nop 1
	v_addc_co_u32_e32 v113, vcc, 0, v131, vcc
	global_store_dwordx4 v[112:113], v[116:119], off
	v_add_co_u32_e32 v112, vcc, s80, v130
	ds_write_b128 v183, v[96:99] offset:64
	s_nop 0
	v_addc_co_u32_e32 v113, vcc, 0, v131, vcc
	ds_read_b128 v[96:99], v184
	ds_read_b128 v[100:103], v184 offset:1152
	global_store_dwordx4 v[112:113], v[104:107], off
	s_nop 1
	v_add_co_u32_e32 v104, vcc, s83, v130
	s_nop 1
	v_addc_co_u32_e32 v105, vcc, 0, v131, vcc
	global_store_dwordx4 v[104:105], v[108:111], off
	v_add_co_u32_e32 v104, vcc, s85, v130
	s_nop 1
	v_addc_co_u32_e32 v105, vcc, 0, v131, vcc
	s_waitcnt lgkmcnt(0)
	global_store_dwordx4 v[104:105], v[96:99], off
	s_nop 1
	v_add_co_u32_e32 v96, vcc, s87, v130
	s_nop 1
	v_addc_co_u32_e32 v97, vcc, 0, v131, vcc
	global_store_dwordx4 v[96:97], v[100:103], off
	ds_read_b128 v[96:99], v152 offset:49152
	ds_read_b128 v[100:103], v152 offset:50176
	ds_read_b128 v[104:107], v151 offset:49152
	ds_read_b128 v[108:111], v151 offset:50176
	ds_read_b128 v[112:115], v150 offset:49152
	ds_read_b128 v[116:119], v150 offset:50176
	ds_read_b128 v[120:123], v149 offset:49152
	ds_read_b128 v[124:127], v149 offset:50176
	s_barrier
	s_waitcnt lgkmcnt(0)
	s_setprio 1
	s_waitcnt lgkmcnt(0)
	v_mfma_f32_16x16x32_bf16 v[32:35], v[8:11], v[96:99], v[32:35]
	v_mfma_f32_16x16x32_bf16 v[36:39], v[76:79], v[96:99], v[36:39]
	v_mfma_f32_16x16x32_bf16 v[40:43], v[8:11], v[104:107], v[40:43]
	v_mfma_f32_16x16x32_bf16 v[130:133], v[76:79], v[104:107], v[44:47]
	v_mfma_f32_16x16x32_bf16 v[150:153], v[8:11], v[112:115], v[48:51]
	v_mfma_f32_16x16x32_bf16 v[52:55], v[76:79], v[112:115], v[52:55]
	v_mfma_f32_16x16x32_bf16 v[8:11], v[8:11], v[120:123], v[56:59]
	v_mfma_f32_16x16x32_bf16 v[60:63], v[76:79], v[120:123], v[60:63]
	v_mfma_f32_16x16x32_bf16 v[56:59], v[0:3], v[100:103], v[32:35]
	v_mfma_f32_16x16x32_bf16 v[48:51], v[72:75], v[100:103], v[36:39]
	v_mfma_f32_16x16x32_bf16 v[44:47], v[0:3], v[108:111], v[40:43]
	v_mfma_f32_16x16x32_bf16 v[40:43], v[72:75], v[108:111], v[130:133]
	v_mfma_f32_16x16x32_bf16 v[36:39], v[0:3], v[116:119], v[150:153]
	v_mfma_f32_16x16x32_bf16 v[32:35], v[72:75], v[116:119], v[52:55]
	v_mfma_f32_16x16x32_bf16 v[8:11], v[0:3], v[124:127], v[8:11]
	v_mfma_f32_16x16x32_bf16 v[0:3], v[72:75], v[124:127], v[60:63]
	s_setprio 0
	s_setprio 1
	v_mfma_f32_16x16x32_bf16 v[4:7], v[88:91], v[96:99], v[4:7]
	v_mfma_f32_16x16x32_bf16 v[12:15], v[92:95], v[96:99], v[12:15]
	v_mfma_f32_16x16x32_bf16 v[16:19], v[88:91], v[104:107], v[16:19]
	v_mfma_f32_16x16x32_bf16 v[20:23], v[92:95], v[104:107], v[20:23]
	v_mfma_f32_16x16x32_bf16 v[72:75], v[88:91], v[112:115], v[24:27]
	v_mfma_f32_16x16x32_bf16 v[76:79], v[92:95], v[112:115], v[28:31]
	v_mfma_f32_16x16x32_bf16 v[64:67], v[88:91], v[120:123], v[64:67]
	v_mfma_f32_16x16x32_bf16 v[68:71], v[92:95], v[120:123], v[68:71]
	v_mfma_f32_16x16x32_bf16 v[60:63], v[80:83], v[100:103], v[4:7]
	v_mfma_f32_16x16x32_bf16 v[52:55], v[84:87], v[100:103], v[12:15]
	v_mfma_f32_16x16x32_bf16 v[28:31], v[80:83], v[108:111], v[16:19]
	v_mfma_f32_16x16x32_bf16 v[24:27], v[84:87], v[108:111], v[20:23]
	v_mfma_f32_16x16x32_bf16 v[20:23], v[80:83], v[116:119], v[72:75]
	v_mfma_f32_16x16x32_bf16 v[16:19], v[84:87], v[116:119], v[76:79]
	v_mfma_f32_16x16x32_bf16 v[12:15], v[80:83], v[124:127], v[64:67]
	v_mfma_f32_16x16x32_bf16 v[4:7], v[84:87], v[124:127], v[68:71]
	s_setprio 0
	v_cmp_gt_u32_e32 vcc, s88, v135
	s_barrier
	s_and_saveexec_b64 s[66:67], vcc
	s_cbranch_execz .LBB0_564
	s_barrier
